# MFMA issue order inside each 8-MFMA group changed to a snake (every consecutive pair shares one operand register tuple); bit-identical
# baseline (speedup 1.0000x reference)
; #define PG8_STAGE(bufoff, gbase, voff) do { _Pragma("unroll") for (int _i = 0; _i < 2; ++_i) \
;         __builtin_amdgcn_global_load_lds((const unsigned*)((const char*)(gbase) + (voff)[_i]), (LAS unsigned*)(lds + (bufoff) + ldsw + _i * 8192), 16, 0, 0); } while (0)
; #define PG8_LDA(dst, b, h) do { _Pragma("unroll") for (int m = 0; m < 4; ++m) _Pragma("unroll") for (int k = 0; k < 2; ++k) dst[m][k] = *(const LAS bf16x8*)(lds + PG8_SA(b, h) + aoff + m * 2048 + k * 1024); } while (0)
; #define PG8_LDB(dst, b, h) do { _Pragma("unroll") for (int n = 0; n < 2; ++n) _Pragma("unroll") for (int k = 0; k < 2; ++k) dst[n][k] = *(const LAS bf16x8*)(lds + PG8_SB(b, h) + boff + n * 2048 + k * 1024); } while (0)
; #define PG8_WAIT_V(n) asm volatile("s_waitcnt vmcnt(" #n ")" ::: "memory")
; #define PG8_BAR __builtin_amdgcn_s_barrier()
; template <class Epi, class Sched>
; __device__ __forceinline__ void gemm_phase(LAS unsigned char* lds, const Gemm g, const Sched& S, const Epi& E, const int tid) {
;     ...
;         for (int t = 0; t < nt; t += 2) {
;             const bool last = (t == nt - 2);
;             const char* a1 = cA + (size_t)(t + 1) * kstep;
;             const char* a2 = last ? nA : cA + (size_t)(t + 2) * kstep; const char* b2 = last ? nB : cB + (size_t)(t + 2) * kstep;
;             const char* a3 = a2 + kstep; const char* b3 = b2 + kstep;
;             PG8_LDB(B0, 0, 0); PG8_LDB(B1, 0, 1); PG8_SCHED; PG8_LDA(At, 0, 0); PG8_STAGE(PG8_SA(1, 1), a1 + hstep, voffA);
;             PG8_WAIT_V(8); PG8_WAIT_L(0); PG8_BAR; PG8_MMA(0, 0, At, B0); PG8_MMA(0, 1, At, B1); PG8_BAR; PG8_SCHED;
;             PG8_LDA(At, 0, 1); PG8_STAGE(PG8_SB(0, 0), b2, voffB); PG8_STAGE(PG8_SB(0, 1), b2 + hstep, voffB); PG8_STAGE(PG8_SA(0, 0), a2, voffA);
;             PG8_WAIT_V(8); PG8_WAIT_L(0); PG8_BAR; PG8_MMA(1, 0, At, B0); PG8_MMA(1, 1, At, B1); PG8_BAR; PG8_SCHED;
;             PG8_LDB(B0, 1, 0); PG8_LDB(B1, 1, 1); PG8_SCHED; PG8_LDA(At, 1, 0); PG8_STAGE(PG8_SA(0, 1), a2 + hstep, voffA);
;             PG8_WAIT_V(8); PG8_WAIT_L(0); PG8_BAR; PG8_MMA(0, 0, At, B0); PG8_MMA(0, 1, At, B1); PG8_BAR; PG8_SCHED;
;             PG8_LDA(At, 1, 1); PG8_STAGE(PG8_SB(1, 0), b3, voffB); PG8_STAGE(PG8_SB(1, 1), b3 + hstep, voffB); PG8_STAGE(PG8_SA(1, 0), a3, voffA);
;             PG8_WAIT_V(8); PG8_WAIT_L(0); PG8_BAR; PG8_MMA(1, 0, At, B0); PG8_MMA(1, 1, At, B1); PG8_BAR; PG8_SCHED;
;         }
.LBB0_167:
	s_or_b64 exec, exec, s[22:23]
	s_ashr_i32 s55, s54, 31
	s_lshl_b64 s[22:23], s[54:55], 19
	s_add_u32 s22, s46, s22
	s_addc_u32 s23, s47, s23
	s_and_b64 s[38:39], s[6:7], exec
	s_cselect_b32 s55, s23, s65
	s_cselect_b32 s56, s22, s64
	s_ashr_i32 s63, s62, 31
	s_lshl_b64 s[38:39], s[62:63], 19
	s_add_u32 s38, s12, s38
	s_addc_u32 s39, s73, s39
	s_and_b64 s[58:59], s[6:7], exec
	s_cselect_b32 s57, s39, s67
	s_cselect_b32 s58, s38, s66
	s_add_u32 s64, s64, 0x40080
	s_addc_u32 s65, s65, 0
	s_add_u32 s59, s66, 0x100
	s_addc_u32 s60, s67, 0
	s_mov_b32 s61, -2
	s_add_u32 s63, s64, 0xfffc0080
	s_addc_u32 s66, s65, -1
	s_add_i32 s78, 0, 0x10000
	s_cmp_eq_u32 s61, 12
	s_cselect_b32 s71, s55, s66
	s_cselect_b32 s70, s56, s63
	v_add_u32_e32 v145, s78, v166
	s_cselect_b32 s67, s57, s60
	s_cselect_b32 s66, s58, s59
	s_add_i32 s63, 0, 0x14000
	ds_read_b128 v[146:149], v145
	ds_read_b128 v[150:153], v145 offset:1024
	ds_read_b128 v[154:157], v145 offset:2048
	ds_read_b128 v[158:161], v145 offset:3072
	v_add_u32_e32 v145, s63, v166
	ds_read_b128 v[172:175], v145
	ds_read_b128 v[176:179], v145 offset:1024
	ds_read_b128 v[180:183], v145 offset:2048
	ds_read_b128 v[184:187], v145 offset:3072
	v_lshl_add_u64 v[162:163], s[64:65], 0, v[140:141]
	s_add_i32 m0, s75, 0xc000
	ds_read_b128 v[188:191], v171
	ds_read_b128 v[198:201], v171 offset:1024
	ds_read_b128 v[202:205], v171 offset:2048
	ds_read_b128 v[206:209], v171 offset:3072
	ds_read_b128 v[210:213], v171 offset:4096
	ds_read_b128 v[214:217], v171 offset:5120
	ds_read_b128 v[218:221], v171 offset:6144
	ds_read_b128 v[230:233], v171 offset:7168
	global_load_lds_dwordx4 v[162:163], off
	v_lshl_add_u64 v[162:163], s[64:65], 0, v[142:143]
	s_add_i32 m0, s75, 0xe000
	s_nop 0
	global_load_lds_dwordx4 v[162:163], off
	s_waitcnt vmcnt(8)
	s_waitcnt lgkmcnt(0)
	s_barrier
	s_waitcnt lgkmcnt(0)
	v_mfma_f32_16x16x32_bf16 v[128:131], v[146:149], v[188:191], 0
	v_mfma_f32_16x16x32_bf16 v[124:127], v[154:157], v[188:191], 0
	v_mfma_f32_16x16x32_bf16 v[104:107], v[154:157], v[202:205], 0
	v_mfma_f32_16x16x32_bf16 v[108:111], v[146:149], v[202:205], 0
	v_mfma_f32_16x16x32_bf16 v[92:95], v[146:149], v[210:213], 0
	v_mfma_f32_16x16x32_bf16 v[88:91], v[154:157], v[210:213], 0
	v_mfma_f32_16x16x32_bf16 v[72:75], v[154:157], v[218:221], 0
	v_mfma_f32_16x16x32_bf16 v[76:79], v[146:149], v[218:221], 0
	v_mfma_f32_16x16x32_bf16 v[128:131], v[150:153], v[198:201], v[128:131]
	v_mfma_f32_16x16x32_bf16 v[124:127], v[158:161], v[198:201], v[124:127]
	v_mfma_f32_16x16x32_bf16 v[104:107], v[158:161], v[206:209], v[104:107]
	v_mfma_f32_16x16x32_bf16 v[108:111], v[150:153], v[206:209], v[108:111]
	v_mfma_f32_16x16x32_bf16 v[92:95], v[150:153], v[214:217], v[92:95]
	v_mfma_f32_16x16x32_bf16 v[88:91], v[158:161], v[214:217], v[88:91]
	v_mfma_f32_16x16x32_bf16 v[72:75], v[158:161], v[230:233], v[72:75]
	v_mfma_f32_16x16x32_bf16 v[76:79], v[150:153], v[230:233], v[76:79]
	v_mfma_f32_16x16x32_bf16 v[120:123], v[172:175], v[188:191], 0
	v_mfma_f32_16x16x32_bf16 v[116:119], v[180:183], v[188:191], 0
	v_mfma_f32_16x16x32_bf16 v[96:99], v[180:183], v[202:205], 0
	v_mfma_f32_16x16x32_bf16 v[100:103], v[172:175], v[202:205], 0
	v_mfma_f32_16x16x32_bf16 v[84:87], v[172:175], v[210:213], 0
	v_mfma_f32_16x16x32_bf16 v[80:83], v[180:183], v[210:213], 0
	v_mfma_f32_16x16x32_bf16 v[64:67], v[180:183], v[218:221], 0
	v_mfma_f32_16x16x32_bf16 v[68:71], v[172:175], v[218:221], 0
	v_mfma_f32_16x16x32_bf16 v[120:123], v[176:179], v[198:201], v[120:123]
	v_mfma_f32_16x16x32_bf16 v[116:119], v[184:187], v[198:201], v[116:119]
	v_mfma_f32_16x16x32_bf16 v[96:99], v[184:187], v[206:209], v[96:99]
	v_mfma_f32_16x16x32_bf16 v[100:103], v[176:179], v[206:209], v[100:103]
	v_mfma_f32_16x16x32_bf16 v[84:87], v[176:179], v[214:217], v[84:87]
	v_mfma_f32_16x16x32_bf16 v[80:83], v[184:187], v[214:217], v[80:83]
	v_mfma_f32_16x16x32_bf16 v[64:67], v[184:187], v[230:233], v[64:67]
	v_mfma_f32_16x16x32_bf16 v[68:71], v[176:179], v[230:233], v[68:71]
	s_barrier
	s_add_i32 s78, s78, s74
	v_lshl_add_u64 v[162:163], s[66:67], 0, v[192:193]
	s_mov_b32 m0, s78
	ds_read_b128 v[188:191], v171 offset:16384
	ds_read_b128 v[198:201], v171 offset:17408
	ds_read_b128 v[202:205], v171 offset:18432
	ds_read_b128 v[206:209], v171 offset:19456
	ds_read_b128 v[210:213], v171 offset:20480
	ds_read_b128 v[214:217], v171 offset:21504
	ds_read_b128 v[218:221], v171 offset:22528
	ds_read_b128 v[230:233], v171 offset:23552
	global_load_lds_dwordx4 v[162:163], off
	s_add_i32 m0, s78, 0x2000
	s_add_u32 s78, s66, 0x40000
	v_lshl_add_u64 v[234:235], s[66:67], 0, v[134:135]
	s_addc_u32 s79, s67, 0
	s_add_i32 s63, s63, s74
	global_load_lds_dwordx4 v[234:235], off
	v_lshl_add_u64 v[236:237], s[78:79], 0, v[192:193]
	s_mov_b32 m0, s63
	v_lshl_add_u64 v[238:239], s[70:71], 0, v[136:137]
	global_load_lds_dwordx4 v[236:237], off
	v_lshl_add_u64 v[236:237], s[78:79], 0, v[134:135]
	s_add_i32 m0, s63, 0x2000
	s_nop 0
	global_load_lds_dwordx4 v[236:237], off
	v_lshl_add_u64 v[236:237], s[70:71], 0, v[138:139]
	s_mov_b32 m0, s75
	s_nop 0
	global_load_lds_dwordx4 v[236:237], off
	s_mov_b32 m0, s81
	s_nop 0
	global_load_lds_dwordx4 v[238:239], off
	s_waitcnt vmcnt(8)
	s_waitcnt lgkmcnt(0)
	s_barrier
; #define PG8_STAGE(bufoff, gbase, voff) do { _Pragma("unroll") for (int _i = 0; _i < 2; ++_i) \
;         __builtin_amdgcn_global_load_lds((const unsigned*)((const char*)(gbase) + (voff)[_i]), (LAS unsigned*)(lds + (bufoff) + ldsw + _i * 8192), 16, 0, 0); } while (0)
; #define PG8_LDA(dst, b, h) do { _Pragma("unroll") for (int m = 0; m < 4; ++m) _Pragma("unroll") for (int k = 0; k < 2; ++k) dst[m][k] = *(const LAS bf16x8*)(lds + PG8_SA(b, h) + aoff + m * 2048 + k * 1024); } while (0)
; #define PG8_LDB(dst, b, h) do { _Pragma("unroll") for (int n = 0; n < 2; ++n) _Pragma("unroll") for (int k = 0; k < 2; ++k) dst[n][k] = *(const LAS bf16x8*)(lds + PG8_SB(b, h) + boff + n * 2048 + k * 1024); } while (0)
; #define PG8_WAIT_V(n) asm volatile("s_waitcnt vmcnt(" #n ")" ::: "memory")
; #define PG8_BAR __builtin_amdgcn_s_barrier()
; template <class Epi, class Sched>
; __device__ __forceinline__ void gemm_phase(LAS unsigned char* lds, const Gemm g, const Sched& S, const Epi& E, const int tid) {
;     ...
;         for (int t = 0; t < nt; t += 2) {
;             const bool last = (t == nt - 2);
;             const char* a1 = cA + (size_t)(t + 1) * kstep;
;             const char* a2 = last ? nA : cA + (size_t)(t + 2) * kstep; const char* b2 = last ? nB : cB + (size_t)(t + 2) * kstep;
;             const char* a3 = a2 + kstep; const char* b3 = b2 + kstep;
;             PG8_LDB(B0, 0, 0); PG8_LDB(B1, 0, 1); PG8_SCHED; PG8_LDA(At, 0, 0); PG8_STAGE(PG8_SA(1, 1), a1 + hstep, voffA);
;             PG8_WAIT_V(8); PG8_WAIT_L(0); PG8_BAR; PG8_MMA(0, 0, At, B0); PG8_MMA(0, 1, At, B1); PG8_BAR; PG8_SCHED;
;             PG8_LDA(At, 0, 1); PG8_STAGE(PG8_SB(0, 0), b2, voffB); PG8_STAGE(PG8_SB(0, 1), b2 + hstep, voffB); PG8_STAGE(PG8_SA(0, 0), a2, voffA);
;             PG8_WAIT_V(8); PG8_WAIT_L(0); PG8_BAR; PG8_MMA(1, 0, At, B0); PG8_MMA(1, 1, At, B1); PG8_BAR; PG8_SCHED;
;             PG8_LDB(B0, 1, 0); PG8_LDB(B1, 1, 1); PG8_SCHED; PG8_LDA(At, 1, 0); PG8_STAGE(PG8_SA(0, 1), a2 + hstep, voffA);
;             PG8_WAIT_V(8); PG8_WAIT_L(0); PG8_BAR; PG8_MMA(0, 0, At, B0); PG8_MMA(0, 1, At, B1); PG8_BAR; PG8_SCHED;
;             PG8_LDA(At, 1, 1); PG8_STAGE(PG8_SB(1, 0), b3, voffB); PG8_STAGE(PG8_SB(1, 1), b3 + hstep, voffB); PG8_STAGE(PG8_SA(1, 0), a3, voffA);
;             PG8_WAIT_V(8); PG8_WAIT_L(0); PG8_BAR; PG8_MMA(1, 0, At, B0); PG8_MMA(1, 1, At, B1); PG8_BAR; PG8_SCHED;
;         }
	s_waitcnt lgkmcnt(0)
	v_mfma_f32_16x16x32_bf16 v[60:63], v[146:149], v[188:191], 0
	v_mfma_f32_16x16x32_bf16 v[56:59], v[154:157], v[188:191], 0
	v_mfma_f32_16x16x32_bf16 v[40:43], v[154:157], v[202:205], 0
	v_mfma_f32_16x16x32_bf16 v[44:47], v[146:149], v[202:205], 0
	v_mfma_f32_16x16x32_bf16 v[28:31], v[146:149], v[210:213], 0
	v_mfma_f32_16x16x32_bf16 v[24:27], v[154:157], v[210:213], 0
	v_mfma_f32_16x16x32_bf16 v[8:11], v[154:157], v[218:221], 0
	v_mfma_f32_16x16x32_bf16 v[12:15], v[146:149], v[218:221], 0
	v_mfma_f32_16x16x32_bf16 v[60:63], v[150:153], v[198:201], v[60:63]
	v_mfma_f32_16x16x32_bf16 v[56:59], v[158:161], v[198:201], v[56:59]
	v_mfma_f32_16x16x32_bf16 v[40:43], v[158:161], v[206:209], v[40:43]
	v_mfma_f32_16x16x32_bf16 v[44:47], v[150:153], v[206:209], v[44:47]
	v_mfma_f32_16x16x32_bf16 v[28:31], v[150:153], v[214:217], v[28:31]
	v_mfma_f32_16x16x32_bf16 v[24:27], v[158:161], v[214:217], v[24:27]
	v_mfma_f32_16x16x32_bf16 v[8:11], v[158:161], v[230:233], v[8:11]
	v_mfma_f32_16x16x32_bf16 v[12:15], v[150:153], v[230:233], v[12:15]
	v_mfma_f32_16x16x32_bf16 v[52:55], v[172:175], v[188:191], 0
	v_mfma_f32_16x16x32_bf16 v[48:51], v[180:183], v[188:191], 0
	v_mfma_f32_16x16x32_bf16 v[32:35], v[180:183], v[202:205], 0
	v_mfma_f32_16x16x32_bf16 v[36:39], v[172:175], v[202:205], 0
	v_mfma_f32_16x16x32_bf16 v[20:23], v[172:175], v[210:213], 0
	v_mfma_f32_16x16x32_bf16 v[16:19], v[180:183], v[210:213], 0
	v_mfma_f32_16x16x32_bf16 v[0:3], v[180:183], v[218:221], 0
	v_mfma_f32_16x16x32_bf16 v[4:7], v[172:175], v[218:221], 0
	v_mfma_f32_16x16x32_bf16 v[52:55], v[176:179], v[198:201], v[52:55]
	v_mfma_f32_16x16x32_bf16 v[48:51], v[184:187], v[198:201], v[48:51]
	v_mfma_f32_16x16x32_bf16 v[32:35], v[184:187], v[206:209], v[32:35]
	v_mfma_f32_16x16x32_bf16 v[36:39], v[176:179], v[206:209], v[36:39]
	v_mfma_f32_16x16x32_bf16 v[20:23], v[176:179], v[214:217], v[20:23]
	v_mfma_f32_16x16x32_bf16 v[16:19], v[184:187], v[214:217], v[16:19]
	v_mfma_f32_16x16x32_bf16 v[0:3], v[184:187], v[230:233], v[0:3]
	v_mfma_f32_16x16x32_bf16 v[4:7], v[176:179], v[230:233], v[4:7]
	s_barrier
	s_add_i32 s63, 0, 0x18000
	v_add_u32_e32 v145, s63, v166
	s_add_i32 s78, 0, 0x1c000
	ds_read_b128 v[146:149], v145
	ds_read_b128 v[150:153], v145 offset:1024
	ds_read_b128 v[154:157], v145 offset:2048
	ds_read_b128 v[158:161], v145 offset:3072
	v_add_u32_e32 v145, s78, v166
	ds_read_b128 v[172:175], v145
	ds_read_b128 v[176:179], v145 offset:1024
	ds_read_b128 v[180:183], v145 offset:2048
	ds_read_b128 v[184:187], v145 offset:3072
	s_add_u32 s70, s70, 0x40000
	s_addc_u32 s71, s71, 0
	s_mov_b32 m0, s82
	v_lshl_add_u64 v[240:241], s[70:71], 0, v[138:139]
	ds_read_b128 v[188:191], v171 offset:32768
	ds_read_b128 v[198:201], v171 offset:33792
	ds_read_b128 v[202:205], v171 offset:34816
	ds_read_b128 v[206:209], v171 offset:35840
	ds_read_b128 v[210:213], v171 offset:36864
	ds_read_b128 v[214:217], v171 offset:37888
	ds_read_b128 v[218:221], v171 offset:38912
	ds_read_b128 v[230:233], v171 offset:39936
	global_load_lds_dwordx4 v[240:241], off
	v_lshl_add_u64 v[240:241], s[70:71], 0, v[136:137]
	s_mov_b32 m0, s83
	s_nop 0
	global_load_lds_dwordx4 v[240:241], off
	s_waitcnt vmcnt(8)
	s_waitcnt lgkmcnt(0)
	s_barrier
	s_waitcnt lgkmcnt(0)
	v_mfma_f32_16x16x32_bf16 v[128:131], v[146:149], v[188:191], v[128:131]
	v_mfma_f32_16x16x32_bf16 v[124:127], v[154:157], v[188:191], v[124:127]
	v_mfma_f32_16x16x32_bf16 v[104:107], v[154:157], v[202:205], v[104:107]
	v_mfma_f32_16x16x32_bf16 v[108:111], v[146:149], v[202:205], v[108:111]
	v_mfma_f32_16x16x32_bf16 v[92:95], v[146:149], v[210:213], v[92:95]
	v_mfma_f32_16x16x32_bf16 v[88:91], v[154:157], v[210:213], v[88:91]
	v_mfma_f32_16x16x32_bf16 v[72:75], v[154:157], v[218:221], v[72:75]
	v_mfma_f32_16x16x32_bf16 v[76:79], v[146:149], v[218:221], v[76:79]
	v_mfma_f32_16x16x32_bf16 v[128:131], v[150:153], v[198:201], v[128:131]
	v_mfma_f32_16x16x32_bf16 v[124:127], v[158:161], v[198:201], v[124:127]
	v_mfma_f32_16x16x32_bf16 v[104:107], v[158:161], v[206:209], v[104:107]
	v_mfma_f32_16x16x32_bf16 v[108:111], v[150:153], v[206:209], v[108:111]
	v_mfma_f32_16x16x32_bf16 v[92:95], v[150:153], v[214:217], v[92:95]
	v_mfma_f32_16x16x32_bf16 v[88:91], v[158:161], v[214:217], v[88:91]
	v_mfma_f32_16x16x32_bf16 v[72:75], v[158:161], v[230:233], v[72:75]
	v_mfma_f32_16x16x32_bf16 v[76:79], v[150:153], v[230:233], v[76:79]
	v_mfma_f32_16x16x32_bf16 v[120:123], v[172:175], v[188:191], v[120:123]
	v_mfma_f32_16x16x32_bf16 v[116:119], v[180:183], v[188:191], v[116:119]
	v_mfma_f32_16x16x32_bf16 v[96:99], v[180:183], v[202:205], v[96:99]
	v_mfma_f32_16x16x32_bf16 v[100:103], v[172:175], v[202:205], v[100:103]
	v_mfma_f32_16x16x32_bf16 v[84:87], v[172:175], v[210:213], v[84:87]
	v_mfma_f32_16x16x32_bf16 v[80:83], v[180:183], v[210:213], v[80:83]
	v_mfma_f32_16x16x32_bf16 v[64:67], v[180:183], v[218:221], v[64:67]
	v_mfma_f32_16x16x32_bf16 v[68:71], v[172:175], v[218:221], v[68:71]
	v_mfma_f32_16x16x32_bf16 v[120:123], v[176:179], v[198:201], v[120:123]
	v_mfma_f32_16x16x32_bf16 v[116:119], v[184:187], v[198:201], v[116:119]
	v_mfma_f32_16x16x32_bf16 v[96:99], v[184:187], v[206:209], v[96:99]
	v_mfma_f32_16x16x32_bf16 v[100:103], v[176:179], v[206:209], v[100:103]
	v_mfma_f32_16x16x32_bf16 v[84:87], v[176:179], v[214:217], v[84:87]
	v_mfma_f32_16x16x32_bf16 v[80:83], v[184:187], v[214:217], v[80:83]
	v_mfma_f32_16x16x32_bf16 v[64:67], v[184:187], v[230:233], v[64:67]
	v_mfma_f32_16x16x32_bf16 v[68:71], v[176:179], v[230:233], v[68:71]
	s_barrier
; #define PG8_STAGE(bufoff, gbase, voff) do { _Pragma("unroll") for (int _i = 0; _i < 2; ++_i) \
;         __builtin_amdgcn_global_load_lds((const unsigned*)((const char*)(gbase) + (voff)[_i]), (LAS unsigned*)(lds + (bufoff) + ldsw + _i * 8192), 16, 0, 0); } while (0)
; #define PG8_LDA(dst, b, h) do { _Pragma("unroll") for (int m = 0; m < 4; ++m) _Pragma("unroll") for (int k = 0; k < 2; ++k) dst[m][k] = *(const LAS bf16x8*)(lds + PG8_SA(b, h) + aoff + m * 2048 + k * 1024); } while (0)
; #define PG8_LDB(dst, b, h) do { _Pragma("unroll") for (int n = 0; n < 2; ++n) _Pragma("unroll") for (int k = 0; k < 2; ++k) dst[n][k] = *(const LAS bf16x8*)(lds + PG8_SB(b, h) + boff + n * 2048 + k * 1024); } while (0)
; #define PG8_WAIT_V(n) asm volatile("s_waitcnt vmcnt(" #n ")" ::: "memory")
; #define PG8_BAR __builtin_amdgcn_s_barrier()
; template <class Epi, class Sched>
; __device__ __forceinline__ void gemm_phase(LAS unsigned char* lds, const Gemm g, const Sched& S, const Epi& E, const int tid) {
;     ...
;         for (int t = 0; t < nt; t += 2) {
;             const bool last = (t == nt - 2);
;             const char* a1 = cA + (size_t)(t + 1) * kstep;
;             const char* a2 = last ? nA : cA + (size_t)(t + 2) * kstep; const char* b2 = last ? nB : cB + (size_t)(t + 2) * kstep;
;             const char* a3 = a2 + kstep; const char* b3 = b2 + kstep;
;             PG8_LDB(B0, 0, 0); PG8_LDB(B1, 0, 1); PG8_SCHED; PG8_LDA(At, 0, 0); PG8_STAGE(PG8_SA(1, 1), a1 + hstep, voffA);
;             PG8_WAIT_V(8); PG8_WAIT_L(0); PG8_BAR; PG8_MMA(0, 0, At, B0); PG8_MMA(0, 1, At, B1); PG8_BAR; PG8_SCHED;
;             PG8_LDA(At, 0, 1); PG8_STAGE(PG8_SB(0, 0), b2, voffB); PG8_STAGE(PG8_SB(0, 1), b2 + hstep, voffB); PG8_STAGE(PG8_SA(0, 0), a2, voffA);
;             PG8_WAIT_V(8); PG8_WAIT_L(0); PG8_BAR; PG8_MMA(1, 0, At, B0); PG8_MMA(1, 1, At, B1); PG8_BAR; PG8_SCHED;
;             PG8_LDB(B0, 1, 0); PG8_LDB(B1, 1, 1); PG8_SCHED; PG8_LDA(At, 1, 0); PG8_STAGE(PG8_SA(0, 1), a2 + hstep, voffA);
;             PG8_WAIT_V(8); PG8_WAIT_L(0); PG8_BAR; PG8_MMA(0, 0, At, B0); PG8_MMA(0, 1, At, B1); PG8_BAR; PG8_SCHED;
;             PG8_LDA(At, 1, 1); PG8_STAGE(PG8_SB(1, 0), b3, voffB); PG8_STAGE(PG8_SB(1, 1), b3 + hstep, voffB); PG8_STAGE(PG8_SA(1, 0), a3, voffA);
;             PG8_WAIT_V(8); PG8_WAIT_L(0); PG8_BAR; PG8_MMA(1, 0, At, B0); PG8_MMA(1, 1, At, B1); PG8_BAR; PG8_SCHED;
;         }
	s_add_i32 s63, s63, s74
	v_lshl_add_u64 v[162:163], v[162:163], 0, s[68:69]
	s_mov_b32 m0, s63
	ds_read_b128 v[188:191], v171 offset:49152
	ds_read_b128 v[198:201], v171 offset:50176
	ds_read_b128 v[202:205], v171 offset:51200
	ds_read_b128 v[206:209], v171 offset:52224
	ds_read_b128 v[210:213], v171 offset:53248
	ds_read_b128 v[214:217], v171 offset:54272
	ds_read_b128 v[218:221], v171 offset:55296
	ds_read_b128 v[230:233], v171 offset:56320
	global_load_lds_dwordx4 v[162:163], off
	s_add_i32 m0, s63, 0x2000
	s_add_u32 s66, s66, 0x40080
	v_lshl_add_u64 v[162:163], v[234:235], 0, s[68:69]
	s_addc_u32 s67, s67, 0
	s_add_i32 s63, s78, s74
	global_load_lds_dwordx4 v[162:163], off
	v_lshl_add_u64 v[162:163], s[66:67], 0, v[192:193]
	s_mov_b32 m0, s63
	s_nop 0
	global_load_lds_dwordx4 v[162:163], off
	v_lshl_add_u64 v[162:163], s[66:67], 0, v[134:135]
	s_add_i32 m0, s63, 0x2000
	s_nop 0
	global_load_lds_dwordx4 v[162:163], off
	v_lshl_add_u64 v[162:163], v[236:237], 0, s[68:69]
	s_mov_b32 m0, s93
	s_nop 0
	global_load_lds_dwordx4 v[162:163], off
	v_lshl_add_u64 v[162:163], v[238:239], 0, s[68:69]
	s_mov_b32 m0, s94
	s_nop 0
	global_load_lds_dwordx4 v[162:163], off
	s_waitcnt vmcnt(8)
	s_waitcnt lgkmcnt(0)
	s_barrier
	s_waitcnt lgkmcnt(0)
	v_mfma_f32_16x16x32_bf16 v[60:63], v[146:149], v[188:191], v[60:63]
	v_mfma_f32_16x16x32_bf16 v[56:59], v[154:157], v[188:191], v[56:59]
	v_mfma_f32_16x16x32_bf16 v[40:43], v[154:157], v[202:205], v[40:43]
	v_mfma_f32_16x16x32_bf16 v[44:47], v[146:149], v[202:205], v[44:47]
	v_mfma_f32_16x16x32_bf16 v[28:31], v[146:149], v[210:213], v[28:31]
	v_mfma_f32_16x16x32_bf16 v[24:27], v[154:157], v[210:213], v[24:27]
	v_mfma_f32_16x16x32_bf16 v[8:11], v[154:157], v[218:221], v[8:11]
	v_mfma_f32_16x16x32_bf16 v[12:15], v[146:149], v[218:221], v[12:15]
	v_mfma_f32_16x16x32_bf16 v[60:63], v[150:153], v[198:201], v[60:63]
	v_mfma_f32_16x16x32_bf16 v[56:59], v[158:161], v[198:201], v[56:59]
	v_mfma_f32_16x16x32_bf16 v[40:43], v[158:161], v[206:209], v[40:43]
	v_mfma_f32_16x16x32_bf16 v[44:47], v[150:153], v[206:209], v[44:47]
	v_mfma_f32_16x16x32_bf16 v[28:31], v[150:153], v[214:217], v[28:31]
	v_mfma_f32_16x16x32_bf16 v[24:27], v[158:161], v[214:217], v[24:27]
	v_mfma_f32_16x16x32_bf16 v[8:11], v[158:161], v[230:233], v[8:11]
	v_mfma_f32_16x16x32_bf16 v[12:15], v[150:153], v[230:233], v[12:15]
	v_mfma_f32_16x16x32_bf16 v[52:55], v[172:175], v[188:191], v[52:55]
	v_mfma_f32_16x16x32_bf16 v[48:51], v[180:183], v[188:191], v[48:51]
	v_mfma_f32_16x16x32_bf16 v[32:35], v[180:183], v[202:205], v[32:35]
	v_mfma_f32_16x16x32_bf16 v[36:39], v[172:175], v[202:205], v[36:39]
	v_mfma_f32_16x16x32_bf16 v[20:23], v[172:175], v[210:213], v[20:23]
	v_mfma_f32_16x16x32_bf16 v[16:19], v[180:183], v[210:213], v[16:19]
	v_mfma_f32_16x16x32_bf16 v[0:3], v[180:183], v[218:221], v[0:3]
	v_mfma_f32_16x16x32_bf16 v[4:7], v[172:175], v[218:221], v[4:7]
	v_mfma_f32_16x16x32_bf16 v[52:55], v[176:179], v[198:201], v[52:55]
	v_mfma_f32_16x16x32_bf16 v[48:51], v[184:187], v[198:201], v[48:51]
	v_mfma_f32_16x16x32_bf16 v[32:35], v[184:187], v[206:209], v[32:35]
	v_mfma_f32_16x16x32_bf16 v[36:39], v[176:179], v[206:209], v[36:39]
	v_mfma_f32_16x16x32_bf16 v[20:23], v[176:179], v[214:217], v[20:23]
	v_mfma_f32_16x16x32_bf16 v[16:19], v[184:187], v[214:217], v[16:19]
	v_mfma_f32_16x16x32_bf16 v[0:3], v[184:187], v[230:233], v[0:3]
	v_mfma_f32_16x16x32_bf16 v[4:7], v[176:179], v[230:233], v[4:7]
	s_barrier
	s_add_i32 s61, s61, 2
	s_add_u32 s64, s64, 0x100
	s_addc_u32 s65, s65, 0
	s_add_u32 s59, s59, 0x100
	s_addc_u32 s60, s60, 0
	s_cmp_gt_u32 s61, 13
.LBB0_168:
	s_add_u32 s63, s64, 0xfffc0080
	s_addc_u32 s66, s65, -1
	s_add_i32 s78, 0, 0x10000
	s_cmp_eq_u32 s61, 12
	s_cselect_b32 s71, s55, s66
	s_cselect_b32 s70, s56, s63
	v_add_u32_e32 v145, s78, v166
	s_cselect_b32 s67, s57, s60
	s_cselect_b32 s66, s58, s59
	s_add_i32 s63, 0, 0x14000
	ds_read_b128 v[146:149], v145
	ds_read_b128 v[150:153], v145 offset:1024
	ds_read_b128 v[154:157], v145 offset:2048
	ds_read_b128 v[158:161], v145 offset:3072
	v_add_u32_e32 v145, s63, v166
	ds_read_b128 v[172:175], v145
	ds_read_b128 v[176:179], v145 offset:1024
	ds_read_b128 v[180:183], v145 offset:2048
	ds_read_b128 v[184:187], v145 offset:3072
	v_lshl_add_u64 v[162:163], s[64:65], 0, v[140:141]
	s_add_i32 m0, s75, 0xc000
	ds_read_b128 v[188:191], v171
	ds_read_b128 v[198:201], v171 offset:1024
	ds_read_b128 v[202:205], v171 offset:2048
	ds_read_b128 v[206:209], v171 offset:3072
	ds_read_b128 v[210:213], v171 offset:4096
	ds_read_b128 v[214:217], v171 offset:5120
	ds_read_b128 v[218:221], v171 offset:6144
	ds_read_b128 v[230:233], v171 offset:7168
	global_load_lds_dwordx4 v[162:163], off
	v_lshl_add_u64 v[162:163], s[64:65], 0, v[142:143]
	s_add_i32 m0, s75, 0xe000
	s_nop 0
	global_load_lds_dwordx4 v[162:163], off
	s_waitcnt vmcnt(8)
	s_waitcnt lgkmcnt(0)
	s_barrier
; #define PG8_STAGE(bufoff, gbase, voff) do { _Pragma("unroll") for (int _i = 0; _i < 2; ++_i) \
;         __builtin_amdgcn_global_load_lds((const unsigned*)((const char*)(gbase) + (voff)[_i]), (LAS unsigned*)(lds + (bufoff) + ldsw + _i * 8192), 16, 0, 0); } while (0)
; #define PG8_LDA(dst, b, h) do { _Pragma("unroll") for (int m = 0; m < 4; ++m) _Pragma("unroll") for (int k = 0; k < 2; ++k) dst[m][k] = *(const LAS bf16x8*)(lds + PG8_SA(b, h) + aoff + m * 2048 + k * 1024); } while (0)
; #define PG8_LDB(dst, b, h) do { _Pragma("unroll") for (int n = 0; n < 2; ++n) _Pragma("unroll") for (int k = 0; k < 2; ++k) dst[n][k] = *(const LAS bf16x8*)(lds + PG8_SB(b, h) + boff + n * 2048 + k * 1024); } while (0)
; #define PG8_WAIT_V(n) asm volatile("s_waitcnt vmcnt(" #n ")" ::: "memory")
; #define PG8_BAR __builtin_amdgcn_s_barrier()
; template <class Epi, class Sched>
; __device__ __forceinline__ void gemm_phase(LAS unsigned char* lds, const Gemm g, const Sched& S, const Epi& E, const int tid) {
;     ...
;         for (int t = 0; t < nt; t += 2) {
;             const bool last = (t == nt - 2);
;             const char* a1 = cA + (size_t)(t + 1) * kstep;
;             const char* a2 = last ? nA : cA + (size_t)(t + 2) * kstep; const char* b2 = last ? nB : cB + (size_t)(t + 2) * kstep;
;             const char* a3 = a2 + kstep; const char* b3 = b2 + kstep;
;             PG8_LDB(B0, 0, 0); PG8_LDB(B1, 0, 1); PG8_SCHED; PG8_LDA(At, 0, 0); PG8_STAGE(PG8_SA(1, 1), a1 + hstep, voffA);
;             PG8_WAIT_V(8); PG8_WAIT_L(0); PG8_BAR; PG8_MMA(0, 0, At, B0); PG8_MMA(0, 1, At, B1); PG8_BAR; PG8_SCHED;
;             PG8_LDA(At, 0, 1); PG8_STAGE(PG8_SB(0, 0), b2, voffB); PG8_STAGE(PG8_SB(0, 1), b2 + hstep, voffB); PG8_STAGE(PG8_SA(0, 0), a2, voffA);
;             PG8_WAIT_V(8); PG8_WAIT_L(0); PG8_BAR; PG8_MMA(1, 0, At, B0); PG8_MMA(1, 1, At, B1); PG8_BAR; PG8_SCHED;
;             PG8_LDB(B0, 1, 0); PG8_LDB(B1, 1, 1); PG8_SCHED; PG8_LDA(At, 1, 0); PG8_STAGE(PG8_SA(0, 1), a2 + hstep, voffA);
;             PG8_WAIT_V(8); PG8_WAIT_L(0); PG8_BAR; PG8_MMA(0, 0, At, B0); PG8_MMA(0, 1, At, B1); PG8_BAR; PG8_SCHED;
;             PG8_LDA(At, 1, 1); PG8_STAGE(PG8_SB(1, 0), b3, voffB); PG8_STAGE(PG8_SB(1, 1), b3 + hstep, voffB); PG8_STAGE(PG8_SA(1, 0), a3, voffA);
;             PG8_WAIT_V(8); PG8_WAIT_L(0); PG8_BAR; PG8_MMA(1, 0, At, B0); PG8_MMA(1, 1, At, B1); PG8_BAR; PG8_SCHED;
;         }
	s_waitcnt lgkmcnt(0)
	v_mfma_f32_16x16x32_bf16 v[128:131], v[146:149], v[188:191], v[128:131]
	v_mfma_f32_16x16x32_bf16 v[124:127], v[154:157], v[188:191], v[124:127]
	v_mfma_f32_16x16x32_bf16 v[104:107], v[154:157], v[202:205], v[104:107]
	v_mfma_f32_16x16x32_bf16 v[108:111], v[146:149], v[202:205], v[108:111]
	v_mfma_f32_16x16x32_bf16 v[92:95], v[146:149], v[210:213], v[92:95]
	v_mfma_f32_16x16x32_bf16 v[88:91], v[154:157], v[210:213], v[88:91]
	v_mfma_f32_16x16x32_bf16 v[72:75], v[154:157], v[218:221], v[72:75]
	v_mfma_f32_16x16x32_bf16 v[76:79], v[146:149], v[218:221], v[76:79]
	v_mfma_f32_16x16x32_bf16 v[128:131], v[150:153], v[198:201], v[128:131]
	v_mfma_f32_16x16x32_bf16 v[124:127], v[158:161], v[198:201], v[124:127]
	v_mfma_f32_16x16x32_bf16 v[104:107], v[158:161], v[206:209], v[104:107]
	v_mfma_f32_16x16x32_bf16 v[108:111], v[150:153], v[206:209], v[108:111]
	v_mfma_f32_16x16x32_bf16 v[92:95], v[150:153], v[214:217], v[92:95]
	v_mfma_f32_16x16x32_bf16 v[88:91], v[158:161], v[214:217], v[88:91]
	v_mfma_f32_16x16x32_bf16 v[72:75], v[158:161], v[230:233], v[72:75]
	v_mfma_f32_16x16x32_bf16 v[76:79], v[150:153], v[230:233], v[76:79]
	v_mfma_f32_16x16x32_bf16 v[120:123], v[172:175], v[188:191], v[120:123]
	v_mfma_f32_16x16x32_bf16 v[116:119], v[180:183], v[188:191], v[116:119]
	v_mfma_f32_16x16x32_bf16 v[96:99], v[180:183], v[202:205], v[96:99]
	v_mfma_f32_16x16x32_bf16 v[100:103], v[172:175], v[202:205], v[100:103]
	v_mfma_f32_16x16x32_bf16 v[84:87], v[172:175], v[210:213], v[84:87]
	v_mfma_f32_16x16x32_bf16 v[80:83], v[180:183], v[210:213], v[80:83]
	v_mfma_f32_16x16x32_bf16 v[64:67], v[180:183], v[218:221], v[64:67]
	v_mfma_f32_16x16x32_bf16 v[68:71], v[172:175], v[218:221], v[68:71]
	v_mfma_f32_16x16x32_bf16 v[120:123], v[176:179], v[198:201], v[120:123]
	v_mfma_f32_16x16x32_bf16 v[116:119], v[184:187], v[198:201], v[116:119]
	v_mfma_f32_16x16x32_bf16 v[96:99], v[184:187], v[206:209], v[96:99]
	v_mfma_f32_16x16x32_bf16 v[100:103], v[176:179], v[206:209], v[100:103]
	v_mfma_f32_16x16x32_bf16 v[84:87], v[176:179], v[214:217], v[84:87]
	v_mfma_f32_16x16x32_bf16 v[80:83], v[184:187], v[214:217], v[80:83]
	v_mfma_f32_16x16x32_bf16 v[64:67], v[184:187], v[230:233], v[64:67]
	v_mfma_f32_16x16x32_bf16 v[68:71], v[176:179], v[230:233], v[68:71]
	s_barrier
	s_add_i32 s78, s78, s74
	v_lshl_add_u64 v[162:163], s[66:67], 0, v[192:193]
	s_mov_b32 m0, s78
	ds_read_b128 v[188:191], v171 offset:16384
	ds_read_b128 v[198:201], v171 offset:17408
	ds_read_b128 v[202:205], v171 offset:18432
	ds_read_b128 v[206:209], v171 offset:19456
	ds_read_b128 v[210:213], v171 offset:20480
	ds_read_b128 v[214:217], v171 offset:21504
	ds_read_b128 v[218:221], v171 offset:22528
	ds_read_b128 v[230:233], v171 offset:23552
	global_load_lds_dwordx4 v[162:163], off
	s_add_i32 m0, s78, 0x2000
	s_add_u32 s78, s66, 0x40000
	v_lshl_add_u64 v[234:235], s[66:67], 0, v[134:135]
	s_addc_u32 s79, s67, 0
	s_add_i32 s63, s63, s74
	global_load_lds_dwordx4 v[234:235], off
	v_lshl_add_u64 v[236:237], s[78:79], 0, v[192:193]
	s_mov_b32 m0, s63
	v_lshl_add_u64 v[238:239], s[70:71], 0, v[136:137]
	global_load_lds_dwordx4 v[236:237], off
	v_lshl_add_u64 v[236:237], s[78:79], 0, v[134:135]
	s_add_i32 m0, s63, 0x2000
	s_nop 0
	global_load_lds_dwordx4 v[236:237], off
	v_lshl_add_u64 v[236:237], s[70:71], 0, v[138:139]
	s_mov_b32 m0, s75
	s_nop 0
	global_load_lds_dwordx4 v[236:237], off
	s_mov_b32 m0, s81
	s_nop 0
	global_load_lds_dwordx4 v[238:239], off
	s_waitcnt vmcnt(8)
	s_waitcnt lgkmcnt(0)
	s_barrier
	s_waitcnt lgkmcnt(0)
	v_mfma_f32_16x16x32_bf16 v[60:63], v[146:149], v[188:191], v[60:63]
	v_mfma_f32_16x16x32_bf16 v[56:59], v[154:157], v[188:191], v[56:59]
	v_mfma_f32_16x16x32_bf16 v[40:43], v[154:157], v[202:205], v[40:43]
	v_mfma_f32_16x16x32_bf16 v[44:47], v[146:149], v[202:205], v[44:47]
	v_mfma_f32_16x16x32_bf16 v[28:31], v[146:149], v[210:213], v[28:31]
	v_mfma_f32_16x16x32_bf16 v[24:27], v[154:157], v[210:213], v[24:27]
	v_mfma_f32_16x16x32_bf16 v[8:11], v[154:157], v[218:221], v[8:11]
	v_mfma_f32_16x16x32_bf16 v[12:15], v[146:149], v[218:221], v[12:15]
	v_mfma_f32_16x16x32_bf16 v[60:63], v[150:153], v[198:201], v[60:63]
	v_mfma_f32_16x16x32_bf16 v[56:59], v[158:161], v[198:201], v[56:59]
	v_mfma_f32_16x16x32_bf16 v[40:43], v[158:161], v[206:209], v[40:43]
	v_mfma_f32_16x16x32_bf16 v[44:47], v[150:153], v[206:209], v[44:47]
	v_mfma_f32_16x16x32_bf16 v[28:31], v[150:153], v[214:217], v[28:31]
	v_mfma_f32_16x16x32_bf16 v[24:27], v[158:161], v[214:217], v[24:27]
	v_mfma_f32_16x16x32_bf16 v[8:11], v[158:161], v[230:233], v[8:11]
	v_mfma_f32_16x16x32_bf16 v[12:15], v[150:153], v[230:233], v[12:15]
	v_mfma_f32_16x16x32_bf16 v[52:55], v[172:175], v[188:191], v[52:55]
	v_mfma_f32_16x16x32_bf16 v[48:51], v[180:183], v[188:191], v[48:51]
	v_mfma_f32_16x16x32_bf16 v[32:35], v[180:183], v[202:205], v[32:35]
	v_mfma_f32_16x16x32_bf16 v[36:39], v[172:175], v[202:205], v[36:39]
	v_mfma_f32_16x16x32_bf16 v[20:23], v[172:175], v[210:213], v[20:23]
	v_mfma_f32_16x16x32_bf16 v[16:19], v[180:183], v[210:213], v[16:19]
	v_mfma_f32_16x16x32_bf16 v[0:3], v[180:183], v[218:221], v[0:3]
	v_mfma_f32_16x16x32_bf16 v[4:7], v[172:175], v[218:221], v[4:7]
	v_mfma_f32_16x16x32_bf16 v[52:55], v[176:179], v[198:201], v[52:55]
	v_mfma_f32_16x16x32_bf16 v[48:51], v[184:187], v[198:201], v[48:51]
	v_mfma_f32_16x16x32_bf16 v[32:35], v[184:187], v[206:209], v[32:35]
	v_mfma_f32_16x16x32_bf16 v[36:39], v[176:179], v[206:209], v[36:39]
	v_mfma_f32_16x16x32_bf16 v[20:23], v[176:179], v[214:217], v[20:23]
	v_mfma_f32_16x16x32_bf16 v[16:19], v[184:187], v[214:217], v[16:19]
	v_mfma_f32_16x16x32_bf16 v[0:3], v[184:187], v[230:233], v[0:3]
	v_mfma_f32_16x16x32_bf16 v[4:7], v[176:179], v[230:233], v[4:7]
	s_barrier
; #define PG8_STAGE(bufoff, gbase, voff) do { _Pragma("unroll") for (int _i = 0; _i < 2; ++_i) \
;         __builtin_amdgcn_global_load_lds((const unsigned*)((const char*)(gbase) + (voff)[_i]), (LAS unsigned*)(lds + (bufoff) + ldsw + _i * 8192), 16, 0, 0); } while (0)
; #define PG8_LDA(dst, b, h) do { _Pragma("unroll") for (int m = 0; m < 4; ++m) _Pragma("unroll") for (int k = 0; k < 2; ++k) dst[m][k] = *(const LAS bf16x8*)(lds + PG8_SA(b, h) + aoff + m * 2048 + k * 1024); } while (0)
; #define PG8_LDB(dst, b, h) do { _Pragma("unroll") for (int n = 0; n < 2; ++n) _Pragma("unroll") for (int k = 0; k < 2; ++k) dst[n][k] = *(const LAS bf16x8*)(lds + PG8_SB(b, h) + boff + n * 2048 + k * 1024); } while (0)
; #define PG8_WAIT_V(n) asm volatile("s_waitcnt vmcnt(" #n ")" ::: "memory")
; #define PG8_BAR __builtin_amdgcn_s_barrier()
; template <class Epi, class Sched>
; __device__ __forceinline__ void gemm_phase(LAS unsigned char* lds, const Gemm g, const Sched& S, const Epi& E, const int tid) {
;     ...
;         for (int t = 0; t < nt; t += 2) {
;             const bool last = (t == nt - 2);
;             const char* a1 = cA + (size_t)(t + 1) * kstep;
;             const char* a2 = last ? nA : cA + (size_t)(t + 2) * kstep; const char* b2 = last ? nB : cB + (size_t)(t + 2) * kstep;
;             const char* a3 = a2 + kstep; const char* b3 = b2 + kstep;
;             PG8_LDB(B0, 0, 0); PG8_LDB(B1, 0, 1); PG8_SCHED; PG8_LDA(At, 0, 0); PG8_STAGE(PG8_SA(1, 1), a1 + hstep, voffA);
;             PG8_WAIT_V(8); PG8_WAIT_L(0); PG8_BAR; PG8_MMA(0, 0, At, B0); PG8_MMA(0, 1, At, B1); PG8_BAR; PG8_SCHED;
;             PG8_LDA(At, 0, 1); PG8_STAGE(PG8_SB(0, 0), b2, voffB); PG8_STAGE(PG8_SB(0, 1), b2 + hstep, voffB); PG8_STAGE(PG8_SA(0, 0), a2, voffA);
;             PG8_WAIT_V(8); PG8_WAIT_L(0); PG8_BAR; PG8_MMA(1, 0, At, B0); PG8_MMA(1, 1, At, B1); PG8_BAR; PG8_SCHED;
;             PG8_LDB(B0, 1, 0); PG8_LDB(B1, 1, 1); PG8_SCHED; PG8_LDA(At, 1, 0); PG8_STAGE(PG8_SA(0, 1), a2 + hstep, voffA);
;             PG8_WAIT_V(8); PG8_WAIT_L(0); PG8_BAR; PG8_MMA(0, 0, At, B0); PG8_MMA(0, 1, At, B1); PG8_BAR; PG8_SCHED;
;             PG8_LDA(At, 1, 1); PG8_STAGE(PG8_SB(1, 0), b3, voffB); PG8_STAGE(PG8_SB(1, 1), b3 + hstep, voffB); PG8_STAGE(PG8_SA(1, 0), a3, voffA);
;             PG8_WAIT_V(8); PG8_WAIT_L(0); PG8_BAR; PG8_MMA(1, 0, At, B0); PG8_MMA(1, 1, At, B1); PG8_BAR; PG8_SCHED;
;         }
	s_add_i32 s63, 0, 0x18000
	v_add_u32_e32 v145, s63, v166
	s_add_i32 s78, 0, 0x1c000
	ds_read_b128 v[146:149], v145
	ds_read_b128 v[150:153], v145 offset:1024
	ds_read_b128 v[154:157], v145 offset:2048
	ds_read_b128 v[158:161], v145 offset:3072
	v_add_u32_e32 v145, s78, v166
	ds_read_b128 v[172:175], v145
	ds_read_b128 v[176:179], v145 offset:1024
	ds_read_b128 v[180:183], v145 offset:2048
	ds_read_b128 v[184:187], v145 offset:3072
	s_add_u32 s70, s70, 0x40000
	s_addc_u32 s71, s71, 0
	s_mov_b32 m0, s82
	v_lshl_add_u64 v[240:241], s[70:71], 0, v[138:139]
	ds_read_b128 v[188:191], v171 offset:32768
	ds_read_b128 v[198:201], v171 offset:33792
	ds_read_b128 v[202:205], v171 offset:34816
	ds_read_b128 v[206:209], v171 offset:35840
	ds_read_b128 v[210:213], v171 offset:36864
	ds_read_b128 v[214:217], v171 offset:37888
	ds_read_b128 v[218:221], v171 offset:38912
	ds_read_b128 v[230:233], v171 offset:39936
	global_load_lds_dwordx4 v[240:241], off
	v_lshl_add_u64 v[240:241], s[70:71], 0, v[136:137]
	s_mov_b32 m0, s83
	s_nop 0
	global_load_lds_dwordx4 v[240:241], off
	s_waitcnt vmcnt(8)
	s_waitcnt lgkmcnt(0)
	s_barrier
	s_waitcnt lgkmcnt(0)
	v_mfma_f32_16x16x32_bf16 v[128:131], v[146:149], v[188:191], v[128:131]
	v_mfma_f32_16x16x32_bf16 v[124:127], v[154:157], v[188:191], v[124:127]
	v_mfma_f32_16x16x32_bf16 v[104:107], v[154:157], v[202:205], v[104:107]
	v_mfma_f32_16x16x32_bf16 v[108:111], v[146:149], v[202:205], v[108:111]
	v_mfma_f32_16x16x32_bf16 v[92:95], v[146:149], v[210:213], v[92:95]
	v_mfma_f32_16x16x32_bf16 v[88:91], v[154:157], v[210:213], v[88:91]
	v_mfma_f32_16x16x32_bf16 v[72:75], v[154:157], v[218:221], v[72:75]
	v_mfma_f32_16x16x32_bf16 v[76:79], v[146:149], v[218:221], v[76:79]
	v_mfma_f32_16x16x32_bf16 v[128:131], v[150:153], v[198:201], v[128:131]
	v_mfma_f32_16x16x32_bf16 v[124:127], v[158:161], v[198:201], v[124:127]
	v_mfma_f32_16x16x32_bf16 v[104:107], v[158:161], v[206:209], v[104:107]
	v_mfma_f32_16x16x32_bf16 v[108:111], v[150:153], v[206:209], v[108:111]
	v_mfma_f32_16x16x32_bf16 v[92:95], v[150:153], v[214:217], v[92:95]
	v_mfma_f32_16x16x32_bf16 v[88:91], v[158:161], v[214:217], v[88:91]
	v_mfma_f32_16x16x32_bf16 v[72:75], v[158:161], v[230:233], v[72:75]
	v_mfma_f32_16x16x32_bf16 v[76:79], v[150:153], v[230:233], v[76:79]
	v_mfma_f32_16x16x32_bf16 v[120:123], v[172:175], v[188:191], v[120:123]
	v_mfma_f32_16x16x32_bf16 v[116:119], v[180:183], v[188:191], v[116:119]
	v_mfma_f32_16x16x32_bf16 v[96:99], v[180:183], v[202:205], v[96:99]
	v_mfma_f32_16x16x32_bf16 v[100:103], v[172:175], v[202:205], v[100:103]
	v_mfma_f32_16x16x32_bf16 v[84:87], v[172:175], v[210:213], v[84:87]
	v_mfma_f32_16x16x32_bf16 v[80:83], v[180:183], v[210:213], v[80:83]
	v_mfma_f32_16x16x32_bf16 v[64:67], v[180:183], v[218:221], v[64:67]
	v_mfma_f32_16x16x32_bf16 v[68:71], v[172:175], v[218:221], v[68:71]
	v_mfma_f32_16x16x32_bf16 v[120:123], v[176:179], v[198:201], v[120:123]
	v_mfma_f32_16x16x32_bf16 v[116:119], v[184:187], v[198:201], v[116:119]
	v_mfma_f32_16x16x32_bf16 v[96:99], v[184:187], v[206:209], v[96:99]
	v_mfma_f32_16x16x32_bf16 v[100:103], v[176:179], v[206:209], v[100:103]
	v_mfma_f32_16x16x32_bf16 v[84:87], v[176:179], v[214:217], v[84:87]
	v_mfma_f32_16x16x32_bf16 v[80:83], v[184:187], v[214:217], v[80:83]
	v_mfma_f32_16x16x32_bf16 v[64:67], v[184:187], v[230:233], v[64:67]
	v_mfma_f32_16x16x32_bf16 v[68:71], v[176:179], v[230:233], v[68:71]
	s_barrier
; #define PG8_STAGE(bufoff, gbase, voff) do { _Pragma("unroll") for (int _i = 0; _i < 2; ++_i) \
;         __builtin_amdgcn_global_load_lds((const unsigned*)((const char*)(gbase) + (voff)[_i]), (LAS unsigned*)(lds + (bufoff) + ldsw + _i * 8192), 16, 0, 0); } while (0)
; #define PG8_LDA(dst, b, h) do { _Pragma("unroll") for (int m = 0; m < 4; ++m) _Pragma("unroll") for (int k = 0; k < 2; ++k) dst[m][k] = *(const LAS bf16x8*)(lds + PG8_SA(b, h) + aoff + m * 2048 + k * 1024); } while (0)
; #define PG8_LDB(dst, b, h) do { _Pragma("unroll") for (int n = 0; n < 2; ++n) _Pragma("unroll") for (int k = 0; k < 2; ++k) dst[n][k] = *(const LAS bf16x8*)(lds + PG8_SB(b, h) + boff + n * 2048 + k * 1024); } while (0)
; #define PG8_WAIT_V(n) asm volatile("s_waitcnt vmcnt(" #n ")" ::: "memory")
; #define PG8_BAR __builtin_amdgcn_s_barrier()
; template <class Epi, class Sched>
; __device__ __forceinline__ void gemm_phase(LAS unsigned char* lds, const Gemm g, const Sched& S, const Epi& E, const int tid) {
;     ...
;         for (int t = 0; t < nt; t += 2) {
;             const bool last = (t == nt - 2);
;             const char* a1 = cA + (size_t)(t + 1) * kstep;
;             const char* a2 = last ? nA : cA + (size_t)(t + 2) * kstep; const char* b2 = last ? nB : cB + (size_t)(t + 2) * kstep;
;             const char* a3 = a2 + kstep; const char* b3 = b2 + kstep;
;             PG8_LDB(B0, 0, 0); PG8_LDB(B1, 0, 1); PG8_SCHED; PG8_LDA(At, 0, 0); PG8_STAGE(PG8_SA(1, 1), a1 + hstep, voffA);
;             PG8_WAIT_V(8); PG8_WAIT_L(0); PG8_BAR; PG8_MMA(0, 0, At, B0); PG8_MMA(0, 1, At, B1); PG8_BAR; PG8_SCHED;
;             PG8_LDA(At, 0, 1); PG8_STAGE(PG8_SB(0, 0), b2, voffB); PG8_STAGE(PG8_SB(0, 1), b2 + hstep, voffB); PG8_STAGE(PG8_SA(0, 0), a2, voffA);
;             PG8_WAIT_V(8); PG8_WAIT_L(0); PG8_BAR; PG8_MMA(1, 0, At, B0); PG8_MMA(1, 1, At, B1); PG8_BAR; PG8_SCHED;
;             PG8_LDB(B0, 1, 0); PG8_LDB(B1, 1, 1); PG8_SCHED; PG8_LDA(At, 1, 0); PG8_STAGE(PG8_SA(0, 1), a2 + hstep, voffA);
;             PG8_WAIT_V(8); PG8_WAIT_L(0); PG8_BAR; PG8_MMA(0, 0, At, B0); PG8_MMA(0, 1, At, B1); PG8_BAR; PG8_SCHED;
;             PG8_LDA(At, 1, 1); PG8_STAGE(PG8_SB(1, 0), b3, voffB); PG8_STAGE(PG8_SB(1, 1), b3 + hstep, voffB); PG8_STAGE(PG8_SA(1, 0), a3, voffA);
;             PG8_WAIT_V(8); PG8_WAIT_L(0); PG8_BAR; PG8_MMA(1, 0, At, B0); PG8_MMA(1, 1, At, B1); PG8_BAR; PG8_SCHED;
;         }
	s_add_i32 s63, s63, s74
	v_lshl_add_u64 v[162:163], v[162:163], 0, s[68:69]
	s_mov_b32 m0, s63
	ds_read_b128 v[188:191], v171 offset:49152
	ds_read_b128 v[198:201], v171 offset:50176
	ds_read_b128 v[202:205], v171 offset:51200
	ds_read_b128 v[206:209], v171 offset:52224
	ds_read_b128 v[210:213], v171 offset:53248
	ds_read_b128 v[214:217], v171 offset:54272
	ds_read_b128 v[218:221], v171 offset:55296
	ds_read_b128 v[230:233], v171 offset:56320
	global_load_lds_dwordx4 v[162:163], off
	s_add_i32 m0, s63, 0x2000
	s_add_u32 s66, s66, 0x40080
	v_lshl_add_u64 v[162:163], v[234:235], 0, s[68:69]
	s_addc_u32 s67, s67, 0
	s_add_i32 s63, s78, s74
	global_load_lds_dwordx4 v[162:163], off
	v_lshl_add_u64 v[162:163], s[66:67], 0, v[192:193]
	s_mov_b32 m0, s63
	s_nop 0
	global_load_lds_dwordx4 v[162:163], off
	v_lshl_add_u64 v[162:163], s[66:67], 0, v[134:135]
	s_add_i32 m0, s63, 0x2000
	s_nop 0
	global_load_lds_dwordx4 v[162:163], off
	v_lshl_add_u64 v[162:163], v[236:237], 0, s[68:69]
	s_mov_b32 m0, s93
	s_nop 0
	global_load_lds_dwordx4 v[162:163], off
	v_lshl_add_u64 v[162:163], v[238:239], 0, s[68:69]
	s_mov_b32 m0, s94
	s_nop 0
	global_load_lds_dwordx4 v[162:163], off
	s_waitcnt vmcnt(8)
	s_waitcnt lgkmcnt(0)
	s_barrier
	s_waitcnt lgkmcnt(0)
	v_mfma_f32_16x16x32_bf16 v[60:63], v[146:149], v[188:191], v[60:63]
	v_mfma_f32_16x16x32_bf16 v[56:59], v[154:157], v[188:191], v[56:59]
	v_mfma_f32_16x16x32_bf16 v[40:43], v[154:157], v[202:205], v[40:43]
	v_mfma_f32_16x16x32_bf16 v[44:47], v[146:149], v[202:205], v[44:47]
	v_mfma_f32_16x16x32_bf16 v[28:31], v[146:149], v[210:213], v[28:31]
	v_mfma_f32_16x16x32_bf16 v[24:27], v[154:157], v[210:213], v[24:27]
	v_mfma_f32_16x16x32_bf16 v[8:11], v[154:157], v[218:221], v[8:11]
	v_mfma_f32_16x16x32_bf16 v[12:15], v[146:149], v[218:221], v[12:15]
	v_mfma_f32_16x16x32_bf16 v[60:63], v[150:153], v[198:201], v[60:63]
	v_mfma_f32_16x16x32_bf16 v[56:59], v[158:161], v[198:201], v[56:59]
	v_mfma_f32_16x16x32_bf16 v[40:43], v[158:161], v[206:209], v[40:43]
	v_mfma_f32_16x16x32_bf16 v[44:47], v[150:153], v[206:209], v[44:47]
	v_mfma_f32_16x16x32_bf16 v[28:31], v[150:153], v[214:217], v[28:31]
	v_mfma_f32_16x16x32_bf16 v[24:27], v[158:161], v[214:217], v[24:27]
	v_mfma_f32_16x16x32_bf16 v[8:11], v[158:161], v[230:233], v[8:11]
	v_mfma_f32_16x16x32_bf16 v[12:15], v[150:153], v[230:233], v[12:15]
	v_mfma_f32_16x16x32_bf16 v[52:55], v[172:175], v[188:191], v[52:55]
	v_mfma_f32_16x16x32_bf16 v[48:51], v[180:183], v[188:191], v[48:51]
	v_mfma_f32_16x16x32_bf16 v[32:35], v[180:183], v[202:205], v[32:35]
	v_mfma_f32_16x16x32_bf16 v[36:39], v[172:175], v[202:205], v[36:39]
	v_mfma_f32_16x16x32_bf16 v[20:23], v[172:175], v[210:213], v[20:23]
	v_mfma_f32_16x16x32_bf16 v[16:19], v[180:183], v[210:213], v[16:19]
	v_mfma_f32_16x16x32_bf16 v[0:3], v[180:183], v[218:221], v[0:3]
	v_mfma_f32_16x16x32_bf16 v[4:7], v[172:175], v[218:221], v[4:7]
	v_mfma_f32_16x16x32_bf16 v[52:55], v[176:179], v[198:201], v[52:55]
	v_mfma_f32_16x16x32_bf16 v[48:51], v[184:187], v[198:201], v[48:51]
	v_mfma_f32_16x16x32_bf16 v[32:35], v[184:187], v[206:209], v[32:35]
	v_mfma_f32_16x16x32_bf16 v[36:39], v[176:179], v[206:209], v[36:39]
	v_mfma_f32_16x16x32_bf16 v[20:23], v[176:179], v[214:217], v[20:23]
	v_mfma_f32_16x16x32_bf16 v[16:19], v[184:187], v[214:217], v[16:19]
	v_mfma_f32_16x16x32_bf16 v[0:3], v[184:187], v[230:233], v[0:3]
	v_mfma_f32_16x16x32_bf16 v[4:7], v[176:179], v[230:233], v[4:7]
	s_barrier
	s_add_i32 s61, s61, 2
	s_add_u32 s64, s64, 0x100
	s_addc_u32 s65, s65, 0
	s_add_u32 s59, s59, 0x100
	s_addc_u32 s60, s60, 0
	s_cmp_gt_u32 s61, 13
	s_cbranch_scc0 .LBB0_168
	s_and_b64 vcc, exec, s[50:51]
	s_cbranch_vccz .LBB0_171
	s_barrier

;     __device__ __forceinline__ Pre prefetch(const Unit& u, int tid) const { return prenorm_load(stats, u.pn * BM, sW + (size_t)(u.pn >> 4) * SW_ROWS + u.pm * BM, tid); }
;     __device__ __forceinline__ Pre prefetch(const Unit& u, int tid) const { return prenorm_load(stats, u.pm * BM, sW + (size_t)(u.pm >> 4) * SW_ROWS + u.pn * BM, tid); }
;     __device__ __forceinline__ Pre prefetch(const Unit& u, int tid) const { return prenorm_load(stats, u.pm * BM, sW + (size_t)(u.pm >> 4) * SW_ROWS + u.pn * BM, tid); }
; #define PG8_STAGE(bufoff, gbase, voff) do { _Pragma("unroll") for (int _i = 0; _i < 2; ++_i) \
;         __builtin_amdgcn_global_load_lds((const unsigned*)((const char*)(gbase) + (voff)[_i]), (LAS unsigned*)(lds + (bufoff) + ldsw + _i * 8192), 16, 0, 0); } while (0)
; #define PG8_LDA(dst, b, h) do { _Pragma("unroll") for (int m = 0; m < 4; ++m) _Pragma("unroll") for (int k = 0; k < 2; ++k) dst[m][k] = *(const LAS bf16x8*)(lds + PG8_SA(b, h) + aoff + m * 2048 + k * 1024); } while (0)
; #define PG8_WAIT_V(n) asm volatile("s_waitcnt vmcnt(" #n ")" ::: "memory")
; template <class Epi, class Sched>
; __device__ __forceinline__ void gemm_phase(LAS unsigned char* lds, const Gemm g, const Sched& S, const Epi& E, const int tid) {
;     ...
;         const bool has_next = S.next(ui + 1, nxt);
;         const char* nA = has_next ? (const char*)g.A + (size_t)nxt.pm * tstep : cA; const char* nB = has_next ? (const char*)g.Bt + (size_t)nxt.pn * tstep : cB;
;         const typename Epi::Pre pre = E.prefetch(cur, tid);
;         for (int t = 0; t < nt; t += 2) {
;             const bool last = (t == nt - 2);
;             const char* a1 = cA + (size_t)(t + 1) * kstep;
;             const char* a2 = last ? nA : cA + (size_t)(t + 2) * kstep; const char* b2 = last ? nB : cB + (size_t)(t + 2) * kstep;
;             const char* a3 = a2 + kstep; const char* b3 = b2 + kstep;
;             PG8_LDB(B0, 0, 0); PG8_LDB(B1, 0, 1); PG8_SCHED; PG8_LDA(At, 0, 0); PG8_STAGE(PG8_SA(1, 1), a1 + hstep, voffA);
;             PG8_WAIT_V(8); PG8_WAIT_L(0); PG8_BAR; PG8_MMA(0, 0, At, B0); PG8_MMA(0, 1, At, B1); PG8_BAR; PG8_SCHED;
;             PG8_LDA(At, 0, 1); PG8_STAGE(PG8_SB(0, 0), b2, voffB); PG8_STAGE(PG8_SB(0, 1), b2 + hstep, voffB); PG8_STAGE(PG8_SA(0, 0), a2, voffA);
;             PG8_WAIT_V(8); PG8_WAIT_L(0); PG8_BAR; PG8_MMA(1, 0, At, B0); PG8_MMA(1, 1, At, B1); PG8_BAR; PG8_SCHED;
.LBB0_265:
	s_or_b64 exec, exec, s[38:39]
	s_ashr_i32 s23, s22, 31
	s_lshl_b64 s[38:39], s[22:23], 19
	s_add_u32 s38, s46, s38
	s_addc_u32 s39, s47, s39
	s_and_b64 s[56:57], s[4:5], exec
	s_cselect_b32 s23, s39, s7
	s_cselect_b32 s56, s38, s6
	s_ashr_i32 s55, s54, 31
	s_lshl_b64 s[58:59], s[54:55], 19
	s_add_u32 s62, s35, s58
	s_addc_u32 s63, s84, s59
	s_and_b64 s[58:59], s[4:5], exec
	s_cselect_b32 s55, s63, s65
	s_cselect_b32 s57, s62, s64
	s_add_u32 s6, s6, 0x40080
	s_addc_u32 s7, s7, 0
	s_add_u32 s58, s64, 0x100
	s_addc_u32 s59, s65, 0
	s_mov_b32 s60, -2
	s_add_u32 s61, s6, 0xfffc0080
	s_addc_u32 s64, s7, -1
	s_add_i32 s70, 0, 0x10000
	s_cmp_eq_u32 s60, 12
	s_cselect_b32 s67, s23, s64
	s_cselect_b32 s66, s56, s61
	v_add_u32_e32 v81, s70, v216
	s_cselect_b32 s65, s55, s59
	s_cselect_b32 s64, s57, s58
	s_add_i32 s61, 0, 0x14000
	ds_read_b128 v[88:91], v81
	ds_read_b128 v[92:95], v81 offset:1024
	ds_read_b128 v[144:147], v81 offset:2048
	ds_read_b128 v[148:151], v81 offset:3072
	v_add_u32_e32 v81, s61, v216
	ds_read_b128 v[152:155], v81
	ds_read_b128 v[156:159], v81 offset:1024
	ds_read_b128 v[178:181], v81 offset:2048
	ds_read_b128 v[182:185], v81 offset:3072
	v_lshl_add_u64 v[82:83], s[6:7], 0, v[174:175]
	s_add_i32 m0, s73, 0xc000
	ds_read_b128 v[186:189], v230
	ds_read_b128 v[198:201], v230 offset:1024
	ds_read_b128 v[202:205], v230 offset:2048
	ds_read_b128 v[206:209], v230 offset:3072
	ds_read_b128 v[234:237], v230 offset:4096
	ds_read_b128 v[238:241], v230 offset:5120
	ds_read_b128 v[242:245], v230 offset:6144
	ds_read_b128 v[246:249], v230 offset:7168
	global_load_lds_dwordx4 v[82:83], off
	v_lshl_add_u64 v[82:83], s[6:7], 0, v[176:177]
	s_add_i32 m0, s73, 0xe000
	s_nop 0
	global_load_lds_dwordx4 v[82:83], off
	s_waitcnt vmcnt(8)
	s_waitcnt lgkmcnt(0)
	s_barrier
	s_waitcnt lgkmcnt(0)
	v_mfma_f32_16x16x32_bf16 v[140:143], v[88:91], v[186:189], 0
	v_mfma_f32_16x16x32_bf16 v[136:139], v[144:147], v[186:189], 0
	v_mfma_f32_16x16x32_bf16 v[120:123], v[144:147], v[202:205], 0
	v_mfma_f32_16x16x32_bf16 v[124:127], v[88:91], v[202:205], 0
	v_mfma_f32_16x16x32_bf16 v[108:111], v[88:91], v[234:237], 0
	v_mfma_f32_16x16x32_bf16 v[104:107], v[144:147], v[234:237], 0
	v_mfma_f32_16x16x32_bf16 v[76:79], v[144:147], v[242:245], 0
	v_mfma_f32_16x16x32_bf16 v[82:85], v[88:91], v[242:245], 0
	v_mfma_f32_16x16x32_bf16 v[140:143], v[92:95], v[198:201], v[140:143]
	v_mfma_f32_16x16x32_bf16 v[136:139], v[148:151], v[198:201], v[136:139]
	v_mfma_f32_16x16x32_bf16 v[120:123], v[148:151], v[206:209], v[120:123]
	v_mfma_f32_16x16x32_bf16 v[124:127], v[92:95], v[206:209], v[124:127]
	v_mfma_f32_16x16x32_bf16 v[108:111], v[92:95], v[238:241], v[108:111]
	v_mfma_f32_16x16x32_bf16 v[104:107], v[148:151], v[238:241], v[104:107]
	v_mfma_f32_16x16x32_bf16 v[76:79], v[148:151], v[246:249], v[76:79]
	v_mfma_f32_16x16x32_bf16 v[82:85], v[92:95], v[246:249], v[82:85]
	v_mfma_f32_16x16x32_bf16 v[132:135], v[152:155], v[186:189], 0
	v_mfma_f32_16x16x32_bf16 v[128:131], v[178:181], v[186:189], 0
	v_mfma_f32_16x16x32_bf16 v[112:115], v[178:181], v[202:205], 0
	v_mfma_f32_16x16x32_bf16 v[116:119], v[152:155], v[202:205], 0
	v_mfma_f32_16x16x32_bf16 v[100:103], v[152:155], v[234:237], 0
	v_mfma_f32_16x16x32_bf16 v[96:99], v[178:181], v[234:237], 0
	v_mfma_f32_16x16x32_bf16 v[64:67], v[178:181], v[242:245], 0
	v_mfma_f32_16x16x32_bf16 v[68:71], v[152:155], v[242:245], 0
	v_mfma_f32_16x16x32_bf16 v[132:135], v[156:159], v[198:201], v[132:135]
	v_mfma_f32_16x16x32_bf16 v[128:131], v[182:185], v[198:201], v[128:131]
	v_mfma_f32_16x16x32_bf16 v[112:115], v[182:185], v[206:209], v[112:115]
	v_mfma_f32_16x16x32_bf16 v[116:119], v[156:159], v[206:209], v[116:119]
	v_mfma_f32_16x16x32_bf16 v[100:103], v[156:159], v[238:241], v[100:103]
	v_mfma_f32_16x16x32_bf16 v[96:99], v[182:185], v[238:241], v[96:99]
	v_mfma_f32_16x16x32_bf16 v[64:67], v[182:185], v[246:249], v[64:67]
	v_mfma_f32_16x16x32_bf16 v[68:71], v[156:159], v[246:249], v[68:71]
	s_barrier
	s_add_i32 s70, s70, s12
	v_lshl_add_u64 v[190:191], s[64:65], 0, v[164:165]
	s_mov_b32 m0, s70
	ds_read_b128 v[186:189], v230 offset:16384
	ds_read_b128 v[198:201], v230 offset:17408
	ds_read_b128 v[202:205], v230 offset:18432
	ds_read_b128 v[206:209], v230 offset:19456
	ds_read_b128 v[234:237], v230 offset:20480
	ds_read_b128 v[238:241], v230 offset:21504
	ds_read_b128 v[242:245], v230 offset:22528
	ds_read_b128 v[246:249], v230 offset:23552
	global_load_lds_dwordx4 v[190:191], off
	s_add_i32 m0, s70, 0x2000
	s_add_u32 s70, s64, 0x40000
	v_lshl_add_u64 v[250:251], s[64:65], 0, v[168:169]
	s_addc_u32 s71, s65, 0
	s_add_i32 s61, s61, s12
	global_load_lds_dwordx4 v[250:251], off
	v_lshl_add_u64 v[86:87], s[70:71], 0, v[164:165]
	s_mov_b32 m0, s61
	v_lshl_add_u64 v[224:225], s[66:67], 0, v[162:163]
	global_load_lds_dwordx4 v[86:87], off
	v_lshl_add_u64 v[86:87], s[70:71], 0, v[168:169]
	s_add_i32 m0, s61, 0x2000
	v_lshl_add_u64 v[226:227], s[66:67], 0, v[166:167]
	global_load_lds_dwordx4 v[86:87], off
	s_mov_b32 m0, s73
	s_nop 0
	global_load_lds_dwordx4 v[224:225], off
	s_mov_b32 m0, s74
	s_nop 0
	global_load_lds_dwordx4 v[226:227], off
	s_waitcnt vmcnt(8)
	s_waitcnt lgkmcnt(0)
	s_barrier
; #define PG8_STAGE(bufoff, gbase, voff) do { _Pragma("unroll") for (int _i = 0; _i < 2; ++_i) \
;         __builtin_amdgcn_global_load_lds((const unsigned*)((const char*)(gbase) + (voff)[_i]), (LAS unsigned*)(lds + (bufoff) + ldsw + _i * 8192), 16, 0, 0); } while (0)
; #define PG8_LDA(dst, b, h) do { _Pragma("unroll") for (int m = 0; m < 4; ++m) _Pragma("unroll") for (int k = 0; k < 2; ++k) dst[m][k] = *(const LAS bf16x8*)(lds + PG8_SA(b, h) + aoff + m * 2048 + k * 1024); } while (0)
; #define PG8_LDB(dst, b, h) do { _Pragma("unroll") for (int n = 0; n < 2; ++n) _Pragma("unroll") for (int k = 0; k < 2; ++k) dst[n][k] = *(const LAS bf16x8*)(lds + PG8_SB(b, h) + boff + n * 2048 + k * 1024); } while (0)
; #define PG8_MMA(ai, bj, At, Bt) do { __builtin_amdgcn_s_setprio(1); _Pragma("unroll") for (int m = 0; m < 4; ++m) _Pragma("unroll") for (int n = 0; n < 2; ++n) _Pragma("unroll") for (int k = 0; k < 2; ++k) \
;         acc[ai][bj][m][n] = __builtin_amdgcn_mfma_f32_16x16x32_bf16(Bt[n][k], At[m][k], acc[ai][bj][m][n], 0, 0, 0); __builtin_amdgcn_s_setprio(0); } while (0)
; #define PG8_WAIT_V(n) asm volatile("s_waitcnt vmcnt(" #n ")" ::: "memory")
; #define PG8_WAIT_L(n) asm volatile("s_waitcnt lgkmcnt(" #n ")" ::: "memory")
; #define PG8_BAR __builtin_amdgcn_s_barrier()
; #define PG8_SCHED __builtin_amdgcn_sched_barrier(0)
; template <class Epi, class Sched>
; __device__ __forceinline__ void gemm_phase(LAS unsigned char* lds, const Gemm g, const Sched& S, const Epi& E, const int tid) {
;     ...
;             PG8_WAIT_V(8); PG8_WAIT_L(0); PG8_BAR; PG8_MMA(1, 0, At, B0); PG8_MMA(1, 1, At, B1); PG8_BAR; PG8_SCHED;
;             PG8_LDB(B0, 1, 0); PG8_LDB(B1, 1, 1); PG8_SCHED; PG8_LDA(At, 1, 0); PG8_STAGE(PG8_SA(0, 1), a2 + hstep, voffA);
;             PG8_WAIT_V(8); PG8_WAIT_L(0); PG8_BAR; PG8_MMA(0, 0, At, B0); PG8_MMA(0, 1, At, B1); PG8_BAR; PG8_SCHED;
	s_waitcnt lgkmcnt(0)
	v_mfma_f32_16x16x32_bf16 v[60:63], v[88:91], v[186:189], 0
	v_mfma_f32_16x16x32_bf16 v[56:59], v[144:147], v[186:189], 0
	v_mfma_f32_16x16x32_bf16 v[40:43], v[144:147], v[202:205], 0
	v_mfma_f32_16x16x32_bf16 v[44:47], v[88:91], v[202:205], 0
	v_mfma_f32_16x16x32_bf16 v[28:31], v[88:91], v[234:237], 0
	v_mfma_f32_16x16x32_bf16 v[24:27], v[144:147], v[234:237], 0
	v_mfma_f32_16x16x32_bf16 v[8:11], v[144:147], v[242:245], 0
	v_mfma_f32_16x16x32_bf16 v[12:15], v[88:91], v[242:245], 0
	v_mfma_f32_16x16x32_bf16 v[60:63], v[92:95], v[198:201], v[60:63]
	v_mfma_f32_16x16x32_bf16 v[56:59], v[148:151], v[198:201], v[56:59]
	v_mfma_f32_16x16x32_bf16 v[40:43], v[148:151], v[206:209], v[40:43]
	v_mfma_f32_16x16x32_bf16 v[44:47], v[92:95], v[206:209], v[44:47]
	v_mfma_f32_16x16x32_bf16 v[28:31], v[92:95], v[238:241], v[28:31]
	v_mfma_f32_16x16x32_bf16 v[24:27], v[148:151], v[238:241], v[24:27]
	v_mfma_f32_16x16x32_bf16 v[8:11], v[148:151], v[246:249], v[8:11]
	v_mfma_f32_16x16x32_bf16 v[12:15], v[92:95], v[246:249], v[12:15]
	v_mfma_f32_16x16x32_bf16 v[52:55], v[152:155], v[186:189], 0
	v_mfma_f32_16x16x32_bf16 v[48:51], v[178:181], v[186:189], 0
	v_mfma_f32_16x16x32_bf16 v[32:35], v[178:181], v[202:205], 0
	v_mfma_f32_16x16x32_bf16 v[36:39], v[152:155], v[202:205], 0
	v_mfma_f32_16x16x32_bf16 v[20:23], v[152:155], v[234:237], 0
	v_mfma_f32_16x16x32_bf16 v[16:19], v[178:181], v[234:237], 0
	v_mfma_f32_16x16x32_bf16 v[0:3], v[178:181], v[242:245], 0
	v_mfma_f32_16x16x32_bf16 v[4:7], v[152:155], v[242:245], 0
	v_mfma_f32_16x16x32_bf16 v[52:55], v[156:159], v[198:201], v[52:55]
	v_mfma_f32_16x16x32_bf16 v[48:51], v[182:185], v[198:201], v[48:51]
	v_mfma_f32_16x16x32_bf16 v[32:35], v[182:185], v[206:209], v[32:35]
	v_mfma_f32_16x16x32_bf16 v[36:39], v[156:159], v[206:209], v[36:39]
	v_mfma_f32_16x16x32_bf16 v[20:23], v[156:159], v[238:241], v[20:23]
	v_mfma_f32_16x16x32_bf16 v[16:19], v[182:185], v[238:241], v[16:19]
	v_mfma_f32_16x16x32_bf16 v[0:3], v[182:185], v[246:249], v[0:3]
	v_mfma_f32_16x16x32_bf16 v[4:7], v[156:159], v[246:249], v[4:7]
	s_barrier
	s_add_i32 s61, 0, 0x18000
	v_add_u32_e32 v81, s61, v216
	s_add_i32 s70, 0, 0x1c000
	ds_read_b128 v[88:91], v81
	ds_read_b128 v[92:95], v81 offset:1024
	ds_read_b128 v[144:147], v81 offset:2048
	ds_read_b128 v[148:151], v81 offset:3072
	v_add_u32_e32 v81, s70, v216
	ds_read_b128 v[152:155], v81
	ds_read_b128 v[156:159], v81 offset:1024
	ds_read_b128 v[178:181], v81 offset:2048
	ds_read_b128 v[182:185], v81 offset:3072
	s_add_u32 s66, s66, 0x40000
	s_addc_u32 s67, s67, 0
	s_mov_b32 m0, s75
	v_lshl_add_u64 v[86:87], s[66:67], 0, v[162:163]
	ds_read_b128 v[186:189], v230 offset:32768
	ds_read_b128 v[198:201], v230 offset:33792
	ds_read_b128 v[202:205], v230 offset:34816
	ds_read_b128 v[206:209], v230 offset:35840
	ds_read_b128 v[234:237], v230 offset:36864
	ds_read_b128 v[238:241], v230 offset:37888
	ds_read_b128 v[242:245], v230 offset:38912
	ds_read_b128 v[246:249], v230 offset:39936
	global_load_lds_dwordx4 v[86:87], off
	v_lshl_add_u64 v[86:87], s[66:67], 0, v[166:167]
	s_mov_b32 m0, s81
	s_nop 0
	global_load_lds_dwordx4 v[86:87], off
	s_waitcnt vmcnt(8)
	s_waitcnt lgkmcnt(0)
	s_barrier
	s_waitcnt lgkmcnt(0)
	v_mfma_f32_16x16x32_bf16 v[140:143], v[88:91], v[186:189], v[140:143]
	v_mfma_f32_16x16x32_bf16 v[136:139], v[144:147], v[186:189], v[136:139]
	v_mfma_f32_16x16x32_bf16 v[120:123], v[144:147], v[202:205], v[120:123]
	v_mfma_f32_16x16x32_bf16 v[124:127], v[88:91], v[202:205], v[124:127]
	v_mfma_f32_16x16x32_bf16 v[108:111], v[88:91], v[234:237], v[108:111]
	v_mfma_f32_16x16x32_bf16 v[104:107], v[144:147], v[234:237], v[104:107]
	v_mfma_f32_16x16x32_bf16 v[76:79], v[144:147], v[242:245], v[76:79]
	v_mfma_f32_16x16x32_bf16 v[82:85], v[88:91], v[242:245], v[82:85]
	v_mfma_f32_16x16x32_bf16 v[140:143], v[92:95], v[198:201], v[140:143]
	v_mfma_f32_16x16x32_bf16 v[136:139], v[148:151], v[198:201], v[136:139]
	v_mfma_f32_16x16x32_bf16 v[120:123], v[148:151], v[206:209], v[120:123]
	v_mfma_f32_16x16x32_bf16 v[124:127], v[92:95], v[206:209], v[124:127]
	v_mfma_f32_16x16x32_bf16 v[108:111], v[92:95], v[238:241], v[108:111]
	v_mfma_f32_16x16x32_bf16 v[104:107], v[148:151], v[238:241], v[104:107]
	v_mfma_f32_16x16x32_bf16 v[76:79], v[148:151], v[246:249], v[76:79]
	v_mfma_f32_16x16x32_bf16 v[84:87], v[92:95], v[246:249], v[82:85]
	v_mfma_f32_16x16x32_bf16 v[132:135], v[152:155], v[186:189], v[132:135]
	v_mfma_f32_16x16x32_bf16 v[128:131], v[178:181], v[186:189], v[128:131]
	v_mfma_f32_16x16x32_bf16 v[112:115], v[178:181], v[202:205], v[112:115]
	v_mfma_f32_16x16x32_bf16 v[116:119], v[152:155], v[202:205], v[116:119]
	v_mfma_f32_16x16x32_bf16 v[100:103], v[152:155], v[234:237], v[100:103]
	v_mfma_f32_16x16x32_bf16 v[96:99], v[178:181], v[234:237], v[96:99]
	v_mfma_f32_16x16x32_bf16 v[64:67], v[178:181], v[242:245], v[64:67]
	v_mfma_f32_16x16x32_bf16 v[68:71], v[152:155], v[242:245], v[68:71]
	v_mfma_f32_16x16x32_bf16 v[132:135], v[156:159], v[198:201], v[132:135]
	v_mfma_f32_16x16x32_bf16 v[128:131], v[182:185], v[198:201], v[128:131]
	v_mfma_f32_16x16x32_bf16 v[112:115], v[182:185], v[206:209], v[112:115]
	v_mfma_f32_16x16x32_bf16 v[116:119], v[156:159], v[206:209], v[116:119]
	v_mfma_f32_16x16x32_bf16 v[100:103], v[156:159], v[238:241], v[100:103]
	v_mfma_f32_16x16x32_bf16 v[96:99], v[182:185], v[238:241], v[96:99]
	v_mfma_f32_16x16x32_bf16 v[64:67], v[182:185], v[246:249], v[64:67]
	v_mfma_f32_16x16x32_bf16 v[68:71], v[156:159], v[246:249], v[68:71]
	s_barrier
; #define PG8_STAGE(bufoff, gbase, voff) do { _Pragma("unroll") for (int _i = 0; _i < 2; ++_i) \
;         __builtin_amdgcn_global_load_lds((const unsigned*)((const char*)(gbase) + (voff)[_i]), (LAS unsigned*)(lds + (bufoff) + ldsw + _i * 8192), 16, 0, 0); } while (0)
; #define PG8_LDA(dst, b, h) do { _Pragma("unroll") for (int m = 0; m < 4; ++m) _Pragma("unroll") for (int k = 0; k < 2; ++k) dst[m][k] = *(const LAS bf16x8*)(lds + PG8_SA(b, h) + aoff + m * 2048 + k * 1024); } while (0)
; #define PG8_LDB(dst, b, h) do { _Pragma("unroll") for (int n = 0; n < 2; ++n) _Pragma("unroll") for (int k = 0; k < 2; ++k) dst[n][k] = *(const LAS bf16x8*)(lds + PG8_SB(b, h) + boff + n * 2048 + k * 1024); } while (0)
; #define PG8_WAIT_V(n) asm volatile("s_waitcnt vmcnt(" #n ")" ::: "memory")
; #define PG8_WAIT_L(n) asm volatile("s_waitcnt lgkmcnt(" #n ")" ::: "memory")
; template <class Epi, class Sched>
; __device__ __forceinline__ void gemm_phase(LAS unsigned char* lds, const Gemm g, const Sched& S, const Epi& E, const int tid) {
;     ...
;             const bool last = (t == nt - 2);
;             const char* a1 = cA + (size_t)(t + 1) * kstep;
;             const char* a2 = last ? nA : cA + (size_t)(t + 2) * kstep; const char* b2 = last ? nB : cB + (size_t)(t + 2) * kstep;
;             const char* a3 = a2 + kstep; const char* b3 = b2 + kstep;
;             PG8_LDB(B0, 0, 0); PG8_LDB(B1, 0, 1); PG8_SCHED; PG8_LDA(At, 0, 0); PG8_STAGE(PG8_SA(1, 1), a1 + hstep, voffA);
;             PG8_WAIT_V(8); PG8_WAIT_L(0); PG8_BAR; PG8_MMA(0, 0, At, B0); PG8_MMA(0, 1, At, B1); PG8_BAR; PG8_SCHED;
;             PG8_LDA(At, 0, 1); PG8_STAGE(PG8_SB(0, 0), b2, voffB); PG8_STAGE(PG8_SB(0, 1), b2 + hstep, voffB); PG8_STAGE(PG8_SA(0, 0), a2, voffA);
;             PG8_WAIT_V(8); PG8_WAIT_L(0); PG8_BAR; PG8_MMA(1, 0, At, B0); PG8_MMA(1, 1, At, B1); PG8_BAR; PG8_SCHED;
;             PG8_LDB(B0, 1, 0); PG8_LDB(B1, 1, 1); PG8_SCHED; PG8_LDA(At, 1, 0); PG8_STAGE(PG8_SA(0, 1), a2 + hstep, voffA);
;             PG8_WAIT_V(8); PG8_WAIT_L(0); PG8_BAR; PG8_MMA(0, 0, At, B0); PG8_MMA(0, 1, At, B1); PG8_BAR; PG8_SCHED;
;             PG8_LDA(At, 1, 1); PG8_STAGE(PG8_SB(1, 0), b3, voffB); PG8_STAGE(PG8_SB(1, 1), b3 + hstep, voffB); PG8_STAGE(PG8_SA(1, 0), a3, voffA);
;             PG8_WAIT_V(8); PG8_WAIT_L(0); PG8_BAR; PG8_MMA(1, 0, At, B0); PG8_MMA(1, 1, At, B1); PG8_BAR; PG8_SCHED;
	s_add_i32 s61, s61, s12
	v_lshl_add_u64 v[82:83], v[190:191], 0, s[68:69]
	s_mov_b32 m0, s61
	ds_read_b128 v[186:189], v230 offset:49152
	ds_read_b128 v[198:201], v230 offset:50176
	ds_read_b128 v[202:205], v230 offset:51200
	ds_read_b128 v[206:209], v230 offset:52224
	ds_read_b128 v[234:237], v230 offset:53248
	ds_read_b128 v[238:241], v230 offset:54272
	ds_read_b128 v[242:245], v230 offset:55296
	ds_read_b128 v[246:249], v230 offset:56320
	global_load_lds_dwordx4 v[82:83], off
	s_add_i32 m0, s61, 0x2000
	s_add_u32 s64, s64, 0x40080
	v_lshl_add_u64 v[82:83], v[250:251], 0, s[68:69]
	s_addc_u32 s65, s65, 0
	s_add_i32 s61, s70, s12
	global_load_lds_dwordx4 v[82:83], off
	v_lshl_add_u64 v[82:83], s[64:65], 0, v[164:165]
	s_mov_b32 m0, s61
	s_nop 0
	global_load_lds_dwordx4 v[82:83], off
	v_lshl_add_u64 v[82:83], s[64:65], 0, v[168:169]
	s_add_i32 m0, s61, 0x2000
	s_nop 0
	global_load_lds_dwordx4 v[82:83], off
	v_lshl_add_u64 v[82:83], v[224:225], 0, s[68:69]
	s_mov_b32 m0, s82
	s_nop 0
	global_load_lds_dwordx4 v[82:83], off
	v_lshl_add_u64 v[82:83], v[226:227], 0, s[68:69]
	s_mov_b32 m0, s83
	s_nop 0
	global_load_lds_dwordx4 v[82:83], off
	s_waitcnt vmcnt(8)
	s_waitcnt lgkmcnt(0)
	s_barrier
	s_waitcnt lgkmcnt(0)
	v_mfma_f32_16x16x32_bf16 v[60:63], v[88:91], v[186:189], v[60:63]
	v_mfma_f32_16x16x32_bf16 v[56:59], v[144:147], v[186:189], v[56:59]
	v_mfma_f32_16x16x32_bf16 v[40:43], v[144:147], v[202:205], v[40:43]
	v_mfma_f32_16x16x32_bf16 v[44:47], v[88:91], v[202:205], v[44:47]
	v_mfma_f32_16x16x32_bf16 v[28:31], v[88:91], v[234:237], v[28:31]
	v_mfma_f32_16x16x32_bf16 v[24:27], v[144:147], v[234:237], v[24:27]
	v_mfma_f32_16x16x32_bf16 v[8:11], v[144:147], v[242:245], v[8:11]
	v_mfma_f32_16x16x32_bf16 v[12:15], v[88:91], v[242:245], v[12:15]
	v_mfma_f32_16x16x32_bf16 v[60:63], v[92:95], v[198:201], v[60:63]
	v_mfma_f32_16x16x32_bf16 v[56:59], v[148:151], v[198:201], v[56:59]
	v_mfma_f32_16x16x32_bf16 v[40:43], v[148:151], v[206:209], v[40:43]
	v_mfma_f32_16x16x32_bf16 v[44:47], v[92:95], v[206:209], v[44:47]
	v_mfma_f32_16x16x32_bf16 v[28:31], v[92:95], v[238:241], v[28:31]
	v_mfma_f32_16x16x32_bf16 v[24:27], v[148:151], v[238:241], v[24:27]
	v_mfma_f32_16x16x32_bf16 v[8:11], v[148:151], v[246:249], v[8:11]
	v_mfma_f32_16x16x32_bf16 v[12:15], v[92:95], v[246:249], v[12:15]
	v_mfma_f32_16x16x32_bf16 v[52:55], v[152:155], v[186:189], v[52:55]
	v_mfma_f32_16x16x32_bf16 v[48:51], v[178:181], v[186:189], v[48:51]
	v_mfma_f32_16x16x32_bf16 v[32:35], v[178:181], v[202:205], v[32:35]
	v_mfma_f32_16x16x32_bf16 v[36:39], v[152:155], v[202:205], v[36:39]
	v_mfma_f32_16x16x32_bf16 v[20:23], v[152:155], v[234:237], v[20:23]
	v_mfma_f32_16x16x32_bf16 v[16:19], v[178:181], v[234:237], v[16:19]
	v_mfma_f32_16x16x32_bf16 v[0:3], v[178:181], v[242:245], v[0:3]
	v_mfma_f32_16x16x32_bf16 v[4:7], v[152:155], v[242:245], v[4:7]
	v_mfma_f32_16x16x32_bf16 v[52:55], v[156:159], v[198:201], v[52:55]
	v_mfma_f32_16x16x32_bf16 v[48:51], v[182:185], v[198:201], v[48:51]
	v_mfma_f32_16x16x32_bf16 v[32:35], v[182:185], v[206:209], v[32:35]
	v_mfma_f32_16x16x32_bf16 v[36:39], v[156:159], v[206:209], v[36:39]
	v_mfma_f32_16x16x32_bf16 v[20:23], v[156:159], v[238:241], v[20:23]
	v_mfma_f32_16x16x32_bf16 v[16:19], v[182:185], v[238:241], v[16:19]
	v_mfma_f32_16x16x32_bf16 v[0:3], v[182:185], v[246:249], v[0:3]
	v_mfma_f32_16x16x32_bf16 v[4:7], v[156:159], v[246:249], v[4:7]
	s_barrier
	s_add_i32 s60, s60, 2
	s_add_u32 s6, s6, 0x100
	s_addc_u32 s7, s7, 0
	s_add_u32 s58, s58, 0x100
	s_addc_u32 s59, s59, 0
	s_cmp_gt_u32 s60, 13
.LBB0_266:
	s_add_u32 s61, s6, 0xfffc0080
	s_addc_u32 s64, s7, -1
	s_add_i32 s70, 0, 0x10000
	s_cmp_eq_u32 s60, 12
	s_cselect_b32 s67, s23, s64
	s_cselect_b32 s66, s56, s61
	v_add_u32_e32 v81, s70, v216
	s_cselect_b32 s65, s55, s59
	s_cselect_b32 s64, s57, s58
	s_add_i32 s61, 0, 0x14000
	ds_read_b128 v[88:91], v81
	ds_read_b128 v[92:95], v81 offset:1024
	ds_read_b128 v[144:147], v81 offset:2048
	ds_read_b128 v[148:151], v81 offset:3072
	v_add_u32_e32 v81, s61, v216
	ds_read_b128 v[152:155], v81
	ds_read_b128 v[156:159], v81 offset:1024
	ds_read_b128 v[178:181], v81 offset:2048
	ds_read_b128 v[182:185], v81 offset:3072
	v_lshl_add_u64 v[82:83], s[6:7], 0, v[174:175]
	s_add_i32 m0, s73, 0xc000
	ds_read_b128 v[186:189], v230
	ds_read_b128 v[198:201], v230 offset:1024
	ds_read_b128 v[202:205], v230 offset:2048
	ds_read_b128 v[206:209], v230 offset:3072
	ds_read_b128 v[234:237], v230 offset:4096
	ds_read_b128 v[238:241], v230 offset:5120
	ds_read_b128 v[242:245], v230 offset:6144
	ds_read_b128 v[246:249], v230 offset:7168
	global_load_lds_dwordx4 v[82:83], off
	v_lshl_add_u64 v[82:83], s[6:7], 0, v[176:177]
	s_add_i32 m0, s73, 0xe000
	s_nop 0
	global_load_lds_dwordx4 v[82:83], off
	s_waitcnt vmcnt(8)
	s_waitcnt lgkmcnt(0)
	s_barrier
; #define PG8_STAGE(bufoff, gbase, voff) do { _Pragma("unroll") for (int _i = 0; _i < 2; ++_i) \
;         __builtin_amdgcn_global_load_lds((const unsigned*)((const char*)(gbase) + (voff)[_i]), (LAS unsigned*)(lds + (bufoff) + ldsw + _i * 8192), 16, 0, 0); } while (0)
; #define PG8_LDA(dst, b, h) do { _Pragma("unroll") for (int m = 0; m < 4; ++m) _Pragma("unroll") for (int k = 0; k < 2; ++k) dst[m][k] = *(const LAS bf16x8*)(lds + PG8_SA(b, h) + aoff + m * 2048 + k * 1024); } while (0)
; #define PG8_MMA(ai, bj, At, Bt) do { __builtin_amdgcn_s_setprio(1); _Pragma("unroll") for (int m = 0; m < 4; ++m) _Pragma("unroll") for (int n = 0; n < 2; ++n) _Pragma("unroll") for (int k = 0; k < 2; ++k) \
;         acc[ai][bj][m][n] = __builtin_amdgcn_mfma_f32_16x16x32_bf16(Bt[n][k], At[m][k], acc[ai][bj][m][n], 0, 0, 0); __builtin_amdgcn_s_setprio(0); } while (0)
; #define PG8_WAIT_V(n) asm volatile("s_waitcnt vmcnt(" #n ")" ::: "memory")
; #define PG8_WAIT_L(n) asm volatile("s_waitcnt lgkmcnt(" #n ")" ::: "memory")
; #define PG8_BAR __builtin_amdgcn_s_barrier()
; #define PG8_SCHED __builtin_amdgcn_sched_barrier(0)
; template <class Epi, class Sched>
; __device__ __forceinline__ void gemm_phase(LAS unsigned char* lds, const Gemm g, const Sched& S, const Epi& E, const int tid) {
;     ...
;             PG8_WAIT_V(8); PG8_WAIT_L(0); PG8_BAR; PG8_MMA(0, 0, At, B0); PG8_MMA(0, 1, At, B1); PG8_BAR; PG8_SCHED;
;             PG8_LDA(At, 0, 1); PG8_STAGE(PG8_SB(0, 0), b2, voffB); PG8_STAGE(PG8_SB(0, 1), b2 + hstep, voffB); PG8_STAGE(PG8_SA(0, 0), a2, voffA);
;             PG8_WAIT_V(8); PG8_WAIT_L(0); PG8_BAR; PG8_MMA(1, 0, At, B0); PG8_MMA(1, 1, At, B1); PG8_BAR; PG8_SCHED;
	s_waitcnt lgkmcnt(0)
	v_mfma_f32_16x16x32_bf16 v[140:143], v[88:91], v[186:189], v[140:143]
	v_mfma_f32_16x16x32_bf16 v[136:139], v[144:147], v[186:189], v[136:139]
	v_mfma_f32_16x16x32_bf16 v[120:123], v[144:147], v[202:205], v[120:123]
	v_mfma_f32_16x16x32_bf16 v[124:127], v[88:91], v[202:205], v[124:127]
	v_mfma_f32_16x16x32_bf16 v[108:111], v[88:91], v[234:237], v[108:111]
	v_mfma_f32_16x16x32_bf16 v[104:107], v[144:147], v[234:237], v[104:107]
	v_mfma_f32_16x16x32_bf16 v[76:79], v[144:147], v[242:245], v[76:79]
	v_mfma_f32_16x16x32_bf16 v[82:85], v[88:91], v[242:245], v[84:87]
	v_mfma_f32_16x16x32_bf16 v[140:143], v[92:95], v[198:201], v[140:143]
	v_mfma_f32_16x16x32_bf16 v[136:139], v[148:151], v[198:201], v[136:139]
	v_mfma_f32_16x16x32_bf16 v[120:123], v[148:151], v[206:209], v[120:123]
	v_mfma_f32_16x16x32_bf16 v[124:127], v[92:95], v[206:209], v[124:127]
	v_mfma_f32_16x16x32_bf16 v[108:111], v[92:95], v[238:241], v[108:111]
	v_mfma_f32_16x16x32_bf16 v[104:107], v[148:151], v[238:241], v[104:107]
	v_mfma_f32_16x16x32_bf16 v[76:79], v[148:151], v[246:249], v[76:79]
	v_mfma_f32_16x16x32_bf16 v[82:85], v[92:95], v[246:249], v[82:85]
	v_mfma_f32_16x16x32_bf16 v[132:135], v[152:155], v[186:189], v[132:135]
	v_mfma_f32_16x16x32_bf16 v[128:131], v[178:181], v[186:189], v[128:131]
	v_mfma_f32_16x16x32_bf16 v[112:115], v[178:181], v[202:205], v[112:115]
	v_mfma_f32_16x16x32_bf16 v[116:119], v[152:155], v[202:205], v[116:119]
	v_mfma_f32_16x16x32_bf16 v[100:103], v[152:155], v[234:237], v[100:103]
	v_mfma_f32_16x16x32_bf16 v[96:99], v[178:181], v[234:237], v[96:99]
	v_mfma_f32_16x16x32_bf16 v[64:67], v[178:181], v[242:245], v[64:67]
	v_mfma_f32_16x16x32_bf16 v[68:71], v[152:155], v[242:245], v[68:71]
	v_mfma_f32_16x16x32_bf16 v[132:135], v[156:159], v[198:201], v[132:135]
	v_mfma_f32_16x16x32_bf16 v[128:131], v[182:185], v[198:201], v[128:131]
	v_mfma_f32_16x16x32_bf16 v[112:115], v[182:185], v[206:209], v[112:115]
	v_mfma_f32_16x16x32_bf16 v[116:119], v[156:159], v[206:209], v[116:119]
	v_mfma_f32_16x16x32_bf16 v[100:103], v[156:159], v[238:241], v[100:103]
	v_mfma_f32_16x16x32_bf16 v[96:99], v[182:185], v[238:241], v[96:99]
	v_mfma_f32_16x16x32_bf16 v[64:67], v[182:185], v[246:249], v[64:67]
	v_mfma_f32_16x16x32_bf16 v[68:71], v[156:159], v[246:249], v[68:71]
	s_barrier
	s_add_i32 s70, s70, s12
	v_lshl_add_u64 v[190:191], s[64:65], 0, v[164:165]
	s_mov_b32 m0, s70
	ds_read_b128 v[186:189], v230 offset:16384
	ds_read_b128 v[198:201], v230 offset:17408
	ds_read_b128 v[202:205], v230 offset:18432
	ds_read_b128 v[206:209], v230 offset:19456
	ds_read_b128 v[234:237], v230 offset:20480
	ds_read_b128 v[238:241], v230 offset:21504
	ds_read_b128 v[242:245], v230 offset:22528
	ds_read_b128 v[246:249], v230 offset:23552
	global_load_lds_dwordx4 v[190:191], off
	s_add_i32 m0, s70, 0x2000
	s_add_u32 s70, s64, 0x40000
	v_lshl_add_u64 v[250:251], s[64:65], 0, v[168:169]
	s_addc_u32 s71, s65, 0
	s_add_i32 s61, s61, s12
	global_load_lds_dwordx4 v[250:251], off
	v_lshl_add_u64 v[86:87], s[70:71], 0, v[164:165]
	s_mov_b32 m0, s61
	v_lshl_add_u64 v[224:225], s[66:67], 0, v[162:163]
	global_load_lds_dwordx4 v[86:87], off
	v_lshl_add_u64 v[86:87], s[70:71], 0, v[168:169]
	s_add_i32 m0, s61, 0x2000
	v_lshl_add_u64 v[226:227], s[66:67], 0, v[166:167]
	global_load_lds_dwordx4 v[86:87], off
	s_mov_b32 m0, s73
	s_nop 0
	global_load_lds_dwordx4 v[224:225], off
	s_mov_b32 m0, s74
	s_nop 0
	global_load_lds_dwordx4 v[226:227], off
	s_waitcnt vmcnt(8)
	s_waitcnt lgkmcnt(0)
	s_barrier
	s_waitcnt lgkmcnt(0)
	v_mfma_f32_16x16x32_bf16 v[60:63], v[88:91], v[186:189], v[60:63]
	v_mfma_f32_16x16x32_bf16 v[56:59], v[144:147], v[186:189], v[56:59]
	v_mfma_f32_16x16x32_bf16 v[40:43], v[144:147], v[202:205], v[40:43]
	v_mfma_f32_16x16x32_bf16 v[44:47], v[88:91], v[202:205], v[44:47]
	v_mfma_f32_16x16x32_bf16 v[28:31], v[88:91], v[234:237], v[28:31]
	v_mfma_f32_16x16x32_bf16 v[24:27], v[144:147], v[234:237], v[24:27]
	v_mfma_f32_16x16x32_bf16 v[8:11], v[144:147], v[242:245], v[8:11]
	v_mfma_f32_16x16x32_bf16 v[12:15], v[88:91], v[242:245], v[12:15]
	v_mfma_f32_16x16x32_bf16 v[60:63], v[92:95], v[198:201], v[60:63]
	v_mfma_f32_16x16x32_bf16 v[56:59], v[148:151], v[198:201], v[56:59]
	v_mfma_f32_16x16x32_bf16 v[40:43], v[148:151], v[206:209], v[40:43]
	v_mfma_f32_16x16x32_bf16 v[44:47], v[92:95], v[206:209], v[44:47]
	v_mfma_f32_16x16x32_bf16 v[28:31], v[92:95], v[238:241], v[28:31]
	v_mfma_f32_16x16x32_bf16 v[24:27], v[148:151], v[238:241], v[24:27]
	v_mfma_f32_16x16x32_bf16 v[8:11], v[148:151], v[246:249], v[8:11]
	v_mfma_f32_16x16x32_bf16 v[12:15], v[92:95], v[246:249], v[12:15]
	v_mfma_f32_16x16x32_bf16 v[52:55], v[152:155], v[186:189], v[52:55]
	v_mfma_f32_16x16x32_bf16 v[48:51], v[178:181], v[186:189], v[48:51]
	v_mfma_f32_16x16x32_bf16 v[32:35], v[178:181], v[202:205], v[32:35]
	v_mfma_f32_16x16x32_bf16 v[36:39], v[152:155], v[202:205], v[36:39]
	v_mfma_f32_16x16x32_bf16 v[20:23], v[152:155], v[234:237], v[20:23]
	v_mfma_f32_16x16x32_bf16 v[16:19], v[178:181], v[234:237], v[16:19]
	v_mfma_f32_16x16x32_bf16 v[0:3], v[178:181], v[242:245], v[0:3]
	v_mfma_f32_16x16x32_bf16 v[4:7], v[152:155], v[242:245], v[4:7]
	v_mfma_f32_16x16x32_bf16 v[52:55], v[156:159], v[198:201], v[52:55]
	v_mfma_f32_16x16x32_bf16 v[48:51], v[182:185], v[198:201], v[48:51]
	v_mfma_f32_16x16x32_bf16 v[32:35], v[182:185], v[206:209], v[32:35]
	v_mfma_f32_16x16x32_bf16 v[36:39], v[156:159], v[206:209], v[36:39]
	v_mfma_f32_16x16x32_bf16 v[20:23], v[156:159], v[238:241], v[20:23]
	v_mfma_f32_16x16x32_bf16 v[16:19], v[182:185], v[238:241], v[16:19]
	v_mfma_f32_16x16x32_bf16 v[0:3], v[182:185], v[246:249], v[0:3]
	v_mfma_f32_16x16x32_bf16 v[4:7], v[156:159], v[246:249], v[4:7]
	s_barrier
; #define PG8_STAGE(bufoff, gbase, voff) do { _Pragma("unroll") for (int _i = 0; _i < 2; ++_i) \
;         __builtin_amdgcn_global_load_lds((const unsigned*)((const char*)(gbase) + (voff)[_i]), (LAS unsigned*)(lds + (bufoff) + ldsw + _i * 8192), 16, 0, 0); } while (0)
; #define PG8_LDA(dst, b, h) do { _Pragma("unroll") for (int m = 0; m < 4; ++m) _Pragma("unroll") for (int k = 0; k < 2; ++k) dst[m][k] = *(const LAS bf16x8*)(lds + PG8_SA(b, h) + aoff + m * 2048 + k * 1024); } while (0)
; #define PG8_LDB(dst, b, h) do { _Pragma("unroll") for (int n = 0; n < 2; ++n) _Pragma("unroll") for (int k = 0; k < 2; ++k) dst[n][k] = *(const LAS bf16x8*)(lds + PG8_SB(b, h) + boff + n * 2048 + k * 1024); } while (0)
; #define PG8_MMA(ai, bj, At, Bt) do { __builtin_amdgcn_s_setprio(1); _Pragma("unroll") for (int m = 0; m < 4; ++m) _Pragma("unroll") for (int n = 0; n < 2; ++n) _Pragma("unroll") for (int k = 0; k < 2; ++k) \
;         acc[ai][bj][m][n] = __builtin_amdgcn_mfma_f32_16x16x32_bf16(Bt[n][k], At[m][k], acc[ai][bj][m][n], 0, 0, 0); __builtin_amdgcn_s_setprio(0); } while (0)
; #define PG8_WAIT_V(n) asm volatile("s_waitcnt vmcnt(" #n ")" ::: "memory")
; #define PG8_WAIT_L(n) asm volatile("s_waitcnt lgkmcnt(" #n ")" ::: "memory")
; #define PG8_BAR __builtin_amdgcn_s_barrier()
; #define PG8_SCHED __builtin_amdgcn_sched_barrier(0)
; template <class Epi, class Sched>
; __device__ __forceinline__ void gemm_phase(LAS unsigned char* lds, const Gemm g, const Sched& S, const Epi& E, const int tid) {
;     ...
;             PG8_LDB(B0, 1, 0); PG8_LDB(B1, 1, 1); PG8_SCHED; PG8_LDA(At, 1, 0); PG8_STAGE(PG8_SA(0, 1), a2 + hstep, voffA);
;             PG8_WAIT_V(8); PG8_WAIT_L(0); PG8_BAR; PG8_MMA(0, 0, At, B0); PG8_MMA(0, 1, At, B1); PG8_BAR; PG8_SCHED;
	s_add_i32 s61, 0, 0x18000
	v_add_u32_e32 v81, s61, v216
	s_add_i32 s70, 0, 0x1c000
	ds_read_b128 v[88:91], v81
	ds_read_b128 v[92:95], v81 offset:1024
	ds_read_b128 v[144:147], v81 offset:2048
	ds_read_b128 v[148:151], v81 offset:3072
	v_add_u32_e32 v81, s70, v216
	ds_read_b128 v[152:155], v81
	ds_read_b128 v[156:159], v81 offset:1024
	ds_read_b128 v[178:181], v81 offset:2048
	ds_read_b128 v[182:185], v81 offset:3072
	s_add_u32 s66, s66, 0x40000
	s_addc_u32 s67, s67, 0
	s_mov_b32 m0, s75
	v_lshl_add_u64 v[86:87], s[66:67], 0, v[162:163]
	ds_read_b128 v[186:189], v230 offset:32768
	ds_read_b128 v[198:201], v230 offset:33792
	ds_read_b128 v[202:205], v230 offset:34816
	ds_read_b128 v[206:209], v230 offset:35840
	ds_read_b128 v[234:237], v230 offset:36864
	ds_read_b128 v[238:241], v230 offset:37888
	ds_read_b128 v[242:245], v230 offset:38912
	ds_read_b128 v[246:249], v230 offset:39936
	global_load_lds_dwordx4 v[86:87], off
	v_lshl_add_u64 v[86:87], s[66:67], 0, v[166:167]
	s_mov_b32 m0, s81
	s_nop 0
	global_load_lds_dwordx4 v[86:87], off
	s_waitcnt vmcnt(8)
	s_waitcnt lgkmcnt(0)
	s_barrier
	s_waitcnt lgkmcnt(0)
	v_mfma_f32_16x16x32_bf16 v[140:143], v[88:91], v[186:189], v[140:143]
	v_mfma_f32_16x16x32_bf16 v[136:139], v[144:147], v[186:189], v[136:139]
	v_mfma_f32_16x16x32_bf16 v[120:123], v[144:147], v[202:205], v[120:123]
	v_mfma_f32_16x16x32_bf16 v[124:127], v[88:91], v[202:205], v[124:127]
	v_mfma_f32_16x16x32_bf16 v[108:111], v[88:91], v[234:237], v[108:111]
	v_mfma_f32_16x16x32_bf16 v[104:107], v[144:147], v[234:237], v[104:107]
	v_mfma_f32_16x16x32_bf16 v[76:79], v[144:147], v[242:245], v[76:79]
	v_mfma_f32_16x16x32_bf16 v[82:85], v[88:91], v[242:245], v[82:85]
	v_mfma_f32_16x16x32_bf16 v[140:143], v[92:95], v[198:201], v[140:143]
	v_mfma_f32_16x16x32_bf16 v[136:139], v[148:151], v[198:201], v[136:139]
	v_mfma_f32_16x16x32_bf16 v[120:123], v[148:151], v[206:209], v[120:123]
	v_mfma_f32_16x16x32_bf16 v[124:127], v[92:95], v[206:209], v[124:127]
	v_mfma_f32_16x16x32_bf16 v[108:111], v[92:95], v[238:241], v[108:111]
	v_mfma_f32_16x16x32_bf16 v[104:107], v[148:151], v[238:241], v[104:107]
	v_mfma_f32_16x16x32_bf16 v[76:79], v[148:151], v[246:249], v[76:79]
	v_mfma_f32_16x16x32_bf16 v[84:87], v[92:95], v[246:249], v[82:85]
	v_mfma_f32_16x16x32_bf16 v[132:135], v[152:155], v[186:189], v[132:135]
	v_mfma_f32_16x16x32_bf16 v[128:131], v[178:181], v[186:189], v[128:131]
	v_mfma_f32_16x16x32_bf16 v[112:115], v[178:181], v[202:205], v[112:115]
	v_mfma_f32_16x16x32_bf16 v[116:119], v[152:155], v[202:205], v[116:119]
	v_mfma_f32_16x16x32_bf16 v[100:103], v[152:155], v[234:237], v[100:103]
	v_mfma_f32_16x16x32_bf16 v[96:99], v[178:181], v[234:237], v[96:99]
	v_mfma_f32_16x16x32_bf16 v[64:67], v[178:181], v[242:245], v[64:67]
	v_mfma_f32_16x16x32_bf16 v[68:71], v[152:155], v[242:245], v[68:71]
	v_mfma_f32_16x16x32_bf16 v[132:135], v[156:159], v[198:201], v[132:135]
	v_mfma_f32_16x16x32_bf16 v[128:131], v[182:185], v[198:201], v[128:131]
	v_mfma_f32_16x16x32_bf16 v[112:115], v[182:185], v[206:209], v[112:115]
	v_mfma_f32_16x16x32_bf16 v[116:119], v[156:159], v[206:209], v[116:119]
	v_mfma_f32_16x16x32_bf16 v[100:103], v[156:159], v[238:241], v[100:103]
	v_mfma_f32_16x16x32_bf16 v[96:99], v[182:185], v[238:241], v[96:99]
	v_mfma_f32_16x16x32_bf16 v[64:67], v[182:185], v[246:249], v[64:67]
	v_mfma_f32_16x16x32_bf16 v[68:71], v[156:159], v[246:249], v[68:71]
	s_barrier
; #define PG8_STAGE(bufoff, gbase, voff) do { _Pragma("unroll") for (int _i = 0; _i < 2; ++_i) \
;         __builtin_amdgcn_global_load_lds((const unsigned*)((const char*)(gbase) + (voff)[_i]), (LAS unsigned*)(lds + (bufoff) + ldsw + _i * 8192), 16, 0, 0); } while (0)
; #define PG8_LDA(dst, b, h) do { _Pragma("unroll") for (int m = 0; m < 4; ++m) _Pragma("unroll") for (int k = 0; k < 2; ++k) dst[m][k] = *(const LAS bf16x8*)(lds + PG8_SA(b, h) + aoff + m * 2048 + k * 1024); } while (0)
; #define PG8_MMA(ai, bj, At, Bt) do { __builtin_amdgcn_s_setprio(1); _Pragma("unroll") for (int m = 0; m < 4; ++m) _Pragma("unroll") for (int n = 0; n < 2; ++n) _Pragma("unroll") for (int k = 0; k < 2; ++k) \
;         acc[ai][bj][m][n] = __builtin_amdgcn_mfma_f32_16x16x32_bf16(Bt[n][k], At[m][k], acc[ai][bj][m][n], 0, 0, 0); __builtin_amdgcn_s_setprio(0); } while (0)
; #define PG8_WAIT_V(n) asm volatile("s_waitcnt vmcnt(" #n ")" ::: "memory")
; #define PG8_WAIT_L(n) asm volatile("s_waitcnt lgkmcnt(" #n ")" ::: "memory")
; #define PG8_BAR __builtin_amdgcn_s_barrier()
; #define PG8_SCHED __builtin_amdgcn_sched_barrier(0)
; template <class Epi, class Sched>
; __device__ __forceinline__ void gemm_phase(LAS unsigned char* lds, const Gemm g, const Sched& S, const Epi& E, const int tid) {
;     ...
;             PG8_LDA(At, 1, 1); PG8_STAGE(PG8_SB(1, 0), b3, voffB); PG8_STAGE(PG8_SB(1, 1), b3 + hstep, voffB); PG8_STAGE(PG8_SA(1, 0), a3, voffA);
;             PG8_WAIT_V(8); PG8_WAIT_L(0); PG8_BAR; PG8_MMA(1, 0, At, B0); PG8_MMA(1, 1, At, B1); PG8_BAR; PG8_SCHED;
;         }
;         if (wr == 0) PG8_BAR;
	s_add_i32 s61, s61, s12
	v_lshl_add_u64 v[82:83], v[190:191], 0, s[68:69]
	s_mov_b32 m0, s61
	ds_read_b128 v[186:189], v230 offset:49152
	ds_read_b128 v[198:201], v230 offset:50176
	ds_read_b128 v[202:205], v230 offset:51200
	ds_read_b128 v[206:209], v230 offset:52224
	ds_read_b128 v[234:237], v230 offset:53248
	ds_read_b128 v[238:241], v230 offset:54272
	ds_read_b128 v[242:245], v230 offset:55296
	ds_read_b128 v[246:249], v230 offset:56320
	global_load_lds_dwordx4 v[82:83], off
	s_add_i32 m0, s61, 0x2000
	s_add_u32 s64, s64, 0x40080
	v_lshl_add_u64 v[82:83], v[250:251], 0, s[68:69]
	s_addc_u32 s65, s65, 0
	s_add_i32 s61, s70, s12
	global_load_lds_dwordx4 v[82:83], off
	v_lshl_add_u64 v[82:83], s[64:65], 0, v[164:165]
	s_mov_b32 m0, s61
	s_nop 0
	global_load_lds_dwordx4 v[82:83], off
	v_lshl_add_u64 v[82:83], s[64:65], 0, v[168:169]
	s_add_i32 m0, s61, 0x2000
	s_nop 0
	global_load_lds_dwordx4 v[82:83], off
	v_lshl_add_u64 v[82:83], v[224:225], 0, s[68:69]
	s_mov_b32 m0, s82
	s_nop 0
	global_load_lds_dwordx4 v[82:83], off
	v_lshl_add_u64 v[82:83], v[226:227], 0, s[68:69]
	s_mov_b32 m0, s83
	s_nop 0
	global_load_lds_dwordx4 v[82:83], off
	s_waitcnt vmcnt(8)
	s_waitcnt lgkmcnt(0)
	s_barrier
	s_waitcnt lgkmcnt(0)
	v_mfma_f32_16x16x32_bf16 v[60:63], v[88:91], v[186:189], v[60:63]
	v_mfma_f32_16x16x32_bf16 v[56:59], v[144:147], v[186:189], v[56:59]
	v_mfma_f32_16x16x32_bf16 v[40:43], v[144:147], v[202:205], v[40:43]
	v_mfma_f32_16x16x32_bf16 v[44:47], v[88:91], v[202:205], v[44:47]
	v_mfma_f32_16x16x32_bf16 v[28:31], v[88:91], v[234:237], v[28:31]
	v_mfma_f32_16x16x32_bf16 v[24:27], v[144:147], v[234:237], v[24:27]
	v_mfma_f32_16x16x32_bf16 v[8:11], v[144:147], v[242:245], v[8:11]
	v_mfma_f32_16x16x32_bf16 v[12:15], v[88:91], v[242:245], v[12:15]
	v_mfma_f32_16x16x32_bf16 v[60:63], v[92:95], v[198:201], v[60:63]
	v_mfma_f32_16x16x32_bf16 v[56:59], v[148:151], v[198:201], v[56:59]
	v_mfma_f32_16x16x32_bf16 v[40:43], v[148:151], v[206:209], v[40:43]
	v_mfma_f32_16x16x32_bf16 v[44:47], v[92:95], v[206:209], v[44:47]
	v_mfma_f32_16x16x32_bf16 v[28:31], v[92:95], v[238:241], v[28:31]
	v_mfma_f32_16x16x32_bf16 v[24:27], v[148:151], v[238:241], v[24:27]
	v_mfma_f32_16x16x32_bf16 v[8:11], v[148:151], v[246:249], v[8:11]
	v_mfma_f32_16x16x32_bf16 v[12:15], v[92:95], v[246:249], v[12:15]
	v_mfma_f32_16x16x32_bf16 v[52:55], v[152:155], v[186:189], v[52:55]
	v_mfma_f32_16x16x32_bf16 v[48:51], v[178:181], v[186:189], v[48:51]
	v_mfma_f32_16x16x32_bf16 v[32:35], v[178:181], v[202:205], v[32:35]
	v_mfma_f32_16x16x32_bf16 v[36:39], v[152:155], v[202:205], v[36:39]
	v_mfma_f32_16x16x32_bf16 v[20:23], v[152:155], v[234:237], v[20:23]
	v_mfma_f32_16x16x32_bf16 v[16:19], v[178:181], v[234:237], v[16:19]
	v_mfma_f32_16x16x32_bf16 v[0:3], v[178:181], v[242:245], v[0:3]
	v_mfma_f32_16x16x32_bf16 v[4:7], v[152:155], v[242:245], v[4:7]
	v_mfma_f32_16x16x32_bf16 v[52:55], v[156:159], v[198:201], v[52:55]
	v_mfma_f32_16x16x32_bf16 v[48:51], v[182:185], v[198:201], v[48:51]
	v_mfma_f32_16x16x32_bf16 v[32:35], v[182:185], v[206:209], v[32:35]
	v_mfma_f32_16x16x32_bf16 v[36:39], v[156:159], v[206:209], v[36:39]
	v_mfma_f32_16x16x32_bf16 v[20:23], v[156:159], v[238:241], v[20:23]
	v_mfma_f32_16x16x32_bf16 v[16:19], v[182:185], v[238:241], v[16:19]
	v_mfma_f32_16x16x32_bf16 v[0:3], v[182:185], v[246:249], v[0:3]
	v_mfma_f32_16x16x32_bf16 v[4:7], v[156:159], v[246:249], v[4:7]
	s_barrier
	s_add_i32 s60, s60, 2
	s_add_u32 s6, s6, 0x100
	s_addc_u32 s7, s7, 0
	s_add_u32 s58, s58, 0x100
	s_addc_u32 s59, s59, 0
	s_cmp_gt_u32 s60, 13
	s_cbranch_scc0 .LBB0_266
	s_and_b64 vcc, exec, s[50:51]
	s_cbranch_vccz .LBB0_269
	s_barrier

;     __device__ __forceinline__ Pre prefetch(const Unit& u, int tid) const { return prenorm_load(stats, u.pn * BM, sW + (size_t)(u.pn >> 4) * SW_ROWS + u.pm * BM, tid); }
;     __device__ __forceinline__ Pre prefetch(const Unit& u, int tid) const { return prenorm_load(stats, u.pm * BM, sW + (size_t)(u.pm >> 4) * SW_ROWS + u.pn * BM, tid); }
;     __device__ __forceinline__ Pre prefetch(const Unit& u, int tid) const { return prenorm_load(stats, u.pm * BM, sW + (size_t)(u.pm >> 4) * SW_ROWS + u.pn * BM, tid); }
; #define PG8_STAGE(bufoff, gbase, voff) do { _Pragma("unroll") for (int _i = 0; _i < 2; ++_i) \
;         __builtin_amdgcn_global_load_lds((const unsigned*)((const char*)(gbase) + (voff)[_i]), (LAS unsigned*)(lds + (bufoff) + ldsw + _i * 8192), 16, 0, 0); } while (0)
; #define PG8_LDA(dst, b, h) do { _Pragma("unroll") for (int m = 0; m < 4; ++m) _Pragma("unroll") for (int k = 0; k < 2; ++k) dst[m][k] = *(const LAS bf16x8*)(lds + PG8_SA(b, h) + aoff + m * 2048 + k * 1024); } while (0)
; #define PG8_WAIT_V(n) asm volatile("s_waitcnt vmcnt(" #n ")" ::: "memory")
; template <class Epi, class Sched>
; __device__ __forceinline__ void gemm_phase(LAS unsigned char* lds, const Gemm g, const Sched& S, const Epi& E, const int tid) {
;     ...
;         const bool has_next = S.next(ui + 1, nxt);
;         const char* nA = has_next ? (const char*)g.A + (size_t)nxt.pm * tstep : cA; const char* nB = has_next ? (const char*)g.Bt + (size_t)nxt.pn * tstep : cB;
;         const typename Epi::Pre pre = E.prefetch(cur, tid);
;         for (int t = 0; t < nt; t += 2) {
;             const bool last = (t == nt - 2);
;             const char* a1 = cA + (size_t)(t + 1) * kstep;
;             const char* a2 = last ? nA : cA + (size_t)(t + 2) * kstep; const char* b2 = last ? nB : cB + (size_t)(t + 2) * kstep;
;             const char* a3 = a2 + kstep; const char* b3 = b2 + kstep;
;             PG8_LDB(B0, 0, 0); PG8_LDB(B1, 0, 1); PG8_SCHED; PG8_LDA(At, 0, 0); PG8_STAGE(PG8_SA(1, 1), a1 + hstep, voffA);
;             PG8_WAIT_V(8); PG8_WAIT_L(0); PG8_BAR; PG8_MMA(0, 0, At, B0); PG8_MMA(0, 1, At, B1); PG8_BAR; PG8_SCHED;
;             PG8_LDA(At, 0, 1); PG8_STAGE(PG8_SB(0, 0), b2, voffB); PG8_STAGE(PG8_SB(0, 1), b2 + hstep, voffB); PG8_STAGE(PG8_SA(0, 0), a2, voffA);
;             PG8_WAIT_V(8); PG8_WAIT_L(0); PG8_BAR; PG8_MMA(1, 0, At, B0); PG8_MMA(1, 1, At, B1); PG8_BAR; PG8_SCHED;
.LBB0_325:
	s_or_b64 exec, exec, s[50:51]
	s_ashr_i32 s39, s38, 31
	s_lshl_b64 s[50:51], s[38:39], 19
	s_add_u32 s50, s85, s50
	s_addc_u32 s51, s86, s51
	s_and_b64 s[54:55], s[4:5], exec
	s_cselect_b32 s39, s51, s63
	s_cselect_b32 s74, s50, s62
	s_ashr_i32 s23, s22, 31
	s_lshl_b64 s[54:55], s[22:23], 19
	s_add_u32 s54, s46, s54
	s_addc_u32 s55, s47, s55
	s_and_b64 s[66:67], s[4:5], exec
	s_cselect_b32 s23, s55, s65
	s_cselect_b32 s75, s54, s64
	s_add_u32 s62, s62, 0x40080
	s_addc_u32 s63, s63, 0
	s_add_u32 s78, s64, 0x100
	s_addc_u32 s79, s65, 0
	s_mov_b32 s81, -2
	s_waitcnt lgkmcnt(0)
	s_add_u32 s64, s62, 0xfffc0080
	s_addc_u32 s65, s63, -1
	s_add_i32 s82, 0, 0x10000
	s_cmp_eq_u32 s81, 12
	s_cselect_b32 s67, s39, s65
	s_cselect_b32 s66, s74, s64
	v_add_u32_e32 v69, s82, v154
	s_cselect_b32 s65, s23, s79
	s_cselect_b32 s64, s75, s78
	s_add_i32 s90, 0, 0x14000
	ds_read_b128 v[70:73], v69
	ds_read_b128 v[74:77], v69 offset:1024
	ds_read_b128 v[172:175], v69 offset:2048
	ds_read_b128 v[176:179], v69 offset:3072
	v_add_u32_e32 v69, s90, v154
	ds_read_b128 v[180:183], v69
	ds_read_b128 v[184:187], v69 offset:1024
	ds_read_b128 v[188:191], v69 offset:2048
	ds_read_b128 v[198:201], v69 offset:3072
	v_lshl_add_u64 v[78:79], s[62:63], 0, v[144:145]
	s_add_i32 m0, s53, 0xc000
	ds_read_b128 v[202:205], v171
	ds_read_b128 v[206:209], v171 offset:1024
	ds_read_b128 v[210:213], v171 offset:2048
	ds_read_b128 v[214:217], v171 offset:3072
	ds_read_b128 v[218:221], v171 offset:4096
	ds_read_b128 v[230:233], v171 offset:5120
	ds_read_b128 v[234:237], v171 offset:6144
	ds_read_b128 v[238:241], v171 offset:7168
	global_load_lds_dwordx4 v[78:79], off
	v_lshl_add_u64 v[78:79], s[62:63], 0, v[146:147]
	s_add_i32 m0, s53, 0xe000
	s_nop 0
	global_load_lds_dwordx4 v[78:79], off
	s_waitcnt vmcnt(8)
	s_waitcnt lgkmcnt(0)
	s_barrier
	s_waitcnt lgkmcnt(0)
	v_mfma_f32_16x16x32_bf16 v[140:143], v[70:73], v[202:205], 0
	v_mfma_f32_16x16x32_bf16 v[136:139], v[172:175], v[202:205], 0
	v_mfma_f32_16x16x32_bf16 v[128:131], v[172:175], v[210:213], 0
	v_mfma_f32_16x16x32_bf16 v[132:135], v[70:73], v[210:213], 0
	v_mfma_f32_16x16x32_bf16 v[116:119], v[70:73], v[218:221], 0
	v_mfma_f32_16x16x32_bf16 v[112:115], v[172:175], v[218:221], 0
	v_mfma_f32_16x16x32_bf16 v[96:99], v[172:175], v[234:237], 0
	v_mfma_f32_16x16x32_bf16 v[100:103], v[70:73], v[234:237], 0
	v_mfma_f32_16x16x32_bf16 v[140:143], v[74:77], v[206:209], v[140:143]
	v_mfma_f32_16x16x32_bf16 v[136:139], v[176:179], v[206:209], v[136:139]
	v_mfma_f32_16x16x32_bf16 v[128:131], v[176:179], v[214:217], v[128:131]
	v_mfma_f32_16x16x32_bf16 v[132:135], v[74:77], v[214:217], v[132:135]
	v_mfma_f32_16x16x32_bf16 v[116:119], v[74:77], v[230:233], v[116:119]
	v_mfma_f32_16x16x32_bf16 v[112:115], v[176:179], v[230:233], v[112:115]
	v_mfma_f32_16x16x32_bf16 v[96:99], v[176:179], v[238:241], v[96:99]
	v_mfma_f32_16x16x32_bf16 v[100:103], v[74:77], v[238:241], v[100:103]
	v_mfma_f32_16x16x32_bf16 v[124:127], v[180:183], v[202:205], 0
	v_mfma_f32_16x16x32_bf16 v[120:123], v[188:191], v[202:205], 0
	v_mfma_f32_16x16x32_bf16 v[104:107], v[188:191], v[210:213], 0
	v_mfma_f32_16x16x32_bf16 v[108:111], v[180:183], v[210:213], 0
	v_mfma_f32_16x16x32_bf16 v[92:95], v[180:183], v[218:221], 0
	v_mfma_f32_16x16x32_bf16 v[88:91], v[188:191], v[218:221], 0
	v_mfma_f32_16x16x32_bf16 v[78:81], v[188:191], v[234:237], 0
	v_mfma_f32_16x16x32_bf16 v[84:87], v[180:183], v[234:237], 0
	v_mfma_f32_16x16x32_bf16 v[124:127], v[184:187], v[206:209], v[124:127]
	v_mfma_f32_16x16x32_bf16 v[120:123], v[198:201], v[206:209], v[120:123]
	v_mfma_f32_16x16x32_bf16 v[104:107], v[198:201], v[214:217], v[104:107]
	v_mfma_f32_16x16x32_bf16 v[108:111], v[184:187], v[214:217], v[108:111]
	v_mfma_f32_16x16x32_bf16 v[92:95], v[184:187], v[230:233], v[92:95]
	v_mfma_f32_16x16x32_bf16 v[88:91], v[198:201], v[230:233], v[88:91]
	v_mfma_f32_16x16x32_bf16 v[78:81], v[198:201], v[238:241], v[78:81]
	v_mfma_f32_16x16x32_bf16 v[84:87], v[184:187], v[238:241], v[84:87]
	s_barrier
	s_add_i32 s82, s82, s52
	v_lshl_add_u64 v[224:225], s[64:65], 0, v[164:165]
	s_mov_b32 m0, s82
	ds_read_b128 v[202:205], v171 offset:16384
	ds_read_b128 v[206:209], v171 offset:17408
	ds_read_b128 v[210:213], v171 offset:18432
	ds_read_b128 v[214:217], v171 offset:19456
	ds_read_b128 v[218:221], v171 offset:20480
	ds_read_b128 v[230:233], v171 offset:21504
	ds_read_b128 v[234:237], v171 offset:22528
	ds_read_b128 v[238:241], v171 offset:23552
	global_load_lds_dwordx4 v[224:225], off
	s_add_i32 m0, s82, 0x2000
	s_add_u32 s82, s64, 0x40000
	v_lshl_add_u64 v[226:227], s[64:65], 0, v[168:169]
	s_addc_u32 s83, s65, 0
	s_add_i32 s90, s90, s52
	global_load_lds_dwordx4 v[226:227], off
	v_lshl_add_u64 v[82:83], s[82:83], 0, v[164:165]
	s_mov_b32 m0, s90
	v_lshl_add_u64 v[242:243], s[66:67], 0, v[162:163]
	global_load_lds_dwordx4 v[82:83], off
	v_lshl_add_u64 v[82:83], s[82:83], 0, v[168:169]
	s_add_i32 m0, s90, 0x2000
	v_lshl_add_u64 v[244:245], s[66:67], 0, v[166:167]
	global_load_lds_dwordx4 v[82:83], off
	s_mov_b32 m0, s53
	s_nop 0
	global_load_lds_dwordx4 v[242:243], off
	s_mov_b32 m0, s56
	s_nop 0
	global_load_lds_dwordx4 v[244:245], off
	s_waitcnt vmcnt(8)
	s_waitcnt lgkmcnt(0)
	s_barrier
; #define PG8_STAGE(bufoff, gbase, voff) do { _Pragma("unroll") for (int _i = 0; _i < 2; ++_i) \
;         __builtin_amdgcn_global_load_lds((const unsigned*)((const char*)(gbase) + (voff)[_i]), (LAS unsigned*)(lds + (bufoff) + ldsw + _i * 8192), 16, 0, 0); } while (0)
; #define PG8_LDA(dst, b, h) do { _Pragma("unroll") for (int m = 0; m < 4; ++m) _Pragma("unroll") for (int k = 0; k < 2; ++k) dst[m][k] = *(const LAS bf16x8*)(lds + PG8_SA(b, h) + aoff + m * 2048 + k * 1024); } while (0)
; #define PG8_LDB(dst, b, h) do { _Pragma("unroll") for (int n = 0; n < 2; ++n) _Pragma("unroll") for (int k = 0; k < 2; ++k) dst[n][k] = *(const LAS bf16x8*)(lds + PG8_SB(b, h) + boff + n * 2048 + k * 1024); } while (0)
; #define PG8_MMA(ai, bj, At, Bt) do { __builtin_amdgcn_s_setprio(1); _Pragma("unroll") for (int m = 0; m < 4; ++m) _Pragma("unroll") for (int n = 0; n < 2; ++n) _Pragma("unroll") for (int k = 0; k < 2; ++k) \
;         acc[ai][bj][m][n] = __builtin_amdgcn_mfma_f32_16x16x32_bf16(Bt[n][k], At[m][k], acc[ai][bj][m][n], 0, 0, 0); __builtin_amdgcn_s_setprio(0); } while (0)
; #define PG8_WAIT_V(n) asm volatile("s_waitcnt vmcnt(" #n ")" ::: "memory")
; #define PG8_WAIT_L(n) asm volatile("s_waitcnt lgkmcnt(" #n ")" ::: "memory")
; #define PG8_BAR __builtin_amdgcn_s_barrier()
; #define PG8_SCHED __builtin_amdgcn_sched_barrier(0)
; template <class Epi, class Sched>
; __device__ __forceinline__ void gemm_phase(LAS unsigned char* lds, const Gemm g, const Sched& S, const Epi& E, const int tid) {
;     ...
;             PG8_WAIT_V(8); PG8_WAIT_L(0); PG8_BAR; PG8_MMA(1, 0, At, B0); PG8_MMA(1, 1, At, B1); PG8_BAR; PG8_SCHED;
;             PG8_LDB(B0, 1, 0); PG8_LDB(B1, 1, 1); PG8_SCHED; PG8_LDA(At, 1, 0); PG8_STAGE(PG8_SA(0, 1), a2 + hstep, voffA);
;             PG8_WAIT_V(8); PG8_WAIT_L(0); PG8_BAR; PG8_MMA(0, 0, At, B0); PG8_MMA(0, 1, At, B1); PG8_BAR; PG8_SCHED;
	s_waitcnt lgkmcnt(0)
	v_mfma_f32_16x16x32_bf16 v[60:63], v[70:73], v[202:205], 0
	v_mfma_f32_16x16x32_bf16 v[56:59], v[172:175], v[202:205], 0
	v_mfma_f32_16x16x32_bf16 v[44:47], v[172:175], v[210:213], 0
	v_mfma_f32_16x16x32_bf16 v[52:55], v[70:73], v[210:213], 0
	v_mfma_f32_16x16x32_bf16 v[28:31], v[70:73], v[218:221], 0
	v_mfma_f32_16x16x32_bf16 v[24:27], v[172:175], v[218:221], 0
	v_mfma_f32_16x16x32_bf16 v[8:11], v[172:175], v[234:237], 0
	v_mfma_f32_16x16x32_bf16 v[16:19], v[70:73], v[234:237], 0
	v_mfma_f32_16x16x32_bf16 v[60:63], v[74:77], v[206:209], v[60:63]
	v_mfma_f32_16x16x32_bf16 v[56:59], v[176:179], v[206:209], v[56:59]
	v_mfma_f32_16x16x32_bf16 v[44:47], v[176:179], v[214:217], v[44:47]
	v_mfma_f32_16x16x32_bf16 v[52:55], v[74:77], v[214:217], v[52:55]
	v_mfma_f32_16x16x32_bf16 v[28:31], v[74:77], v[230:233], v[28:31]
	v_mfma_f32_16x16x32_bf16 v[24:27], v[176:179], v[230:233], v[24:27]
	v_mfma_f32_16x16x32_bf16 v[8:11], v[176:179], v[238:241], v[8:11]
	v_mfma_f32_16x16x32_bf16 v[16:19], v[74:77], v[238:241], v[16:19]
	v_mfma_f32_16x16x32_bf16 v[48:51], v[180:183], v[202:205], 0
	v_mfma_f32_16x16x32_bf16 v[40:43], v[188:191], v[202:205], 0
	v_mfma_f32_16x16x32_bf16 v[32:35], v[188:191], v[210:213], 0
	v_mfma_f32_16x16x32_bf16 v[36:39], v[180:183], v[210:213], 0
	v_mfma_f32_16x16x32_bf16 v[20:23], v[180:183], v[218:221], 0
	v_mfma_f32_16x16x32_bf16 v[12:15], v[188:191], v[218:221], 0
	v_mfma_f32_16x16x32_bf16 v[0:3], v[188:191], v[234:237], 0
	v_mfma_f32_16x16x32_bf16 v[4:7], v[180:183], v[234:237], 0
	v_mfma_f32_16x16x32_bf16 v[48:51], v[184:187], v[206:209], v[48:51]
	v_mfma_f32_16x16x32_bf16 v[40:43], v[198:201], v[206:209], v[40:43]
	v_mfma_f32_16x16x32_bf16 v[32:35], v[198:201], v[214:217], v[32:35]
	v_mfma_f32_16x16x32_bf16 v[36:39], v[184:187], v[214:217], v[36:39]
	v_mfma_f32_16x16x32_bf16 v[20:23], v[184:187], v[230:233], v[20:23]
	v_mfma_f32_16x16x32_bf16 v[12:15], v[198:201], v[230:233], v[12:15]
	v_mfma_f32_16x16x32_bf16 v[0:3], v[198:201], v[238:241], v[0:3]
	v_mfma_f32_16x16x32_bf16 v[4:7], v[184:187], v[238:241], v[4:7]
	s_barrier
	s_add_i32 s82, 0, 0x18000
	v_add_u32_e32 v69, s82, v154
	s_add_i32 s83, 0, 0x1c000
	ds_read_b128 v[70:73], v69
	ds_read_b128 v[74:77], v69 offset:1024
	ds_read_b128 v[172:175], v69 offset:2048
	ds_read_b128 v[176:179], v69 offset:3072
	v_add_u32_e32 v69, s83, v154
	ds_read_b128 v[180:183], v69
	ds_read_b128 v[184:187], v69 offset:1024
	ds_read_b128 v[188:191], v69 offset:2048
	ds_read_b128 v[198:201], v69 offset:3072
	s_add_u32 s66, s66, 0x40000
	s_addc_u32 s67, s67, 0
	s_mov_b32 m0, s57
	v_lshl_add_u64 v[82:83], s[66:67], 0, v[162:163]
	ds_read_b128 v[202:205], v171 offset:32768
	ds_read_b128 v[206:209], v171 offset:33792
	ds_read_b128 v[210:213], v171 offset:34816
	ds_read_b128 v[214:217], v171 offset:35840
	ds_read_b128 v[218:221], v171 offset:36864
	ds_read_b128 v[230:233], v171 offset:37888
	ds_read_b128 v[234:237], v171 offset:38912
	ds_read_b128 v[238:241], v171 offset:39936
	global_load_lds_dwordx4 v[82:83], off
	v_lshl_add_u64 v[82:83], s[66:67], 0, v[166:167]
	s_mov_b32 m0, s58
	s_nop 0
	global_load_lds_dwordx4 v[82:83], off
	s_waitcnt vmcnt(8)
	s_waitcnt lgkmcnt(0)
	s_barrier
	s_waitcnt lgkmcnt(0)
	v_mfma_f32_16x16x32_bf16 v[140:143], v[70:73], v[202:205], v[140:143]
	v_mfma_f32_16x16x32_bf16 v[136:139], v[172:175], v[202:205], v[136:139]
	v_mfma_f32_16x16x32_bf16 v[128:131], v[172:175], v[210:213], v[128:131]
	v_mfma_f32_16x16x32_bf16 v[132:135], v[70:73], v[210:213], v[132:135]
	v_mfma_f32_16x16x32_bf16 v[116:119], v[70:73], v[218:221], v[116:119]
	v_mfma_f32_16x16x32_bf16 v[112:115], v[172:175], v[218:221], v[112:115]
	v_mfma_f32_16x16x32_bf16 v[96:99], v[172:175], v[234:237], v[96:99]
	v_mfma_f32_16x16x32_bf16 v[100:103], v[70:73], v[234:237], v[100:103]
	v_mfma_f32_16x16x32_bf16 v[140:143], v[74:77], v[206:209], v[140:143]
	v_mfma_f32_16x16x32_bf16 v[136:139], v[176:179], v[206:209], v[136:139]
	v_mfma_f32_16x16x32_bf16 v[128:131], v[176:179], v[214:217], v[128:131]
	v_mfma_f32_16x16x32_bf16 v[132:135], v[74:77], v[214:217], v[132:135]
	v_mfma_f32_16x16x32_bf16 v[116:119], v[74:77], v[230:233], v[116:119]
	v_mfma_f32_16x16x32_bf16 v[112:115], v[176:179], v[230:233], v[112:115]
	v_mfma_f32_16x16x32_bf16 v[96:99], v[176:179], v[238:241], v[96:99]
	v_mfma_f32_16x16x32_bf16 v[100:103], v[74:77], v[238:241], v[100:103]
	v_mfma_f32_16x16x32_bf16 v[124:127], v[180:183], v[202:205], v[124:127]
	v_mfma_f32_16x16x32_bf16 v[120:123], v[188:191], v[202:205], v[120:123]
	v_mfma_f32_16x16x32_bf16 v[104:107], v[188:191], v[210:213], v[104:107]
	v_mfma_f32_16x16x32_bf16 v[108:111], v[180:183], v[210:213], v[108:111]
	v_mfma_f32_16x16x32_bf16 v[92:95], v[180:183], v[218:221], v[92:95]
	v_mfma_f32_16x16x32_bf16 v[88:91], v[188:191], v[218:221], v[88:91]
	v_mfma_f32_16x16x32_bf16 v[78:81], v[188:191], v[234:237], v[78:81]
	v_mfma_f32_16x16x32_bf16 v[82:85], v[180:183], v[234:237], v[84:87]
	v_mfma_f32_16x16x32_bf16 v[124:127], v[184:187], v[206:209], v[124:127]
	v_mfma_f32_16x16x32_bf16 v[120:123], v[198:201], v[206:209], v[120:123]
	v_mfma_f32_16x16x32_bf16 v[104:107], v[198:201], v[214:217], v[104:107]
	v_mfma_f32_16x16x32_bf16 v[108:111], v[184:187], v[214:217], v[108:111]
	v_mfma_f32_16x16x32_bf16 v[92:95], v[184:187], v[230:233], v[92:95]
	v_mfma_f32_16x16x32_bf16 v[88:91], v[198:201], v[230:233], v[88:91]
	v_mfma_f32_16x16x32_bf16 v[80:83], v[198:201], v[238:241], v[78:81]
	v_mfma_f32_16x16x32_bf16 v[84:87], v[184:187], v[238:241], v[82:85]
	s_barrier
; #define PG8_STAGE(bufoff, gbase, voff) do { _Pragma("unroll") for (int _i = 0; _i < 2; ++_i) \
;         __builtin_amdgcn_global_load_lds((const unsigned*)((const char*)(gbase) + (voff)[_i]), (LAS unsigned*)(lds + (bufoff) + ldsw + _i * 8192), 16, 0, 0); } while (0)
; #define PG8_LDA(dst, b, h) do { _Pragma("unroll") for (int m = 0; m < 4; ++m) _Pragma("unroll") for (int k = 0; k < 2; ++k) dst[m][k] = *(const LAS bf16x8*)(lds + PG8_SA(b, h) + aoff + m * 2048 + k * 1024); } while (0)
; #define PG8_LDB(dst, b, h) do { _Pragma("unroll") for (int n = 0; n < 2; ++n) _Pragma("unroll") for (int k = 0; k < 2; ++k) dst[n][k] = *(const LAS bf16x8*)(lds + PG8_SB(b, h) + boff + n * 2048 + k * 1024); } while (0)
; #define PG8_WAIT_V(n) asm volatile("s_waitcnt vmcnt(" #n ")" ::: "memory")
; #define PG8_WAIT_L(n) asm volatile("s_waitcnt lgkmcnt(" #n ")" ::: "memory")
; template <class Epi, class Sched>
; __device__ __forceinline__ void gemm_phase(LAS unsigned char* lds, const Gemm g, const Sched& S, const Epi& E, const int tid) {
;     ...
;             const bool last = (t == nt - 2);
;             const char* a1 = cA + (size_t)(t + 1) * kstep;
;             const char* a2 = last ? nA : cA + (size_t)(t + 2) * kstep; const char* b2 = last ? nB : cB + (size_t)(t + 2) * kstep;
;             const char* a3 = a2 + kstep; const char* b3 = b2 + kstep;
;             PG8_LDB(B0, 0, 0); PG8_LDB(B1, 0, 1); PG8_SCHED; PG8_LDA(At, 0, 0); PG8_STAGE(PG8_SA(1, 1), a1 + hstep, voffA);
;             PG8_WAIT_V(8); PG8_WAIT_L(0); PG8_BAR; PG8_MMA(0, 0, At, B0); PG8_MMA(0, 1, At, B1); PG8_BAR; PG8_SCHED;
;             PG8_LDA(At, 0, 1); PG8_STAGE(PG8_SB(0, 0), b2, voffB); PG8_STAGE(PG8_SB(0, 1), b2 + hstep, voffB); PG8_STAGE(PG8_SA(0, 0), a2, voffA);
;             PG8_WAIT_V(8); PG8_WAIT_L(0); PG8_BAR; PG8_MMA(1, 0, At, B0); PG8_MMA(1, 1, At, B1); PG8_BAR; PG8_SCHED;
;             PG8_LDB(B0, 1, 0); PG8_LDB(B1, 1, 1); PG8_SCHED; PG8_LDA(At, 1, 0); PG8_STAGE(PG8_SA(0, 1), a2 + hstep, voffA);
;             PG8_WAIT_V(8); PG8_WAIT_L(0); PG8_BAR; PG8_MMA(0, 0, At, B0); PG8_MMA(0, 1, At, B1); PG8_BAR; PG8_SCHED;
;             PG8_LDA(At, 1, 1); PG8_STAGE(PG8_SB(1, 0), b3, voffB); PG8_STAGE(PG8_SB(1, 1), b3 + hstep, voffB); PG8_STAGE(PG8_SA(1, 0), a3, voffA);
;             PG8_WAIT_V(8); PG8_WAIT_L(0); PG8_BAR; PG8_MMA(1, 0, At, B0); PG8_MMA(1, 1, At, B1); PG8_BAR; PG8_SCHED;
	s_add_i32 s66, s82, s52
	v_lshl_add_u64 v[78:79], v[224:225], 0, s[68:69]
	s_mov_b32 m0, s66
	ds_read_b128 v[202:205], v171 offset:49152
	ds_read_b128 v[206:209], v171 offset:50176
	ds_read_b128 v[210:213], v171 offset:51200
	ds_read_b128 v[214:217], v171 offset:52224
	ds_read_b128 v[218:221], v171 offset:53248
	ds_read_b128 v[230:233], v171 offset:54272
	ds_read_b128 v[234:237], v171 offset:55296
	ds_read_b128 v[238:241], v171 offset:56320
	global_load_lds_dwordx4 v[78:79], off
	s_add_i32 m0, s66, 0x2000
	s_add_u32 s64, s64, 0x40080
	v_lshl_add_u64 v[78:79], v[226:227], 0, s[68:69]
	s_addc_u32 s65, s65, 0
	s_add_i32 s66, s83, s52
	global_load_lds_dwordx4 v[78:79], off
	v_lshl_add_u64 v[78:79], s[64:65], 0, v[164:165]
	s_mov_b32 m0, s66
	s_nop 0
	global_load_lds_dwordx4 v[78:79], off
	v_lshl_add_u64 v[78:79], s[64:65], 0, v[168:169]
	s_add_i32 m0, s66, 0x2000
	s_nop 0
	global_load_lds_dwordx4 v[78:79], off
	v_lshl_add_u64 v[78:79], v[242:243], 0, s[68:69]
	s_mov_b32 m0, s61
	s_nop 0
	global_load_lds_dwordx4 v[78:79], off
	v_lshl_add_u64 v[78:79], v[244:245], 0, s[68:69]
	s_mov_b32 m0, s70
	s_nop 0
	global_load_lds_dwordx4 v[78:79], off
	s_waitcnt vmcnt(8)
	s_waitcnt lgkmcnt(0)
	s_barrier
	s_waitcnt lgkmcnt(0)
	v_mfma_f32_16x16x32_bf16 v[60:63], v[70:73], v[202:205], v[60:63]
	v_mfma_f32_16x16x32_bf16 v[56:59], v[172:175], v[202:205], v[56:59]
	v_mfma_f32_16x16x32_bf16 v[44:47], v[172:175], v[210:213], v[44:47]
	v_mfma_f32_16x16x32_bf16 v[52:55], v[70:73], v[210:213], v[52:55]
	v_mfma_f32_16x16x32_bf16 v[28:31], v[70:73], v[218:221], v[28:31]
	v_mfma_f32_16x16x32_bf16 v[24:27], v[172:175], v[218:221], v[24:27]
	v_mfma_f32_16x16x32_bf16 v[8:11], v[172:175], v[234:237], v[8:11]
	v_mfma_f32_16x16x32_bf16 v[16:19], v[70:73], v[234:237], v[16:19]
	v_mfma_f32_16x16x32_bf16 v[60:63], v[74:77], v[206:209], v[60:63]
	v_mfma_f32_16x16x32_bf16 v[56:59], v[176:179], v[206:209], v[56:59]
	v_mfma_f32_16x16x32_bf16 v[44:47], v[176:179], v[214:217], v[44:47]
	v_mfma_f32_16x16x32_bf16 v[52:55], v[74:77], v[214:217], v[52:55]
	v_mfma_f32_16x16x32_bf16 v[28:31], v[74:77], v[230:233], v[28:31]
	v_mfma_f32_16x16x32_bf16 v[24:27], v[176:179], v[230:233], v[24:27]
	v_mfma_f32_16x16x32_bf16 v[8:11], v[176:179], v[238:241], v[8:11]
	v_mfma_f32_16x16x32_bf16 v[16:19], v[74:77], v[238:241], v[16:19]
	v_mfma_f32_16x16x32_bf16 v[48:51], v[180:183], v[202:205], v[48:51]
	v_mfma_f32_16x16x32_bf16 v[40:43], v[188:191], v[202:205], v[40:43]
	v_mfma_f32_16x16x32_bf16 v[32:35], v[188:191], v[210:213], v[32:35]
	v_mfma_f32_16x16x32_bf16 v[36:39], v[180:183], v[210:213], v[36:39]
	v_mfma_f32_16x16x32_bf16 v[20:23], v[180:183], v[218:221], v[20:23]
	v_mfma_f32_16x16x32_bf16 v[12:15], v[188:191], v[218:221], v[12:15]
	v_mfma_f32_16x16x32_bf16 v[0:3], v[188:191], v[234:237], v[0:3]
	v_mfma_f32_16x16x32_bf16 v[4:7], v[180:183], v[234:237], v[4:7]
	v_mfma_f32_16x16x32_bf16 v[48:51], v[184:187], v[206:209], v[48:51]
	v_mfma_f32_16x16x32_bf16 v[40:43], v[198:201], v[206:209], v[40:43]
	v_mfma_f32_16x16x32_bf16 v[32:35], v[198:201], v[214:217], v[32:35]
	v_mfma_f32_16x16x32_bf16 v[36:39], v[184:187], v[214:217], v[36:39]
	v_mfma_f32_16x16x32_bf16 v[20:23], v[184:187], v[230:233], v[20:23]
	v_mfma_f32_16x16x32_bf16 v[12:15], v[198:201], v[230:233], v[12:15]
	v_mfma_f32_16x16x32_bf16 v[0:3], v[198:201], v[238:241], v[0:3]
	v_mfma_f32_16x16x32_bf16 v[4:7], v[184:187], v[238:241], v[4:7]
	s_barrier
	s_add_i32 s81, s81, 2
	s_add_u32 s62, s62, 0x100
	s_addc_u32 s63, s63, 0
	s_add_u32 s78, s78, 0x100
	s_addc_u32 s79, s79, 0
	s_cmp_gt_u32 s81, 13
.LBB0_326:
	s_add_u32 s64, s62, 0xfffc0080
	s_addc_u32 s65, s63, -1
	s_add_i32 s82, 0, 0x10000
	s_cmp_eq_u32 s81, 12
	s_cselect_b32 s67, s39, s65
	s_cselect_b32 s66, s74, s64
	v_add_u32_e32 v69, s82, v154
	s_cselect_b32 s65, s23, s79
	s_cselect_b32 s64, s75, s78
	s_add_i32 s90, 0, 0x14000
	ds_read_b128 v[70:73], v69
	ds_read_b128 v[74:77], v69 offset:1024
	ds_read_b128 v[172:175], v69 offset:2048
	ds_read_b128 v[176:179], v69 offset:3072
	v_add_u32_e32 v69, s90, v154
	ds_read_b128 v[180:183], v69
	ds_read_b128 v[184:187], v69 offset:1024
	ds_read_b128 v[188:191], v69 offset:2048
	ds_read_b128 v[198:201], v69 offset:3072
	v_lshl_add_u64 v[78:79], s[62:63], 0, v[144:145]
	s_add_i32 m0, s53, 0xc000
	ds_read_b128 v[202:205], v171
	ds_read_b128 v[206:209], v171 offset:1024
	ds_read_b128 v[210:213], v171 offset:2048
	ds_read_b128 v[214:217], v171 offset:3072
	ds_read_b128 v[218:221], v171 offset:4096
	ds_read_b128 v[230:233], v171 offset:5120
	ds_read_b128 v[234:237], v171 offset:6144
	ds_read_b128 v[238:241], v171 offset:7168
	global_load_lds_dwordx4 v[78:79], off
	v_lshl_add_u64 v[78:79], s[62:63], 0, v[146:147]
	s_add_i32 m0, s53, 0xe000
	s_nop 0
	global_load_lds_dwordx4 v[78:79], off
	s_waitcnt vmcnt(8)
	s_waitcnt lgkmcnt(0)
	s_barrier
; #define PG8_STAGE(bufoff, gbase, voff) do { _Pragma("unroll") for (int _i = 0; _i < 2; ++_i) \
;         __builtin_amdgcn_global_load_lds((const unsigned*)((const char*)(gbase) + (voff)[_i]), (LAS unsigned*)(lds + (bufoff) + ldsw + _i * 8192), 16, 0, 0); } while (0)
; #define PG8_LDA(dst, b, h) do { _Pragma("unroll") for (int m = 0; m < 4; ++m) _Pragma("unroll") for (int k = 0; k < 2; ++k) dst[m][k] = *(const LAS bf16x8*)(lds + PG8_SA(b, h) + aoff + m * 2048 + k * 1024); } while (0)
; #define PG8_MMA(ai, bj, At, Bt) do { __builtin_amdgcn_s_setprio(1); _Pragma("unroll") for (int m = 0; m < 4; ++m) _Pragma("unroll") for (int n = 0; n < 2; ++n) _Pragma("unroll") for (int k = 0; k < 2; ++k) \
;         acc[ai][bj][m][n] = __builtin_amdgcn_mfma_f32_16x16x32_bf16(Bt[n][k], At[m][k], acc[ai][bj][m][n], 0, 0, 0); __builtin_amdgcn_s_setprio(0); } while (0)
; #define PG8_WAIT_V(n) asm volatile("s_waitcnt vmcnt(" #n ")" ::: "memory")
; #define PG8_WAIT_L(n) asm volatile("s_waitcnt lgkmcnt(" #n ")" ::: "memory")
; #define PG8_BAR __builtin_amdgcn_s_barrier()
; #define PG8_SCHED __builtin_amdgcn_sched_barrier(0)
; template <class Epi, class Sched>
; __device__ __forceinline__ void gemm_phase(LAS unsigned char* lds, const Gemm g, const Sched& S, const Epi& E, const int tid) {
;     ...
;             PG8_WAIT_V(8); PG8_WAIT_L(0); PG8_BAR; PG8_MMA(0, 0, At, B0); PG8_MMA(0, 1, At, B1); PG8_BAR; PG8_SCHED;
;             PG8_LDA(At, 0, 1); PG8_STAGE(PG8_SB(0, 0), b2, voffB); PG8_STAGE(PG8_SB(0, 1), b2 + hstep, voffB); PG8_STAGE(PG8_SA(0, 0), a2, voffA);
;             PG8_WAIT_V(8); PG8_WAIT_L(0); PG8_BAR; PG8_MMA(1, 0, At, B0); PG8_MMA(1, 1, At, B1); PG8_BAR; PG8_SCHED;
	s_waitcnt lgkmcnt(0)
	v_mfma_f32_16x16x32_bf16 v[140:143], v[70:73], v[202:205], v[140:143]
	v_mfma_f32_16x16x32_bf16 v[136:139], v[172:175], v[202:205], v[136:139]
	v_mfma_f32_16x16x32_bf16 v[128:131], v[172:175], v[210:213], v[128:131]
	v_mfma_f32_16x16x32_bf16 v[132:135], v[70:73], v[210:213], v[132:135]
	v_mfma_f32_16x16x32_bf16 v[116:119], v[70:73], v[218:221], v[116:119]
	v_mfma_f32_16x16x32_bf16 v[112:115], v[172:175], v[218:221], v[112:115]
	v_mfma_f32_16x16x32_bf16 v[96:99], v[172:175], v[234:237], v[96:99]
	v_mfma_f32_16x16x32_bf16 v[100:103], v[70:73], v[234:237], v[100:103]
	v_mfma_f32_16x16x32_bf16 v[140:143], v[74:77], v[206:209], v[140:143]
	v_mfma_f32_16x16x32_bf16 v[136:139], v[176:179], v[206:209], v[136:139]
	v_mfma_f32_16x16x32_bf16 v[128:131], v[176:179], v[214:217], v[128:131]
	v_mfma_f32_16x16x32_bf16 v[132:135], v[74:77], v[214:217], v[132:135]
	v_mfma_f32_16x16x32_bf16 v[116:119], v[74:77], v[230:233], v[116:119]
	v_mfma_f32_16x16x32_bf16 v[112:115], v[176:179], v[230:233], v[112:115]
	v_mfma_f32_16x16x32_bf16 v[96:99], v[176:179], v[238:241], v[96:99]
	v_mfma_f32_16x16x32_bf16 v[100:103], v[74:77], v[238:241], v[100:103]
	v_mfma_f32_16x16x32_bf16 v[124:127], v[180:183], v[202:205], v[124:127]
	v_mfma_f32_16x16x32_bf16 v[120:123], v[188:191], v[202:205], v[120:123]
	v_mfma_f32_16x16x32_bf16 v[104:107], v[188:191], v[210:213], v[104:107]
	v_mfma_f32_16x16x32_bf16 v[108:111], v[180:183], v[210:213], v[108:111]
	v_mfma_f32_16x16x32_bf16 v[92:95], v[180:183], v[218:221], v[92:95]
	v_mfma_f32_16x16x32_bf16 v[88:91], v[188:191], v[218:221], v[88:91]
	v_mfma_f32_16x16x32_bf16 v[78:81], v[188:191], v[234:237], v[80:83]
	v_mfma_f32_16x16x32_bf16 v[84:87], v[180:183], v[234:237], v[84:87]
	v_mfma_f32_16x16x32_bf16 v[124:127], v[184:187], v[206:209], v[124:127]
	v_mfma_f32_16x16x32_bf16 v[120:123], v[198:201], v[206:209], v[120:123]
	v_mfma_f32_16x16x32_bf16 v[104:107], v[198:201], v[214:217], v[104:107]
	v_mfma_f32_16x16x32_bf16 v[108:111], v[184:187], v[214:217], v[108:111]
	v_mfma_f32_16x16x32_bf16 v[92:95], v[184:187], v[230:233], v[92:95]
	v_mfma_f32_16x16x32_bf16 v[88:91], v[198:201], v[230:233], v[88:91]
	v_mfma_f32_16x16x32_bf16 v[78:81], v[198:201], v[238:241], v[78:81]
	v_mfma_f32_16x16x32_bf16 v[84:87], v[184:187], v[238:241], v[84:87]
	s_barrier
	s_add_i32 s82, s82, s52
	v_lshl_add_u64 v[224:225], s[64:65], 0, v[164:165]
	s_mov_b32 m0, s82
	ds_read_b128 v[202:205], v171 offset:16384
	ds_read_b128 v[206:209], v171 offset:17408
	ds_read_b128 v[210:213], v171 offset:18432
	ds_read_b128 v[214:217], v171 offset:19456
	ds_read_b128 v[218:221], v171 offset:20480
	ds_read_b128 v[230:233], v171 offset:21504
	ds_read_b128 v[234:237], v171 offset:22528
	ds_read_b128 v[238:241], v171 offset:23552
	global_load_lds_dwordx4 v[224:225], off
	s_add_i32 m0, s82, 0x2000
	s_add_u32 s82, s64, 0x40000
	v_lshl_add_u64 v[226:227], s[64:65], 0, v[168:169]
	s_addc_u32 s83, s65, 0
	s_add_i32 s90, s90, s52
	global_load_lds_dwordx4 v[226:227], off
	v_lshl_add_u64 v[82:83], s[82:83], 0, v[164:165]
	s_mov_b32 m0, s90
	v_lshl_add_u64 v[242:243], s[66:67], 0, v[162:163]
	global_load_lds_dwordx4 v[82:83], off
	v_lshl_add_u64 v[82:83], s[82:83], 0, v[168:169]
	s_add_i32 m0, s90, 0x2000
	v_lshl_add_u64 v[244:245], s[66:67], 0, v[166:167]
	global_load_lds_dwordx4 v[82:83], off
	s_mov_b32 m0, s53
	s_nop 0
	global_load_lds_dwordx4 v[242:243], off
	s_mov_b32 m0, s56
	s_nop 0
	global_load_lds_dwordx4 v[244:245], off
	s_waitcnt vmcnt(8)
	s_waitcnt lgkmcnt(0)
	s_barrier
	s_waitcnt lgkmcnt(0)
	v_mfma_f32_16x16x32_bf16 v[60:63], v[70:73], v[202:205], v[60:63]
	v_mfma_f32_16x16x32_bf16 v[56:59], v[172:175], v[202:205], v[56:59]
	v_mfma_f32_16x16x32_bf16 v[44:47], v[172:175], v[210:213], v[44:47]
	v_mfma_f32_16x16x32_bf16 v[52:55], v[70:73], v[210:213], v[52:55]
	v_mfma_f32_16x16x32_bf16 v[28:31], v[70:73], v[218:221], v[28:31]
	v_mfma_f32_16x16x32_bf16 v[24:27], v[172:175], v[218:221], v[24:27]
	v_mfma_f32_16x16x32_bf16 v[8:11], v[172:175], v[234:237], v[8:11]
	v_mfma_f32_16x16x32_bf16 v[16:19], v[70:73], v[234:237], v[16:19]
	v_mfma_f32_16x16x32_bf16 v[60:63], v[74:77], v[206:209], v[60:63]
	v_mfma_f32_16x16x32_bf16 v[56:59], v[176:179], v[206:209], v[56:59]
	v_mfma_f32_16x16x32_bf16 v[44:47], v[176:179], v[214:217], v[44:47]
	v_mfma_f32_16x16x32_bf16 v[52:55], v[74:77], v[214:217], v[52:55]
	v_mfma_f32_16x16x32_bf16 v[28:31], v[74:77], v[230:233], v[28:31]
	v_mfma_f32_16x16x32_bf16 v[24:27], v[176:179], v[230:233], v[24:27]
	v_mfma_f32_16x16x32_bf16 v[8:11], v[176:179], v[238:241], v[8:11]
	v_mfma_f32_16x16x32_bf16 v[16:19], v[74:77], v[238:241], v[16:19]
	v_mfma_f32_16x16x32_bf16 v[48:51], v[180:183], v[202:205], v[48:51]
	v_mfma_f32_16x16x32_bf16 v[40:43], v[188:191], v[202:205], v[40:43]
	v_mfma_f32_16x16x32_bf16 v[32:35], v[188:191], v[210:213], v[32:35]
	v_mfma_f32_16x16x32_bf16 v[36:39], v[180:183], v[210:213], v[36:39]
	v_mfma_f32_16x16x32_bf16 v[20:23], v[180:183], v[218:221], v[20:23]
	v_mfma_f32_16x16x32_bf16 v[12:15], v[188:191], v[218:221], v[12:15]
	v_mfma_f32_16x16x32_bf16 v[0:3], v[188:191], v[234:237], v[0:3]
	v_mfma_f32_16x16x32_bf16 v[4:7], v[180:183], v[234:237], v[4:7]
	v_mfma_f32_16x16x32_bf16 v[48:51], v[184:187], v[206:209], v[48:51]
	v_mfma_f32_16x16x32_bf16 v[40:43], v[198:201], v[206:209], v[40:43]
	v_mfma_f32_16x16x32_bf16 v[32:35], v[198:201], v[214:217], v[32:35]
	v_mfma_f32_16x16x32_bf16 v[36:39], v[184:187], v[214:217], v[36:39]
	v_mfma_f32_16x16x32_bf16 v[20:23], v[184:187], v[230:233], v[20:23]
	v_mfma_f32_16x16x32_bf16 v[12:15], v[198:201], v[230:233], v[12:15]
	v_mfma_f32_16x16x32_bf16 v[0:3], v[198:201], v[238:241], v[0:3]
	v_mfma_f32_16x16x32_bf16 v[4:7], v[184:187], v[238:241], v[4:7]
	s_barrier
; #define PG8_STAGE(bufoff, gbase, voff) do { _Pragma("unroll") for (int _i = 0; _i < 2; ++_i) \
;         __builtin_amdgcn_global_load_lds((const unsigned*)((const char*)(gbase) + (voff)[_i]), (LAS unsigned*)(lds + (bufoff) + ldsw + _i * 8192), 16, 0, 0); } while (0)
; #define PG8_LDA(dst, b, h) do { _Pragma("unroll") for (int m = 0; m < 4; ++m) _Pragma("unroll") for (int k = 0; k < 2; ++k) dst[m][k] = *(const LAS bf16x8*)(lds + PG8_SA(b, h) + aoff + m * 2048 + k * 1024); } while (0)
; #define PG8_LDB(dst, b, h) do { _Pragma("unroll") for (int n = 0; n < 2; ++n) _Pragma("unroll") for (int k = 0; k < 2; ++k) dst[n][k] = *(const LAS bf16x8*)(lds + PG8_SB(b, h) + boff + n * 2048 + k * 1024); } while (0)
; #define PG8_MMA(ai, bj, At, Bt) do { __builtin_amdgcn_s_setprio(1); _Pragma("unroll") for (int m = 0; m < 4; ++m) _Pragma("unroll") for (int n = 0; n < 2; ++n) _Pragma("unroll") for (int k = 0; k < 2; ++k) \
;         acc[ai][bj][m][n] = __builtin_amdgcn_mfma_f32_16x16x32_bf16(Bt[n][k], At[m][k], acc[ai][bj][m][n], 0, 0, 0); __builtin_amdgcn_s_setprio(0); } while (0)
; #define PG8_WAIT_V(n) asm volatile("s_waitcnt vmcnt(" #n ")" ::: "memory")
; #define PG8_WAIT_L(n) asm volatile("s_waitcnt lgkmcnt(" #n ")" ::: "memory")
; #define PG8_BAR __builtin_amdgcn_s_barrier()
; #define PG8_SCHED __builtin_amdgcn_sched_barrier(0)
; template <class Epi, class Sched>
; __device__ __forceinline__ void gemm_phase(LAS unsigned char* lds, const Gemm g, const Sched& S, const Epi& E, const int tid) {
;     ...
;             PG8_LDB(B0, 1, 0); PG8_LDB(B1, 1, 1); PG8_SCHED; PG8_LDA(At, 1, 0); PG8_STAGE(PG8_SA(0, 1), a2 + hstep, voffA);
;             PG8_WAIT_V(8); PG8_WAIT_L(0); PG8_BAR; PG8_MMA(0, 0, At, B0); PG8_MMA(0, 1, At, B1); PG8_BAR; PG8_SCHED;
	s_add_i32 s82, 0, 0x18000
	v_add_u32_e32 v69, s82, v154
	s_add_i32 s83, 0, 0x1c000
	ds_read_b128 v[70:73], v69
	ds_read_b128 v[74:77], v69 offset:1024
	ds_read_b128 v[172:175], v69 offset:2048
	ds_read_b128 v[176:179], v69 offset:3072
	v_add_u32_e32 v69, s83, v154
	ds_read_b128 v[180:183], v69
	ds_read_b128 v[184:187], v69 offset:1024
	ds_read_b128 v[188:191], v69 offset:2048
	ds_read_b128 v[198:201], v69 offset:3072
	s_add_u32 s66, s66, 0x40000
	s_addc_u32 s67, s67, 0
	s_mov_b32 m0, s57
	v_lshl_add_u64 v[82:83], s[66:67], 0, v[162:163]
	ds_read_b128 v[202:205], v171 offset:32768
	ds_read_b128 v[206:209], v171 offset:33792
	ds_read_b128 v[210:213], v171 offset:34816
	ds_read_b128 v[214:217], v171 offset:35840
	ds_read_b128 v[218:221], v171 offset:36864
	ds_read_b128 v[230:233], v171 offset:37888
	ds_read_b128 v[234:237], v171 offset:38912
	ds_read_b128 v[238:241], v171 offset:39936
	global_load_lds_dwordx4 v[82:83], off
	v_lshl_add_u64 v[82:83], s[66:67], 0, v[166:167]
	s_mov_b32 m0, s58
	s_nop 0
	global_load_lds_dwordx4 v[82:83], off
	s_waitcnt vmcnt(8)
	s_waitcnt lgkmcnt(0)
	s_barrier
	s_waitcnt lgkmcnt(0)
	v_mfma_f32_16x16x32_bf16 v[140:143], v[70:73], v[202:205], v[140:143]
	v_mfma_f32_16x16x32_bf16 v[136:139], v[172:175], v[202:205], v[136:139]
	v_mfma_f32_16x16x32_bf16 v[128:131], v[172:175], v[210:213], v[128:131]
	v_mfma_f32_16x16x32_bf16 v[132:135], v[70:73], v[210:213], v[132:135]
	v_mfma_f32_16x16x32_bf16 v[116:119], v[70:73], v[218:221], v[116:119]
	v_mfma_f32_16x16x32_bf16 v[112:115], v[172:175], v[218:221], v[112:115]
	v_mfma_f32_16x16x32_bf16 v[96:99], v[172:175], v[234:237], v[96:99]
	v_mfma_f32_16x16x32_bf16 v[100:103], v[70:73], v[234:237], v[100:103]
	v_mfma_f32_16x16x32_bf16 v[140:143], v[74:77], v[206:209], v[140:143]
	v_mfma_f32_16x16x32_bf16 v[136:139], v[176:179], v[206:209], v[136:139]
	v_mfma_f32_16x16x32_bf16 v[128:131], v[176:179], v[214:217], v[128:131]
	v_mfma_f32_16x16x32_bf16 v[132:135], v[74:77], v[214:217], v[132:135]
	v_mfma_f32_16x16x32_bf16 v[116:119], v[74:77], v[230:233], v[116:119]
	v_mfma_f32_16x16x32_bf16 v[112:115], v[176:179], v[230:233], v[112:115]
	v_mfma_f32_16x16x32_bf16 v[96:99], v[176:179], v[238:241], v[96:99]
	v_mfma_f32_16x16x32_bf16 v[100:103], v[74:77], v[238:241], v[100:103]
	v_mfma_f32_16x16x32_bf16 v[124:127], v[180:183], v[202:205], v[124:127]
	v_mfma_f32_16x16x32_bf16 v[120:123], v[188:191], v[202:205], v[120:123]
	v_mfma_f32_16x16x32_bf16 v[104:107], v[188:191], v[210:213], v[104:107]
	v_mfma_f32_16x16x32_bf16 v[108:111], v[180:183], v[210:213], v[108:111]
	v_mfma_f32_16x16x32_bf16 v[92:95], v[180:183], v[218:221], v[92:95]
	v_mfma_f32_16x16x32_bf16 v[88:91], v[188:191], v[218:221], v[88:91]
	v_mfma_f32_16x16x32_bf16 v[78:81], v[188:191], v[234:237], v[78:81]
	v_mfma_f32_16x16x32_bf16 v[82:85], v[180:183], v[234:237], v[84:87]
	v_mfma_f32_16x16x32_bf16 v[124:127], v[184:187], v[206:209], v[124:127]
	v_mfma_f32_16x16x32_bf16 v[120:123], v[198:201], v[206:209], v[120:123]
	v_mfma_f32_16x16x32_bf16 v[104:107], v[198:201], v[214:217], v[104:107]
	v_mfma_f32_16x16x32_bf16 v[108:111], v[184:187], v[214:217], v[108:111]
	v_mfma_f32_16x16x32_bf16 v[92:95], v[184:187], v[230:233], v[92:95]
	v_mfma_f32_16x16x32_bf16 v[88:91], v[198:201], v[230:233], v[88:91]
	v_mfma_f32_16x16x32_bf16 v[80:83], v[198:201], v[238:241], v[78:81]
	v_mfma_f32_16x16x32_bf16 v[84:87], v[184:187], v[238:241], v[82:85]
	s_barrier
; #define PG8_STAGE(bufoff, gbase, voff) do { _Pragma("unroll") for (int _i = 0; _i < 2; ++_i) \
;         __builtin_amdgcn_global_load_lds((const unsigned*)((const char*)(gbase) + (voff)[_i]), (LAS unsigned*)(lds + (bufoff) + ldsw + _i * 8192), 16, 0, 0); } while (0)
; #define PG8_LDA(dst, b, h) do { _Pragma("unroll") for (int m = 0; m < 4; ++m) _Pragma("unroll") for (int k = 0; k < 2; ++k) dst[m][k] = *(const LAS bf16x8*)(lds + PG8_SA(b, h) + aoff + m * 2048 + k * 1024); } while (0)
; #define PG8_MMA(ai, bj, At, Bt) do { __builtin_amdgcn_s_setprio(1); _Pragma("unroll") for (int m = 0; m < 4; ++m) _Pragma("unroll") for (int n = 0; n < 2; ++n) _Pragma("unroll") for (int k = 0; k < 2; ++k) \
;         acc[ai][bj][m][n] = __builtin_amdgcn_mfma_f32_16x16x32_bf16(Bt[n][k], At[m][k], acc[ai][bj][m][n], 0, 0, 0); __builtin_amdgcn_s_setprio(0); } while (0)
; #define PG8_WAIT_V(n) asm volatile("s_waitcnt vmcnt(" #n ")" ::: "memory")
; #define PG8_WAIT_L(n) asm volatile("s_waitcnt lgkmcnt(" #n ")" ::: "memory")
; #define PG8_BAR __builtin_amdgcn_s_barrier()
; #define PG8_SCHED __builtin_amdgcn_sched_barrier(0)
; template <class Epi, class Sched>
; __device__ __forceinline__ void gemm_phase(LAS unsigned char* lds, const Gemm g, const Sched& S, const Epi& E, const int tid) {
;     ...
;             PG8_LDA(At, 1, 1); PG8_STAGE(PG8_SB(1, 0), b3, voffB); PG8_STAGE(PG8_SB(1, 1), b3 + hstep, voffB); PG8_STAGE(PG8_SA(1, 0), a3, voffA);
;             PG8_WAIT_V(8); PG8_WAIT_L(0); PG8_BAR; PG8_MMA(1, 0, At, B0); PG8_MMA(1, 1, At, B1); PG8_BAR; PG8_SCHED;
;         }
;         if (wr == 0) PG8_BAR;
	s_add_i32 s66, s82, s52
	v_lshl_add_u64 v[78:79], v[224:225], 0, s[68:69]
	s_mov_b32 m0, s66
	ds_read_b128 v[202:205], v171 offset:49152
	ds_read_b128 v[206:209], v171 offset:50176
	ds_read_b128 v[210:213], v171 offset:51200
	ds_read_b128 v[214:217], v171 offset:52224
	ds_read_b128 v[218:221], v171 offset:53248
	ds_read_b128 v[230:233], v171 offset:54272
	ds_read_b128 v[234:237], v171 offset:55296
	ds_read_b128 v[238:241], v171 offset:56320
	global_load_lds_dwordx4 v[78:79], off
	s_add_i32 m0, s66, 0x2000
	s_add_u32 s64, s64, 0x40080
	v_lshl_add_u64 v[78:79], v[226:227], 0, s[68:69]
	s_addc_u32 s65, s65, 0
	s_add_i32 s66, s83, s52
	global_load_lds_dwordx4 v[78:79], off
	v_lshl_add_u64 v[78:79], s[64:65], 0, v[164:165]
	s_mov_b32 m0, s66
	s_nop 0
	global_load_lds_dwordx4 v[78:79], off
	v_lshl_add_u64 v[78:79], s[64:65], 0, v[168:169]
	s_add_i32 m0, s66, 0x2000
	s_nop 0
	global_load_lds_dwordx4 v[78:79], off
	v_lshl_add_u64 v[78:79], v[242:243], 0, s[68:69]
	s_mov_b32 m0, s61
	s_nop 0
	global_load_lds_dwordx4 v[78:79], off
	v_lshl_add_u64 v[78:79], v[244:245], 0, s[68:69]
	s_mov_b32 m0, s70
	s_nop 0
	global_load_lds_dwordx4 v[78:79], off
	s_waitcnt vmcnt(8)
	s_waitcnt lgkmcnt(0)
	s_barrier
	s_waitcnt lgkmcnt(0)
	v_mfma_f32_16x16x32_bf16 v[60:63], v[70:73], v[202:205], v[60:63]
	v_mfma_f32_16x16x32_bf16 v[56:59], v[172:175], v[202:205], v[56:59]
	v_mfma_f32_16x16x32_bf16 v[44:47], v[172:175], v[210:213], v[44:47]
	v_mfma_f32_16x16x32_bf16 v[52:55], v[70:73], v[210:213], v[52:55]
	v_mfma_f32_16x16x32_bf16 v[28:31], v[70:73], v[218:221], v[28:31]
	v_mfma_f32_16x16x32_bf16 v[24:27], v[172:175], v[218:221], v[24:27]
	v_mfma_f32_16x16x32_bf16 v[8:11], v[172:175], v[234:237], v[8:11]
	v_mfma_f32_16x16x32_bf16 v[16:19], v[70:73], v[234:237], v[16:19]
	v_mfma_f32_16x16x32_bf16 v[60:63], v[74:77], v[206:209], v[60:63]
	v_mfma_f32_16x16x32_bf16 v[56:59], v[176:179], v[206:209], v[56:59]
	v_mfma_f32_16x16x32_bf16 v[44:47], v[176:179], v[214:217], v[44:47]
	v_mfma_f32_16x16x32_bf16 v[52:55], v[74:77], v[214:217], v[52:55]
	v_mfma_f32_16x16x32_bf16 v[28:31], v[74:77], v[230:233], v[28:31]
	v_mfma_f32_16x16x32_bf16 v[24:27], v[176:179], v[230:233], v[24:27]
	v_mfma_f32_16x16x32_bf16 v[8:11], v[176:179], v[238:241], v[8:11]
	v_mfma_f32_16x16x32_bf16 v[16:19], v[74:77], v[238:241], v[16:19]
	v_mfma_f32_16x16x32_bf16 v[48:51], v[180:183], v[202:205], v[48:51]
	v_mfma_f32_16x16x32_bf16 v[40:43], v[188:191], v[202:205], v[40:43]
	v_mfma_f32_16x16x32_bf16 v[32:35], v[188:191], v[210:213], v[32:35]
	v_mfma_f32_16x16x32_bf16 v[36:39], v[180:183], v[210:213], v[36:39]
	v_mfma_f32_16x16x32_bf16 v[20:23], v[180:183], v[218:221], v[20:23]
	v_mfma_f32_16x16x32_bf16 v[12:15], v[188:191], v[218:221], v[12:15]
	v_mfma_f32_16x16x32_bf16 v[0:3], v[188:191], v[234:237], v[0:3]
	v_mfma_f32_16x16x32_bf16 v[4:7], v[180:183], v[234:237], v[4:7]
	v_mfma_f32_16x16x32_bf16 v[48:51], v[184:187], v[206:209], v[48:51]
	v_mfma_f32_16x16x32_bf16 v[40:43], v[198:201], v[206:209], v[40:43]
	v_mfma_f32_16x16x32_bf16 v[32:35], v[198:201], v[214:217], v[32:35]
	v_mfma_f32_16x16x32_bf16 v[36:39], v[184:187], v[214:217], v[36:39]
	v_mfma_f32_16x16x32_bf16 v[20:23], v[184:187], v[230:233], v[20:23]
	v_mfma_f32_16x16x32_bf16 v[12:15], v[198:201], v[230:233], v[12:15]
	v_mfma_f32_16x16x32_bf16 v[0:3], v[198:201], v[238:241], v[0:3]
	v_mfma_f32_16x16x32_bf16 v[4:7], v[184:187], v[238:241], v[4:7]
	s_barrier
	s_add_i32 s81, s81, 2
	s_add_u32 s62, s62, 0x100
	s_addc_u32 s63, s63, 0
	s_add_u32 s78, s78, 0x100
	s_addc_u32 s79, s79, 0
	s_cmp_gt_u32 s81, 13
	s_cbranch_scc0 .LBB0_326
	s_and_b64 vcc, exec, s[8:9]
	s_cbranch_vccz .LBB0_329
	s_barrier

; #define PG8_STAGE(bufoff, gbase, voff) do { _Pragma("unroll") for (int _i = 0; _i < 2; ++_i) \
;         __builtin_amdgcn_global_load_lds((const unsigned*)((const char*)(gbase) + (voff)[_i]), (LAS unsigned*)(lds + (bufoff) + ldsw + _i * 8192), 16, 0, 0); } while (0)
; #define PG8_LDA(dst, b, h) do { _Pragma("unroll") for (int m = 0; m < 4; ++m) _Pragma("unroll") for (int k = 0; k < 2; ++k) dst[m][k] = *(const LAS bf16x8*)(lds + PG8_SA(b, h) + aoff + m * 2048 + k * 1024); } while (0)
; #define PG8_LDB(dst, b, h) do { _Pragma("unroll") for (int n = 0; n < 2; ++n) _Pragma("unroll") for (int k = 0; k < 2; ++k) dst[n][k] = *(const LAS bf16x8*)(lds + PG8_SB(b, h) + boff + n * 2048 + k * 1024); } while (0)
; #define PG8_MMA(ai, bj, At, Bt) do { __builtin_amdgcn_s_setprio(1); _Pragma("unroll") for (int m = 0; m < 4; ++m) _Pragma("unroll") for (int n = 0; n < 2; ++n) _Pragma("unroll") for (int k = 0; k < 2; ++k) \
;         acc[ai][bj][m][n] = __builtin_amdgcn_mfma_f32_16x16x32_bf16(Bt[n][k], At[m][k], acc[ai][bj][m][n], 0, 0, 0); __builtin_amdgcn_s_setprio(0); } while (0)
; #define PG8_WAIT_V(n) asm volatile("s_waitcnt vmcnt(" #n ")" ::: "memory")
; #define PG8_WAIT_L(n) asm volatile("s_waitcnt lgkmcnt(" #n ")" ::: "memory")
; #define PG8_BAR __builtin_amdgcn_s_barrier()
; #define PG8_SCHED __builtin_amdgcn_sched_barrier(0)
; template <class Epi, class Sched>
; __device__ __forceinline__ void gemm_phase(LAS unsigned char* lds, const Gemm g, const Sched& S, const Epi& E, const int tid) {
;     ...
;         for (int t = 0; t < nt; t += 2) {
;             const bool last = (t == nt - 2);
;             const char* a1 = cA + (size_t)(t + 1) * kstep;
;             const char* a2 = last ? nA : cA + (size_t)(t + 2) * kstep; const char* b2 = last ? nB : cB + (size_t)(t + 2) * kstep;
;             const char* a3 = a2 + kstep; const char* b3 = b2 + kstep;
;             PG8_LDB(B0, 0, 0); PG8_LDB(B1, 0, 1); PG8_SCHED; PG8_LDA(At, 0, 0); PG8_STAGE(PG8_SA(1, 1), a1 + hstep, voffA);
;             PG8_WAIT_V(8); PG8_WAIT_L(0); PG8_BAR; PG8_MMA(0, 0, At, B0); PG8_MMA(0, 1, At, B1); PG8_BAR; PG8_SCHED;
;             PG8_LDA(At, 0, 1); PG8_STAGE(PG8_SB(0, 0), b2, voffB); PG8_STAGE(PG8_SB(0, 1), b2 + hstep, voffB); PG8_STAGE(PG8_SA(0, 0), a2, voffA);
.LBB0_565:
.LBB0_566:
	s_or_b64 exec, exec, s[82:83]
	s_add_u32 vcc_lo, s80, 0x80
	s_addc_u32 vcc_hi, s81, 0
	s_add_u32 s61, s74, 0x100
	s_addc_u32 s67, s75, 0
	s_mov_b32 s74, 0
	s_add_i32 s80, s74, 2
	s_add_u32 s81, vcc_lo, 0x80
	s_addc_u32 s75, vcc_hi, 0
	s_add_i32 s3, 0, 0x10000
	s_cmp_eq_u32 s57, s74
	s_cselect_b32 s75, s71, s75
	s_cselect_b32 s74, s70, s81
	v_add_u32_e32 v70, s3, v232
	s_cselect_b32 s83, s73, s67
	s_cselect_b32 s82, s72, s61
	s_add_i32 s81, 0, 0x14000
	ds_read_b128 v[58:61], v70
	ds_read_b128 v[62:65], v70 offset:1024
	ds_read_b128 v[66:69], v70 offset:2048
	ds_read_b128 v[80:83], v70 offset:3072
	v_add_u32_e32 v70, s81, v232
	ds_read_b128 v[84:87], v70
	ds_read_b128 v[88:91], v70 offset:1024
	ds_read_b128 v[92:95], v70 offset:2048
	ds_read_b128 v[152:155], v70 offset:3072
	v_lshl_add_u64 v[70:71], vcc, 0, v[204:205]
	s_add_i32 m0, s97, 0xc000
	ds_read_b128 v[164:167], v240
	ds_read_b128 v[168:171], v240 offset:1024
	ds_read_b128 v[172:175], v240 offset:2048
	ds_read_b128 v[176:179], v240 offset:3072
	ds_read_b128 v[180:183], v240 offset:4096
	ds_read_b128 v[184:187], v240 offset:5120
	ds_read_b128 v[188:191], v240 offset:6144
	ds_read_b128 v[208:211], v240 offset:7168
	global_load_lds_dwordx4 v[70:71], off
	v_lshl_add_u64 v[70:71], vcc, 0, v[206:207]
	s_add_i32 m0, s97, 0xe000
	s_nop 0
	global_load_lds_dwordx4 v[70:71], off
	s_waitcnt vmcnt(8)
	s_waitcnt lgkmcnt(0)
	s_barrier
	s_waitcnt lgkmcnt(0)
	v_mfma_f32_16x16x32_bf16 v[160:163], v[58:61], v[164:167], 0
	v_mfma_f32_16x16x32_bf16 v[156:159], v[66:69], v[164:167], 0
	v_mfma_f32_16x16x32_bf16 v[136:139], v[66:69], v[172:175], 0
	v_mfma_f32_16x16x32_bf16 v[140:143], v[58:61], v[172:175], 0
	v_mfma_f32_16x16x32_bf16 v[124:127], v[58:61], v[180:183], 0
	v_mfma_f32_16x16x32_bf16 v[120:123], v[66:69], v[180:183], 0
	v_mfma_f32_16x16x32_bf16 v[104:107], v[66:69], v[188:191], 0
	v_mfma_f32_16x16x32_bf16 v[108:111], v[58:61], v[188:191], 0
	v_mfma_f32_16x16x32_bf16 v[160:163], v[62:65], v[168:171], v[160:163]
	v_mfma_f32_16x16x32_bf16 v[156:159], v[80:83], v[168:171], v[156:159]
	v_mfma_f32_16x16x32_bf16 v[136:139], v[80:83], v[176:179], v[136:139]
	v_mfma_f32_16x16x32_bf16 v[140:143], v[62:65], v[176:179], v[140:143]
	v_mfma_f32_16x16x32_bf16 v[124:127], v[62:65], v[184:187], v[124:127]
	v_mfma_f32_16x16x32_bf16 v[120:123], v[80:83], v[184:187], v[120:123]
	v_mfma_f32_16x16x32_bf16 v[104:107], v[80:83], v[208:211], v[104:107]
	v_mfma_f32_16x16x32_bf16 v[108:111], v[62:65], v[208:211], v[108:111]
	v_mfma_f32_16x16x32_bf16 v[148:151], v[84:87], v[164:167], 0
	v_mfma_f32_16x16x32_bf16 v[144:147], v[92:95], v[164:167], 0
	v_mfma_f32_16x16x32_bf16 v[128:131], v[92:95], v[172:175], 0
	v_mfma_f32_16x16x32_bf16 v[132:135], v[84:87], v[172:175], 0
	v_mfma_f32_16x16x32_bf16 v[116:119], v[84:87], v[180:183], 0
	v_mfma_f32_16x16x32_bf16 v[112:115], v[92:95], v[180:183], 0
	v_mfma_f32_16x16x32_bf16 v[96:99], v[92:95], v[188:191], 0
	v_mfma_f32_16x16x32_bf16 v[100:103], v[84:87], v[188:191], 0
	v_mfma_f32_16x16x32_bf16 v[148:151], v[88:91], v[168:171], v[148:151]
	v_mfma_f32_16x16x32_bf16 v[144:147], v[152:155], v[168:171], v[144:147]
	v_mfma_f32_16x16x32_bf16 v[128:131], v[152:155], v[176:179], v[128:131]
	v_mfma_f32_16x16x32_bf16 v[132:135], v[88:91], v[176:179], v[132:135]
	v_mfma_f32_16x16x32_bf16 v[116:119], v[88:91], v[184:187], v[116:119]
	v_mfma_f32_16x16x32_bf16 v[112:115], v[152:155], v[184:187], v[112:115]
	v_mfma_f32_16x16x32_bf16 v[96:99], v[152:155], v[208:211], v[96:99]
	v_mfma_f32_16x16x32_bf16 v[100:103], v[88:91], v[208:211], v[100:103]
	s_barrier
	s_add_i32 s3, s3, s94
	v_lshl_add_u64 v[212:213], s[82:83], 0, v[192:193]
	s_mov_b32 m0, s3
	ds_read_b128 v[164:167], v240 offset:16384
	ds_read_b128 v[168:171], v240 offset:17408
	ds_read_b128 v[172:175], v240 offset:18432
	ds_read_b128 v[176:179], v240 offset:19456
	ds_read_b128 v[180:183], v240 offset:20480
	ds_read_b128 v[184:187], v240 offset:21504
	ds_read_b128 v[188:191], v240 offset:22528
	ds_read_b128 v[208:211], v240 offset:23552
	global_load_lds_dwordx4 v[212:213], off
	s_add_i32 m0, s3, 0x2000
	v_lshl_add_u64 v[214:215], s[82:83], 0, v[198:199]
	s_add_u32 s82, s82, s12
	s_addc_u32 s83, s83, 0
	s_add_i32 s3, s81, s94
	global_load_lds_dwordx4 v[214:215], off
	v_lshl_add_u64 v[216:217], s[82:83], 0, v[192:193]
	s_mov_b32 m0, s3
	v_lshl_add_u64 v[218:219], s[82:83], 0, v[198:199]
	global_load_lds_dwordx4 v[216:217], off
	s_add_i32 m0, s3, 0x2000
	v_lshl_add_u64 v[220:221], s[74:75], 0, v[202:203]
	global_load_lds_dwordx4 v[218:219], off
	s_mov_b32 m0, s97
	v_lshl_add_u64 v[224:225], s[74:75], 0, v[200:201]
	global_load_lds_dwordx4 v[220:221], off
	s_mov_b32 m0, s98
	s_nop 0
	global_load_lds_dwordx4 v[224:225], off
	s_waitcnt vmcnt(8)
	s_waitcnt lgkmcnt(0)
	s_barrier
; #define PG8_STAGE(bufoff, gbase, voff) do { _Pragma("unroll") for (int _i = 0; _i < 2; ++_i) \
;         __builtin_amdgcn_global_load_lds((const unsigned*)((const char*)(gbase) + (voff)[_i]), (LAS unsigned*)(lds + (bufoff) + ldsw + _i * 8192), 16, 0, 0); } while (0)
; #define PG8_LDA(dst, b, h) do { _Pragma("unroll") for (int m = 0; m < 4; ++m) _Pragma("unroll") for (int k = 0; k < 2; ++k) dst[m][k] = *(const LAS bf16x8*)(lds + PG8_SA(b, h) + aoff + m * 2048 + k * 1024); } while (0)
; #define PG8_LDB(dst, b, h) do { _Pragma("unroll") for (int n = 0; n < 2; ++n) _Pragma("unroll") for (int k = 0; k < 2; ++k) dst[n][k] = *(const LAS bf16x8*)(lds + PG8_SB(b, h) + boff + n * 2048 + k * 1024); } while (0)
; #define PG8_MMA(ai, bj, At, Bt) do { __builtin_amdgcn_s_setprio(1); _Pragma("unroll") for (int m = 0; m < 4; ++m) _Pragma("unroll") for (int n = 0; n < 2; ++n) _Pragma("unroll") for (int k = 0; k < 2; ++k) \
;         acc[ai][bj][m][n] = __builtin_amdgcn_mfma_f32_16x16x32_bf16(Bt[n][k], At[m][k], acc[ai][bj][m][n], 0, 0, 0); __builtin_amdgcn_s_setprio(0); } while (0)
; #define PG8_WAIT_V(n) asm volatile("s_waitcnt vmcnt(" #n ")" ::: "memory")
; #define PG8_WAIT_L(n) asm volatile("s_waitcnt lgkmcnt(" #n ")" ::: "memory")
; #define PG8_BAR __builtin_amdgcn_s_barrier()
; #define PG8_SCHED __builtin_amdgcn_sched_barrier(0)
; template <class Epi, class Sched>
; __device__ __forceinline__ void gemm_phase(LAS unsigned char* lds, const Gemm g, const Sched& S, const Epi& E, const int tid) {
;     ...
;             PG8_WAIT_V(8); PG8_WAIT_L(0); PG8_BAR; PG8_MMA(1, 0, At, B0); PG8_MMA(1, 1, At, B1); PG8_BAR; PG8_SCHED;
;             PG8_LDB(B0, 1, 0); PG8_LDB(B1, 1, 1); PG8_SCHED; PG8_LDA(At, 1, 0); PG8_STAGE(PG8_SA(0, 1), a2 + hstep, voffA);
;             PG8_WAIT_V(8); PG8_WAIT_L(0); PG8_BAR; PG8_MMA(0, 0, At, B0); PG8_MMA(0, 1, At, B1); PG8_BAR; PG8_SCHED;
	s_waitcnt lgkmcnt(0)
	v_mfma_f32_16x16x32_bf16 v[76:79], v[58:61], v[164:167], 0
	v_mfma_f32_16x16x32_bf16 v[70:73], v[66:69], v[164:167], 0
	v_mfma_f32_16x16x32_bf16 v[40:43], v[66:69], v[172:175], 0
	v_mfma_f32_16x16x32_bf16 v[44:47], v[58:61], v[172:175], 0
	v_mfma_f32_16x16x32_bf16 v[28:31], v[58:61], v[180:183], 0
	v_mfma_f32_16x16x32_bf16 v[24:27], v[66:69], v[180:183], 0
	v_mfma_f32_16x16x32_bf16 v[8:11], v[66:69], v[188:191], 0
	v_mfma_f32_16x16x32_bf16 v[12:15], v[58:61], v[188:191], 0
	v_mfma_f32_16x16x32_bf16 v[76:79], v[62:65], v[168:171], v[76:79]
	v_mfma_f32_16x16x32_bf16 v[70:73], v[80:83], v[168:171], v[70:73]
	v_mfma_f32_16x16x32_bf16 v[40:43], v[80:83], v[176:179], v[40:43]
	v_mfma_f32_16x16x32_bf16 v[44:47], v[62:65], v[176:179], v[44:47]
	v_mfma_f32_16x16x32_bf16 v[28:31], v[62:65], v[184:187], v[28:31]
	v_mfma_f32_16x16x32_bf16 v[24:27], v[80:83], v[184:187], v[24:27]
	v_mfma_f32_16x16x32_bf16 v[8:11], v[80:83], v[208:211], v[8:11]
	v_mfma_f32_16x16x32_bf16 v[12:15], v[62:65], v[208:211], v[12:15]
	v_mfma_f32_16x16x32_bf16 v[52:55], v[84:87], v[164:167], 0
	v_mfma_f32_16x16x32_bf16 v[48:51], v[92:95], v[164:167], 0
	v_mfma_f32_16x16x32_bf16 v[32:35], v[92:95], v[172:175], 0
	v_mfma_f32_16x16x32_bf16 v[36:39], v[84:87], v[172:175], 0
	v_mfma_f32_16x16x32_bf16 v[20:23], v[84:87], v[180:183], 0
	v_mfma_f32_16x16x32_bf16 v[16:19], v[92:95], v[180:183], 0
	v_mfma_f32_16x16x32_bf16 v[0:3], v[92:95], v[188:191], 0
	v_mfma_f32_16x16x32_bf16 v[4:7], v[84:87], v[188:191], 0
	v_mfma_f32_16x16x32_bf16 v[52:55], v[88:91], v[168:171], v[52:55]
	v_mfma_f32_16x16x32_bf16 v[48:51], v[152:155], v[168:171], v[48:51]
	v_mfma_f32_16x16x32_bf16 v[32:35], v[152:155], v[176:179], v[32:35]
	v_mfma_f32_16x16x32_bf16 v[36:39], v[88:91], v[176:179], v[36:39]
	v_mfma_f32_16x16x32_bf16 v[20:23], v[88:91], v[184:187], v[20:23]
	v_mfma_f32_16x16x32_bf16 v[16:19], v[152:155], v[184:187], v[16:19]
	v_mfma_f32_16x16x32_bf16 v[0:3], v[152:155], v[208:211], v[0:3]
	v_mfma_f32_16x16x32_bf16 v[4:7], v[88:91], v[208:211], v[4:7]
	s_barrier
	s_add_i32 s3, 0, 0x18000
	v_add_u32_e32 v74, s3, v232
	s_add_i32 s81, 0, 0x1c000
	ds_read_b128 v[58:61], v74
	ds_read_b128 v[62:65], v74 offset:1024
	ds_read_b128 v[66:69], v74 offset:2048
	ds_read_b128 v[80:83], v74 offset:3072
	v_add_u32_e32 v74, s81, v232
	ds_read_b128 v[84:87], v74
	ds_read_b128 v[88:91], v74 offset:1024
	ds_read_b128 v[92:95], v74 offset:2048
	ds_read_b128 v[152:155], v74 offset:3072
	s_add_u32 s74, s74, s12
	s_addc_u32 s75, s75, 0
	s_mov_b32 m0, s99
	v_lshl_add_u64 v[74:75], s[74:75], 0, v[202:203]
	ds_read_b128 v[164:167], v240 offset:32768
	ds_read_b128 v[168:171], v240 offset:33792
	ds_read_b128 v[172:175], v240 offset:34816
	ds_read_b128 v[176:179], v240 offset:35840
	ds_read_b128 v[180:183], v240 offset:36864
	ds_read_b128 v[184:187], v240 offset:37888
	ds_read_b128 v[188:191], v240 offset:38912
	ds_read_b128 v[208:211], v240 offset:39936
	global_load_lds_dwordx4 v[74:75], off
	v_lshl_add_u64 v[74:75], s[74:75], 0, v[200:201]
	s_mov_b32 m0, s78
	s_nop 0
	global_load_lds_dwordx4 v[74:75], off
	s_waitcnt vmcnt(8)
	s_waitcnt lgkmcnt(0)
	s_barrier
	s_waitcnt lgkmcnt(0)
	v_mfma_f32_16x16x32_bf16 v[160:163], v[58:61], v[164:167], v[160:163]
	v_mfma_f32_16x16x32_bf16 v[156:159], v[66:69], v[164:167], v[156:159]
	v_mfma_f32_16x16x32_bf16 v[136:139], v[66:69], v[172:175], v[136:139]
	v_mfma_f32_16x16x32_bf16 v[140:143], v[58:61], v[172:175], v[140:143]
	v_mfma_f32_16x16x32_bf16 v[124:127], v[58:61], v[180:183], v[124:127]
	v_mfma_f32_16x16x32_bf16 v[120:123], v[66:69], v[180:183], v[120:123]
	v_mfma_f32_16x16x32_bf16 v[104:107], v[66:69], v[188:191], v[104:107]
	v_mfma_f32_16x16x32_bf16 v[108:111], v[58:61], v[188:191], v[108:111]
	v_mfma_f32_16x16x32_bf16 v[160:163], v[62:65], v[168:171], v[160:163]
	v_mfma_f32_16x16x32_bf16 v[156:159], v[80:83], v[168:171], v[156:159]
	v_mfma_f32_16x16x32_bf16 v[136:139], v[80:83], v[176:179], v[136:139]
	v_mfma_f32_16x16x32_bf16 v[140:143], v[62:65], v[176:179], v[140:143]
	v_mfma_f32_16x16x32_bf16 v[124:127], v[62:65], v[184:187], v[124:127]
	v_mfma_f32_16x16x32_bf16 v[120:123], v[80:83], v[184:187], v[120:123]
	v_mfma_f32_16x16x32_bf16 v[104:107], v[80:83], v[208:211], v[104:107]
	v_mfma_f32_16x16x32_bf16 v[108:111], v[62:65], v[208:211], v[108:111]
	v_mfma_f32_16x16x32_bf16 v[148:151], v[84:87], v[164:167], v[148:151]
	v_mfma_f32_16x16x32_bf16 v[144:147], v[92:95], v[164:167], v[144:147]
	v_mfma_f32_16x16x32_bf16 v[128:131], v[92:95], v[172:175], v[128:131]
	v_mfma_f32_16x16x32_bf16 v[132:135], v[84:87], v[172:175], v[132:135]
	v_mfma_f32_16x16x32_bf16 v[116:119], v[84:87], v[180:183], v[116:119]
	v_mfma_f32_16x16x32_bf16 v[112:115], v[92:95], v[180:183], v[112:115]
	v_mfma_f32_16x16x32_bf16 v[96:99], v[92:95], v[188:191], v[96:99]
	v_mfma_f32_16x16x32_bf16 v[100:103], v[84:87], v[188:191], v[100:103]
	v_mfma_f32_16x16x32_bf16 v[148:151], v[88:91], v[168:171], v[148:151]
	v_mfma_f32_16x16x32_bf16 v[144:147], v[152:155], v[168:171], v[144:147]
	v_mfma_f32_16x16x32_bf16 v[128:131], v[152:155], v[176:179], v[128:131]
	v_mfma_f32_16x16x32_bf16 v[132:135], v[88:91], v[176:179], v[132:135]
	v_mfma_f32_16x16x32_bf16 v[116:119], v[88:91], v[184:187], v[116:119]
	v_mfma_f32_16x16x32_bf16 v[112:115], v[152:155], v[184:187], v[112:115]
	v_mfma_f32_16x16x32_bf16 v[96:99], v[152:155], v[208:211], v[96:99]
	v_mfma_f32_16x16x32_bf16 v[100:103], v[88:91], v[208:211], v[100:103]
	s_barrier
; #define PG8_STAGE(bufoff, gbase, voff) do { _Pragma("unroll") for (int _i = 0; _i < 2; ++_i) \
;         __builtin_amdgcn_global_load_lds((const unsigned*)((const char*)(gbase) + (voff)[_i]), (LAS unsigned*)(lds + (bufoff) + ldsw + _i * 8192), 16, 0, 0); } while (0)
; #define PG8_LDA(dst, b, h) do { _Pragma("unroll") for (int m = 0; m < 4; ++m) _Pragma("unroll") for (int k = 0; k < 2; ++k) dst[m][k] = *(const LAS bf16x8*)(lds + PG8_SA(b, h) + aoff + m * 2048 + k * 1024); } while (0)
; #define PG8_LDB(dst, b, h) do { _Pragma("unroll") for (int n = 0; n < 2; ++n) _Pragma("unroll") for (int k = 0; k < 2; ++k) dst[n][k] = *(const LAS bf16x8*)(lds + PG8_SB(b, h) + boff + n * 2048 + k * 1024); } while (0)
; #define PG8_WAIT_V(n) asm volatile("s_waitcnt vmcnt(" #n ")" ::: "memory")
; #define PG8_WAIT_L(n) asm volatile("s_waitcnt lgkmcnt(" #n ")" ::: "memory")
; template <class Epi, class Sched>
; __device__ __forceinline__ void gemm_phase(LAS unsigned char* lds, const Gemm g, const Sched& S, const Epi& E, const int tid) {
;     ...
;             const bool last = (t == nt - 2);
;             const char* a1 = cA + (size_t)(t + 1) * kstep;
;             const char* a2 = last ? nA : cA + (size_t)(t + 2) * kstep; const char* b2 = last ? nB : cB + (size_t)(t + 2) * kstep;
;             const char* a3 = a2 + kstep; const char* b3 = b2 + kstep;
;             PG8_LDB(B0, 0, 0); PG8_LDB(B1, 0, 1); PG8_SCHED; PG8_LDA(At, 0, 0); PG8_STAGE(PG8_SA(1, 1), a1 + hstep, voffA);
;             PG8_WAIT_V(8); PG8_WAIT_L(0); PG8_BAR; PG8_MMA(0, 0, At, B0); PG8_MMA(0, 1, At, B1); PG8_BAR; PG8_SCHED;
;             PG8_LDA(At, 0, 1); PG8_STAGE(PG8_SB(0, 0), b2, voffB); PG8_STAGE(PG8_SB(0, 1), b2 + hstep, voffB); PG8_STAGE(PG8_SA(0, 0), a2, voffA);
;             PG8_WAIT_V(8); PG8_WAIT_L(0); PG8_BAR; PG8_MMA(1, 0, At, B0); PG8_MMA(1, 1, At, B1); PG8_BAR; PG8_SCHED;
;             PG8_LDB(B0, 1, 0); PG8_LDB(B1, 1, 1); PG8_SCHED; PG8_LDA(At, 1, 0); PG8_STAGE(PG8_SA(0, 1), a2 + hstep, voffA);
;             PG8_WAIT_V(8); PG8_WAIT_L(0); PG8_BAR; PG8_MMA(0, 0, At, B0); PG8_MMA(0, 1, At, B1); PG8_BAR; PG8_SCHED;
;             PG8_LDA(At, 1, 1); PG8_STAGE(PG8_SB(1, 0), b3, voffB); PG8_STAGE(PG8_SB(1, 1), b3 + hstep, voffB); PG8_STAGE(PG8_SA(1, 0), a3, voffA);
;             PG8_WAIT_V(8); PG8_WAIT_L(0); PG8_BAR; PG8_MMA(1, 0, At, B0); PG8_MMA(1, 1, At, B1); PG8_BAR; PG8_SCHED;
	s_add_i32 s3, s3, s94
	v_lshl_add_u64 v[74:75], v[212:213], 0, s[68:69]
	s_mov_b32 m0, s3
	ds_read_b128 v[164:167], v240 offset:49152
	ds_read_b128 v[168:171], v240 offset:50176
	ds_read_b128 v[172:175], v240 offset:51200
	ds_read_b128 v[176:179], v240 offset:52224
	ds_read_b128 v[180:183], v240 offset:53248
	ds_read_b128 v[184:187], v240 offset:54272
	ds_read_b128 v[188:191], v240 offset:55296
	ds_read_b128 v[208:211], v240 offset:56320
	global_load_lds_dwordx4 v[74:75], off
	v_lshl_add_u64 v[74:75], v[214:215], 0, s[68:69]
	s_add_i32 m0, s3, 0x2000
	s_add_i32 s3, s81, s94
	global_load_lds_dwordx4 v[74:75], off
	v_lshl_add_u64 v[74:75], v[216:217], 0, s[68:69]
	s_mov_b32 m0, s3
	s_nop 0
	global_load_lds_dwordx4 v[74:75], off
	v_lshl_add_u64 v[74:75], v[218:219], 0, s[68:69]
	s_add_i32 m0, s3, 0x2000
	s_nop 0
	global_load_lds_dwordx4 v[74:75], off
	v_lshl_add_u64 v[74:75], v[220:221], 0, s[68:69]
	s_mov_b32 m0, s53
	s_nop 0
	global_load_lds_dwordx4 v[74:75], off
	v_lshl_add_u64 v[74:75], v[224:225], 0, s[68:69]
	s_mov_b32 m0, s56
	s_nop 0
	global_load_lds_dwordx4 v[74:75], off
	s_waitcnt vmcnt(8)
	s_waitcnt lgkmcnt(0)
	s_barrier
	s_waitcnt lgkmcnt(0)
	v_mfma_f32_16x16x32_bf16 v[74:77], v[58:61], v[164:167], v[76:79]
	v_mfma_f32_16x16x32_bf16 v[70:73], v[66:69], v[164:167], v[70:73]
	v_mfma_f32_16x16x32_bf16 v[40:43], v[66:69], v[172:175], v[40:43]
	v_mfma_f32_16x16x32_bf16 v[44:47], v[58:61], v[172:175], v[44:47]
	v_mfma_f32_16x16x32_bf16 v[28:31], v[58:61], v[180:183], v[28:31]
	v_mfma_f32_16x16x32_bf16 v[24:27], v[66:69], v[180:183], v[24:27]
	v_mfma_f32_16x16x32_bf16 v[8:11], v[66:69], v[188:191], v[8:11]
	v_mfma_f32_16x16x32_bf16 v[12:15], v[58:61], v[188:191], v[12:15]
	v_mfma_f32_16x16x32_bf16 v[76:79], v[62:65], v[168:171], v[74:77]
	v_mfma_f32_16x16x32_bf16 v[72:75], v[80:83], v[168:171], v[70:73]
	v_mfma_f32_16x16x32_bf16 v[40:43], v[80:83], v[176:179], v[40:43]
	v_mfma_f32_16x16x32_bf16 v[44:47], v[62:65], v[176:179], v[44:47]
	v_mfma_f32_16x16x32_bf16 v[28:31], v[62:65], v[184:187], v[28:31]
	v_mfma_f32_16x16x32_bf16 v[24:27], v[80:83], v[184:187], v[24:27]
	v_mfma_f32_16x16x32_bf16 v[8:11], v[80:83], v[208:211], v[8:11]
	v_mfma_f32_16x16x32_bf16 v[12:15], v[62:65], v[208:211], v[12:15]
	v_mfma_f32_16x16x32_bf16 v[52:55], v[84:87], v[164:167], v[52:55]
	v_mfma_f32_16x16x32_bf16 v[48:51], v[92:95], v[164:167], v[48:51]
	v_mfma_f32_16x16x32_bf16 v[32:35], v[92:95], v[172:175], v[32:35]
	v_mfma_f32_16x16x32_bf16 v[36:39], v[84:87], v[172:175], v[36:39]
	v_mfma_f32_16x16x32_bf16 v[20:23], v[84:87], v[180:183], v[20:23]
	v_mfma_f32_16x16x32_bf16 v[16:19], v[92:95], v[180:183], v[16:19]
	v_mfma_f32_16x16x32_bf16 v[0:3], v[92:95], v[188:191], v[0:3]
	v_mfma_f32_16x16x32_bf16 v[4:7], v[84:87], v[188:191], v[4:7]
	v_mfma_f32_16x16x32_bf16 v[52:55], v[88:91], v[168:171], v[52:55]
	v_mfma_f32_16x16x32_bf16 v[48:51], v[152:155], v[168:171], v[48:51]
	v_mfma_f32_16x16x32_bf16 v[32:35], v[152:155], v[176:179], v[32:35]
	v_mfma_f32_16x16x32_bf16 v[36:39], v[88:91], v[176:179], v[36:39]
	v_mfma_f32_16x16x32_bf16 v[20:23], v[88:91], v[184:187], v[20:23]
	v_mfma_f32_16x16x32_bf16 v[16:19], v[152:155], v[184:187], v[16:19]
	v_mfma_f32_16x16x32_bf16 v[0:3], v[152:155], v[208:211], v[0:3]
	v_mfma_f32_16x16x32_bf16 v[4:7], v[88:91], v[208:211], v[4:7]
	s_barrier
	s_add_u32 vcc_lo, vcc_lo, 0x100
	s_addc_u32 vcc_hi, vcc_hi, 0
	s_add_u32 s61, s61, 0x100
	s_addc_u32 s67, s67, 0
	s_cmp_ge_u32 s80, s52
	s_mov_b32 s74, s80
.LBB0_567:
	s_add_i32 s80, s74, 2
	s_add_u32 s81, vcc_lo, 0x80
	s_addc_u32 s75, vcc_hi, 0
	s_add_i32 s3, 0, 0x10000
	s_cmp_eq_u32 s57, s74
	s_cselect_b32 s75, s71, s75
	s_cselect_b32 s74, s70, s81
	v_add_u32_e32 v70, s3, v232
	s_cselect_b32 s83, s73, s67
	s_cselect_b32 s82, s72, s61
	s_add_i32 s81, 0, 0x14000
	ds_read_b128 v[58:61], v70
	ds_read_b128 v[62:65], v70 offset:1024
	ds_read_b128 v[66:69], v70 offset:2048
	ds_read_b128 v[80:83], v70 offset:3072
	v_add_u32_e32 v70, s81, v232
	ds_read_b128 v[84:87], v70
	ds_read_b128 v[88:91], v70 offset:1024
	ds_read_b128 v[92:95], v70 offset:2048
	ds_read_b128 v[152:155], v70 offset:3072
	v_lshl_add_u64 v[70:71], vcc, 0, v[204:205]
	s_add_i32 m0, s97, 0xc000
	ds_read_b128 v[164:167], v240
	ds_read_b128 v[168:171], v240 offset:1024
	ds_read_b128 v[172:175], v240 offset:2048
	ds_read_b128 v[176:179], v240 offset:3072
	ds_read_b128 v[180:183], v240 offset:4096
	ds_read_b128 v[184:187], v240 offset:5120
	ds_read_b128 v[188:191], v240 offset:6144
	ds_read_b128 v[208:211], v240 offset:7168
	global_load_lds_dwordx4 v[70:71], off
	v_lshl_add_u64 v[70:71], vcc, 0, v[206:207]
	s_add_i32 m0, s97, 0xe000
	s_nop 0
	global_load_lds_dwordx4 v[70:71], off
	s_waitcnt vmcnt(8)
	s_waitcnt lgkmcnt(0)
	s_barrier
; #define PG8_STAGE(bufoff, gbase, voff) do { _Pragma("unroll") for (int _i = 0; _i < 2; ++_i) \
;         __builtin_amdgcn_global_load_lds((const unsigned*)((const char*)(gbase) + (voff)[_i]), (LAS unsigned*)(lds + (bufoff) + ldsw + _i * 8192), 16, 0, 0); } while (0)
; #define PG8_LDA(dst, b, h) do { _Pragma("unroll") for (int m = 0; m < 4; ++m) _Pragma("unroll") for (int k = 0; k < 2; ++k) dst[m][k] = *(const LAS bf16x8*)(lds + PG8_SA(b, h) + aoff + m * 2048 + k * 1024); } while (0)
; #define PG8_MMA(ai, bj, At, Bt) do { __builtin_amdgcn_s_setprio(1); _Pragma("unroll") for (int m = 0; m < 4; ++m) _Pragma("unroll") for (int n = 0; n < 2; ++n) _Pragma("unroll") for (int k = 0; k < 2; ++k) \
;         acc[ai][bj][m][n] = __builtin_amdgcn_mfma_f32_16x16x32_bf16(Bt[n][k], At[m][k], acc[ai][bj][m][n], 0, 0, 0); __builtin_amdgcn_s_setprio(0); } while (0)
; #define PG8_WAIT_V(n) asm volatile("s_waitcnt vmcnt(" #n ")" ::: "memory")
; #define PG8_WAIT_L(n) asm volatile("s_waitcnt lgkmcnt(" #n ")" ::: "memory")
; #define PG8_BAR __builtin_amdgcn_s_barrier()
; #define PG8_SCHED __builtin_amdgcn_sched_barrier(0)
; template <class Epi, class Sched>
; __device__ __forceinline__ void gemm_phase(LAS unsigned char* lds, const Gemm g, const Sched& S, const Epi& E, const int tid) {
;     ...
;             PG8_WAIT_V(8); PG8_WAIT_L(0); PG8_BAR; PG8_MMA(0, 0, At, B0); PG8_MMA(0, 1, At, B1); PG8_BAR; PG8_SCHED;
;             PG8_LDA(At, 0, 1); PG8_STAGE(PG8_SB(0, 0), b2, voffB); PG8_STAGE(PG8_SB(0, 1), b2 + hstep, voffB); PG8_STAGE(PG8_SA(0, 0), a2, voffA);
;             PG8_WAIT_V(8); PG8_WAIT_L(0); PG8_BAR; PG8_MMA(1, 0, At, B0); PG8_MMA(1, 1, At, B1); PG8_BAR; PG8_SCHED;
	s_waitcnt lgkmcnt(0)
	v_mfma_f32_16x16x32_bf16 v[160:163], v[58:61], v[164:167], v[160:163]
	v_mfma_f32_16x16x32_bf16 v[156:159], v[66:69], v[164:167], v[156:159]
	v_mfma_f32_16x16x32_bf16 v[136:139], v[66:69], v[172:175], v[136:139]
	v_mfma_f32_16x16x32_bf16 v[140:143], v[58:61], v[172:175], v[140:143]
	v_mfma_f32_16x16x32_bf16 v[124:127], v[58:61], v[180:183], v[124:127]
	v_mfma_f32_16x16x32_bf16 v[120:123], v[66:69], v[180:183], v[120:123]
	v_mfma_f32_16x16x32_bf16 v[104:107], v[66:69], v[188:191], v[104:107]
	v_mfma_f32_16x16x32_bf16 v[108:111], v[58:61], v[188:191], v[108:111]
	v_mfma_f32_16x16x32_bf16 v[160:163], v[62:65], v[168:171], v[160:163]
	v_mfma_f32_16x16x32_bf16 v[156:159], v[80:83], v[168:171], v[156:159]
	v_mfma_f32_16x16x32_bf16 v[136:139], v[80:83], v[176:179], v[136:139]
	v_mfma_f32_16x16x32_bf16 v[140:143], v[62:65], v[176:179], v[140:143]
	v_mfma_f32_16x16x32_bf16 v[124:127], v[62:65], v[184:187], v[124:127]
	v_mfma_f32_16x16x32_bf16 v[120:123], v[80:83], v[184:187], v[120:123]
	v_mfma_f32_16x16x32_bf16 v[104:107], v[80:83], v[208:211], v[104:107]
	v_mfma_f32_16x16x32_bf16 v[108:111], v[62:65], v[208:211], v[108:111]
	v_mfma_f32_16x16x32_bf16 v[148:151], v[84:87], v[164:167], v[148:151]
	v_mfma_f32_16x16x32_bf16 v[144:147], v[92:95], v[164:167], v[144:147]
	v_mfma_f32_16x16x32_bf16 v[128:131], v[92:95], v[172:175], v[128:131]
	v_mfma_f32_16x16x32_bf16 v[132:135], v[84:87], v[172:175], v[132:135]
	v_mfma_f32_16x16x32_bf16 v[116:119], v[84:87], v[180:183], v[116:119]
	v_mfma_f32_16x16x32_bf16 v[112:115], v[92:95], v[180:183], v[112:115]
	v_mfma_f32_16x16x32_bf16 v[96:99], v[92:95], v[188:191], v[96:99]
	v_mfma_f32_16x16x32_bf16 v[100:103], v[84:87], v[188:191], v[100:103]
	v_mfma_f32_16x16x32_bf16 v[148:151], v[88:91], v[168:171], v[148:151]
	v_mfma_f32_16x16x32_bf16 v[144:147], v[152:155], v[168:171], v[144:147]
	v_mfma_f32_16x16x32_bf16 v[128:131], v[152:155], v[176:179], v[128:131]
	v_mfma_f32_16x16x32_bf16 v[132:135], v[88:91], v[176:179], v[132:135]
	v_mfma_f32_16x16x32_bf16 v[116:119], v[88:91], v[184:187], v[116:119]
	v_mfma_f32_16x16x32_bf16 v[112:115], v[152:155], v[184:187], v[112:115]
	v_mfma_f32_16x16x32_bf16 v[96:99], v[152:155], v[208:211], v[96:99]
	v_mfma_f32_16x16x32_bf16 v[100:103], v[88:91], v[208:211], v[100:103]
	s_barrier
	s_add_i32 s3, s3, s94
	v_lshl_add_u64 v[212:213], s[82:83], 0, v[192:193]
	s_mov_b32 m0, s3
	ds_read_b128 v[164:167], v240 offset:16384
	ds_read_b128 v[168:171], v240 offset:17408
	ds_read_b128 v[172:175], v240 offset:18432
	ds_read_b128 v[176:179], v240 offset:19456
	ds_read_b128 v[180:183], v240 offset:20480
	ds_read_b128 v[184:187], v240 offset:21504
	ds_read_b128 v[188:191], v240 offset:22528
	ds_read_b128 v[208:211], v240 offset:23552
	global_load_lds_dwordx4 v[212:213], off
	s_add_i32 m0, s3, 0x2000
	v_lshl_add_u64 v[214:215], s[82:83], 0, v[198:199]
	s_add_u32 s82, s82, s12
	s_addc_u32 s83, s83, 0
	s_add_i32 s3, s81, s94
	global_load_lds_dwordx4 v[214:215], off
	v_lshl_add_u64 v[216:217], s[82:83], 0, v[192:193]
	s_mov_b32 m0, s3
	v_lshl_add_u64 v[218:219], s[82:83], 0, v[198:199]
	global_load_lds_dwordx4 v[216:217], off
	s_add_i32 m0, s3, 0x2000
	v_lshl_add_u64 v[220:221], s[74:75], 0, v[202:203]
	global_load_lds_dwordx4 v[218:219], off
	s_mov_b32 m0, s97
	v_lshl_add_u64 v[224:225], s[74:75], 0, v[200:201]
	global_load_lds_dwordx4 v[220:221], off
	s_mov_b32 m0, s98
	s_nop 0
	global_load_lds_dwordx4 v[224:225], off
	s_waitcnt vmcnt(8)
	s_waitcnt lgkmcnt(0)
	s_barrier
	s_waitcnt lgkmcnt(0)
	v_mfma_f32_16x16x32_bf16 v[76:79], v[58:61], v[164:167], v[76:79]
	v_mfma_f32_16x16x32_bf16 v[70:73], v[66:69], v[164:167], v[72:75]
	v_mfma_f32_16x16x32_bf16 v[40:43], v[66:69], v[172:175], v[40:43]
	v_mfma_f32_16x16x32_bf16 v[44:47], v[58:61], v[172:175], v[44:47]
	v_mfma_f32_16x16x32_bf16 v[28:31], v[58:61], v[180:183], v[28:31]
	v_mfma_f32_16x16x32_bf16 v[24:27], v[66:69], v[180:183], v[24:27]
	v_mfma_f32_16x16x32_bf16 v[8:11], v[66:69], v[188:191], v[8:11]
	v_mfma_f32_16x16x32_bf16 v[12:15], v[58:61], v[188:191], v[12:15]
	v_mfma_f32_16x16x32_bf16 v[76:79], v[62:65], v[168:171], v[76:79]
	v_mfma_f32_16x16x32_bf16 v[70:73], v[80:83], v[168:171], v[70:73]
	v_mfma_f32_16x16x32_bf16 v[40:43], v[80:83], v[176:179], v[40:43]
	v_mfma_f32_16x16x32_bf16 v[44:47], v[62:65], v[176:179], v[44:47]
	v_mfma_f32_16x16x32_bf16 v[28:31], v[62:65], v[184:187], v[28:31]
	v_mfma_f32_16x16x32_bf16 v[24:27], v[80:83], v[184:187], v[24:27]
	v_mfma_f32_16x16x32_bf16 v[8:11], v[80:83], v[208:211], v[8:11]
	v_mfma_f32_16x16x32_bf16 v[12:15], v[62:65], v[208:211], v[12:15]
	v_mfma_f32_16x16x32_bf16 v[52:55], v[84:87], v[164:167], v[52:55]
	v_mfma_f32_16x16x32_bf16 v[48:51], v[92:95], v[164:167], v[48:51]
	v_mfma_f32_16x16x32_bf16 v[32:35], v[92:95], v[172:175], v[32:35]
	v_mfma_f32_16x16x32_bf16 v[36:39], v[84:87], v[172:175], v[36:39]
	v_mfma_f32_16x16x32_bf16 v[20:23], v[84:87], v[180:183], v[20:23]
	v_mfma_f32_16x16x32_bf16 v[16:19], v[92:95], v[180:183], v[16:19]
	v_mfma_f32_16x16x32_bf16 v[0:3], v[92:95], v[188:191], v[0:3]
	v_mfma_f32_16x16x32_bf16 v[4:7], v[84:87], v[188:191], v[4:7]
	v_mfma_f32_16x16x32_bf16 v[52:55], v[88:91], v[168:171], v[52:55]
	v_mfma_f32_16x16x32_bf16 v[48:51], v[152:155], v[168:171], v[48:51]
	v_mfma_f32_16x16x32_bf16 v[32:35], v[152:155], v[176:179], v[32:35]
	v_mfma_f32_16x16x32_bf16 v[36:39], v[88:91], v[176:179], v[36:39]
	v_mfma_f32_16x16x32_bf16 v[20:23], v[88:91], v[184:187], v[20:23]
	v_mfma_f32_16x16x32_bf16 v[16:19], v[152:155], v[184:187], v[16:19]
	v_mfma_f32_16x16x32_bf16 v[0:3], v[152:155], v[208:211], v[0:3]
	v_mfma_f32_16x16x32_bf16 v[4:7], v[88:91], v[208:211], v[4:7]
	s_barrier
; #define PG8_STAGE(bufoff, gbase, voff) do { _Pragma("unroll") for (int _i = 0; _i < 2; ++_i) \
;         __builtin_amdgcn_global_load_lds((const unsigned*)((const char*)(gbase) + (voff)[_i]), (LAS unsigned*)(lds + (bufoff) + ldsw + _i * 8192), 16, 0, 0); } while (0)
; #define PG8_LDA(dst, b, h) do { _Pragma("unroll") for (int m = 0; m < 4; ++m) _Pragma("unroll") for (int k = 0; k < 2; ++k) dst[m][k] = *(const LAS bf16x8*)(lds + PG8_SA(b, h) + aoff + m * 2048 + k * 1024); } while (0)
; #define PG8_LDB(dst, b, h) do { _Pragma("unroll") for (int n = 0; n < 2; ++n) _Pragma("unroll") for (int k = 0; k < 2; ++k) dst[n][k] = *(const LAS bf16x8*)(lds + PG8_SB(b, h) + boff + n * 2048 + k * 1024); } while (0)
; #define PG8_MMA(ai, bj, At, Bt) do { __builtin_amdgcn_s_setprio(1); _Pragma("unroll") for (int m = 0; m < 4; ++m) _Pragma("unroll") for (int n = 0; n < 2; ++n) _Pragma("unroll") for (int k = 0; k < 2; ++k) \
;         acc[ai][bj][m][n] = __builtin_amdgcn_mfma_f32_16x16x32_bf16(Bt[n][k], At[m][k], acc[ai][bj][m][n], 0, 0, 0); __builtin_amdgcn_s_setprio(0); } while (0)
; #define PG8_WAIT_V(n) asm volatile("s_waitcnt vmcnt(" #n ")" ::: "memory")
; #define PG8_WAIT_L(n) asm volatile("s_waitcnt lgkmcnt(" #n ")" ::: "memory")
; #define PG8_BAR __builtin_amdgcn_s_barrier()
; #define PG8_SCHED __builtin_amdgcn_sched_barrier(0)
; template <class Epi, class Sched>
; __device__ __forceinline__ void gemm_phase(LAS unsigned char* lds, const Gemm g, const Sched& S, const Epi& E, const int tid) {
;     ...
;             PG8_LDB(B0, 1, 0); PG8_LDB(B1, 1, 1); PG8_SCHED; PG8_LDA(At, 1, 0); PG8_STAGE(PG8_SA(0, 1), a2 + hstep, voffA);
;             PG8_WAIT_V(8); PG8_WAIT_L(0); PG8_BAR; PG8_MMA(0, 0, At, B0); PG8_MMA(0, 1, At, B1); PG8_BAR; PG8_SCHED;
;             PG8_LDA(At, 1, 1); PG8_STAGE(PG8_SB(1, 0), b3, voffB); PG8_STAGE(PG8_SB(1, 1), b3 + hstep, voffB); PG8_STAGE(PG8_SA(1, 0), a3, voffA);
;             PG8_WAIT_V(8); PG8_WAIT_L(0); PG8_BAR; PG8_MMA(1, 0, At, B0); PG8_MMA(1, 1, At, B1); PG8_BAR; PG8_SCHED;
;         }
;         if (wr == 0) PG8_BAR;
	s_add_i32 s3, 0, 0x18000
	v_add_u32_e32 v74, s3, v232
	s_add_i32 s81, 0, 0x1c000
	ds_read_b128 v[58:61], v74
	ds_read_b128 v[62:65], v74 offset:1024
	ds_read_b128 v[66:69], v74 offset:2048
	ds_read_b128 v[80:83], v74 offset:3072
	v_add_u32_e32 v74, s81, v232
	ds_read_b128 v[84:87], v74
	ds_read_b128 v[88:91], v74 offset:1024
	ds_read_b128 v[92:95], v74 offset:2048
	ds_read_b128 v[152:155], v74 offset:3072
	s_add_u32 s74, s74, s12
	s_addc_u32 s75, s75, 0
	s_mov_b32 m0, s99
	v_lshl_add_u64 v[74:75], s[74:75], 0, v[202:203]
	ds_read_b128 v[164:167], v240 offset:32768
	ds_read_b128 v[168:171], v240 offset:33792
	ds_read_b128 v[172:175], v240 offset:34816
	ds_read_b128 v[176:179], v240 offset:35840
	ds_read_b128 v[180:183], v240 offset:36864
	ds_read_b128 v[184:187], v240 offset:37888
	ds_read_b128 v[188:191], v240 offset:38912
	ds_read_b128 v[208:211], v240 offset:39936
	global_load_lds_dwordx4 v[74:75], off
	v_lshl_add_u64 v[74:75], s[74:75], 0, v[200:201]
	s_mov_b32 m0, s78
	s_nop 0
	global_load_lds_dwordx4 v[74:75], off
	s_waitcnt vmcnt(8)
	s_waitcnt lgkmcnt(0)
	s_barrier
	s_waitcnt lgkmcnt(0)
	v_mfma_f32_16x16x32_bf16 v[160:163], v[58:61], v[164:167], v[160:163]
	v_mfma_f32_16x16x32_bf16 v[156:159], v[66:69], v[164:167], v[156:159]
	v_mfma_f32_16x16x32_bf16 v[136:139], v[66:69], v[172:175], v[136:139]
	v_mfma_f32_16x16x32_bf16 v[140:143], v[58:61], v[172:175], v[140:143]
	v_mfma_f32_16x16x32_bf16 v[124:127], v[58:61], v[180:183], v[124:127]
	v_mfma_f32_16x16x32_bf16 v[120:123], v[66:69], v[180:183], v[120:123]
	v_mfma_f32_16x16x32_bf16 v[104:107], v[66:69], v[188:191], v[104:107]
	v_mfma_f32_16x16x32_bf16 v[108:111], v[58:61], v[188:191], v[108:111]
	v_mfma_f32_16x16x32_bf16 v[160:163], v[62:65], v[168:171], v[160:163]
	v_mfma_f32_16x16x32_bf16 v[156:159], v[80:83], v[168:171], v[156:159]
	v_mfma_f32_16x16x32_bf16 v[136:139], v[80:83], v[176:179], v[136:139]
	v_mfma_f32_16x16x32_bf16 v[140:143], v[62:65], v[176:179], v[140:143]
	v_mfma_f32_16x16x32_bf16 v[124:127], v[62:65], v[184:187], v[124:127]
	v_mfma_f32_16x16x32_bf16 v[120:123], v[80:83], v[184:187], v[120:123]
	v_mfma_f32_16x16x32_bf16 v[104:107], v[80:83], v[208:211], v[104:107]
	v_mfma_f32_16x16x32_bf16 v[108:111], v[62:65], v[208:211], v[108:111]
	v_mfma_f32_16x16x32_bf16 v[148:151], v[84:87], v[164:167], v[148:151]
	v_mfma_f32_16x16x32_bf16 v[144:147], v[92:95], v[164:167], v[144:147]
	v_mfma_f32_16x16x32_bf16 v[128:131], v[92:95], v[172:175], v[128:131]
	v_mfma_f32_16x16x32_bf16 v[132:135], v[84:87], v[172:175], v[132:135]
	v_mfma_f32_16x16x32_bf16 v[116:119], v[84:87], v[180:183], v[116:119]
	v_mfma_f32_16x16x32_bf16 v[112:115], v[92:95], v[180:183], v[112:115]
	v_mfma_f32_16x16x32_bf16 v[96:99], v[92:95], v[188:191], v[96:99]
	v_mfma_f32_16x16x32_bf16 v[100:103], v[84:87], v[188:191], v[100:103]
	v_mfma_f32_16x16x32_bf16 v[148:151], v[88:91], v[168:171], v[148:151]
	v_mfma_f32_16x16x32_bf16 v[144:147], v[152:155], v[168:171], v[144:147]
	v_mfma_f32_16x16x32_bf16 v[128:131], v[152:155], v[176:179], v[128:131]
	v_mfma_f32_16x16x32_bf16 v[132:135], v[88:91], v[176:179], v[132:135]
	v_mfma_f32_16x16x32_bf16 v[116:119], v[88:91], v[184:187], v[116:119]
	v_mfma_f32_16x16x32_bf16 v[112:115], v[152:155], v[184:187], v[112:115]
	v_mfma_f32_16x16x32_bf16 v[96:99], v[152:155], v[208:211], v[96:99]
	v_mfma_f32_16x16x32_bf16 v[100:103], v[88:91], v[208:211], v[100:103]
	s_barrier
	s_add_i32 s3, s3, s94
	v_lshl_add_u64 v[74:75], v[212:213], 0, s[68:69]
	s_mov_b32 m0, s3
	ds_read_b128 v[164:167], v240 offset:49152
	ds_read_b128 v[168:171], v240 offset:50176
	ds_read_b128 v[172:175], v240 offset:51200
	ds_read_b128 v[176:179], v240 offset:52224
	ds_read_b128 v[180:183], v240 offset:53248
	ds_read_b128 v[184:187], v240 offset:54272
	ds_read_b128 v[188:191], v240 offset:55296
	ds_read_b128 v[208:211], v240 offset:56320
	global_load_lds_dwordx4 v[74:75], off
	v_lshl_add_u64 v[74:75], v[214:215], 0, s[68:69]
	s_add_i32 m0, s3, 0x2000
	s_add_i32 s3, s81, s94
	global_load_lds_dwordx4 v[74:75], off
	v_lshl_add_u64 v[74:75], v[216:217], 0, s[68:69]
	s_mov_b32 m0, s3
	s_nop 0
	global_load_lds_dwordx4 v[74:75], off
	v_lshl_add_u64 v[74:75], v[218:219], 0, s[68:69]
	s_add_i32 m0, s3, 0x2000
	s_nop 0
	global_load_lds_dwordx4 v[74:75], off
	v_lshl_add_u64 v[74:75], v[220:221], 0, s[68:69]
	s_mov_b32 m0, s53
	s_nop 0
	global_load_lds_dwordx4 v[74:75], off
	v_lshl_add_u64 v[74:75], v[224:225], 0, s[68:69]
	s_mov_b32 m0, s56
	s_nop 0
	global_load_lds_dwordx4 v[74:75], off
	s_waitcnt vmcnt(8)
	s_waitcnt lgkmcnt(0)
	s_barrier
	s_waitcnt lgkmcnt(0)
	v_mfma_f32_16x16x32_bf16 v[74:77], v[58:61], v[164:167], v[76:79]
	v_mfma_f32_16x16x32_bf16 v[70:73], v[66:69], v[164:167], v[70:73]
	v_mfma_f32_16x16x32_bf16 v[40:43], v[66:69], v[172:175], v[40:43]
	v_mfma_f32_16x16x32_bf16 v[44:47], v[58:61], v[172:175], v[44:47]
	v_mfma_f32_16x16x32_bf16 v[28:31], v[58:61], v[180:183], v[28:31]
	v_mfma_f32_16x16x32_bf16 v[24:27], v[66:69], v[180:183], v[24:27]
	v_mfma_f32_16x16x32_bf16 v[8:11], v[66:69], v[188:191], v[8:11]
	v_mfma_f32_16x16x32_bf16 v[12:15], v[58:61], v[188:191], v[12:15]
	v_mfma_f32_16x16x32_bf16 v[76:79], v[62:65], v[168:171], v[74:77]
	v_mfma_f32_16x16x32_bf16 v[72:75], v[80:83], v[168:171], v[70:73]
	v_mfma_f32_16x16x32_bf16 v[40:43], v[80:83], v[176:179], v[40:43]
	v_mfma_f32_16x16x32_bf16 v[44:47], v[62:65], v[176:179], v[44:47]
	v_mfma_f32_16x16x32_bf16 v[28:31], v[62:65], v[184:187], v[28:31]
	v_mfma_f32_16x16x32_bf16 v[24:27], v[80:83], v[184:187], v[24:27]
	v_mfma_f32_16x16x32_bf16 v[8:11], v[80:83], v[208:211], v[8:11]
	v_mfma_f32_16x16x32_bf16 v[12:15], v[62:65], v[208:211], v[12:15]
	v_mfma_f32_16x16x32_bf16 v[52:55], v[84:87], v[164:167], v[52:55]
	v_mfma_f32_16x16x32_bf16 v[48:51], v[92:95], v[164:167], v[48:51]
	v_mfma_f32_16x16x32_bf16 v[32:35], v[92:95], v[172:175], v[32:35]
	v_mfma_f32_16x16x32_bf16 v[36:39], v[84:87], v[172:175], v[36:39]
	v_mfma_f32_16x16x32_bf16 v[20:23], v[84:87], v[180:183], v[20:23]
	v_mfma_f32_16x16x32_bf16 v[16:19], v[92:95], v[180:183], v[16:19]
	v_mfma_f32_16x16x32_bf16 v[0:3], v[92:95], v[188:191], v[0:3]
	v_mfma_f32_16x16x32_bf16 v[4:7], v[84:87], v[188:191], v[4:7]
	v_mfma_f32_16x16x32_bf16 v[52:55], v[88:91], v[168:171], v[52:55]
	v_mfma_f32_16x16x32_bf16 v[48:51], v[152:155], v[168:171], v[48:51]
	v_mfma_f32_16x16x32_bf16 v[32:35], v[152:155], v[176:179], v[32:35]
	v_mfma_f32_16x16x32_bf16 v[36:39], v[88:91], v[176:179], v[36:39]
	v_mfma_f32_16x16x32_bf16 v[20:23], v[88:91], v[184:187], v[20:23]
	v_mfma_f32_16x16x32_bf16 v[16:19], v[152:155], v[184:187], v[16:19]
	v_mfma_f32_16x16x32_bf16 v[0:3], v[152:155], v[208:211], v[0:3]
	v_mfma_f32_16x16x32_bf16 v[4:7], v[88:91], v[208:211], v[4:7]
	s_barrier
	s_add_u32 vcc_lo, vcc_lo, 0x100
	s_addc_u32 vcc_hi, vcc_hi, 0
	s_add_u32 s61, s61, 0x100
	s_addc_u32 s67, s67, 0
	s_cmp_ge_u32 s80, s52
	s_mov_b32 s74, s80
	s_cbranch_scc0 .LBB0_567
	s_and_b64 vcc, exec, s[64:65]
	s_cbranch_vccz .LBB0_570
	s_barrier
